# LayerNorm row assignment: each wave normalises 16 consecutive rows (sequential 64 KB stream per wave) instead of rows 2048 apart
# speedup vs baseline: 1.0067x; 1.0067x over previous
; __device__ __forceinline__ int otid() { int t = threadIdx.x; asm volatile("" : "+v"(t)); return t; }
; __device__ __forceinline__ void phase_ln(float* R, const float* __restrict__ g, const float* __restrict__ b, bf16_t* xbf, float samp_scale, const float* __restrict__ part, int nsplit, bool f32_all) {
;   const int tid = otid(), lane = tid & 63, gw = blockIdx.x * 8 + (tid >> 6), nw = gridDim.x * 8;
;   f32x4 gv[4], bv[4];
; #pragma unroll
;   for (int i = 0; i < 4; ++i) { gv[i] = *(const f32x4*)(g + i * 256 + lane * 4); bv[i] = *(const f32x4*)(b + i * 256 + lane * 4); }
;   for (int r = gw; r < MT; r += nw) {
;     float* row = R + (size_t)r * 1024;
;     f32x4 v[4];
; #pragma unroll
;     for (int i = 0; i < 4; ++i) v[i] = *(const f32x4*)(row + i * 256 + lane * 4);
;     if (r >= MP) {
;       for (int sp = 0; sp < nsplit; ++sp) {
;         const float* prow = part + ((size_t)sp * MS + (r - MP)) * 1024;
; #pragma unroll
;         for (int i = 0; i < 4; ++i) v[i] = v[i] + *(const f32x4*)(prow + i * 256 + lane * 4);
;       }
;     }
;     float s = 0.f;
; #pragma unroll
;     for (int i = 0; i < 4; ++i) s += v[i][0] + v[i][1] + v[i][2] + v[i][3];
; #pragma unroll
;     for (int o = 32; o >= 1; o >>= 1) s += __shfl_xor(s, o);
;     const float mean = s * (1.f / 1024.f);
;     float ss = 0.f;
; #pragma unroll
;     for (int i = 0; i < 4; ++i) { v[i] = v[i] - mean; ss += v[i][0] * v[i][0] + v[i][1] * v[i][1] + v[i][2] * v[i][2] + v[i][3] * v[i][3]; }
; #pragma unroll
;     for (int o = 32; o >= 1; o >>= 1) ss += __shfl_xor(ss, o);
;     const float rstd = rsqrtf(ss * (1.f / 1024.f) + LN_EPS);
; #pragma unroll
;     for (int i = 0; i < 4; ++i) {
;       const f32x4 y = v[i] * rstd * gv[i] + bv[i];
;       if (r >= MP) *(f32x4*)(row + i * 256 + lane * 4) = y * samp_scale;
;       else if (f32_all) *(f32x4*)(row + i * 256 + lane * 4) = y;
;       if (xbf) {
;         u32x2 wv;
;         wv[0] = cvt_pk_bf16(y[0], y[1]); wv[1] = cvt_pk_bf16(y[2], y[3]);
;         *(u32x2*)(xbf + (size_t)r * 1024 + i * 256 + lane * 4) = wv;
;       }
;     }
.LBB0_3720:
	s_or_b64 exec, exec, s[0:1]
	v_readlane_b32 s0, v254, 51
	s_nop 0
	s_cmp_lg_u32 s0, 0
	s_cbranch_scc1 .Lln1_orig
	v_readlane_b32 s6, v254, 2
	v_readlane_b32 s7, v254, 3
	v_readlane_b32 s8, v255, 22
	s_waitcnt lgkmcnt(0)
	s_barrier
	s_load_dwordx4 s[0:3], s[6:7], 0x78
	s_load_dwordx4 s[4:7], s[6:7], 0xa8
	v_readlane_b32 s9, v254, 15
	v_readfirstlane_b32 s10, v244
	v_lshlrev_b32_e32 v114, 4, v252
	v_lshlrev_b32_e32 v115, 3, v252
	s_lshr_b32 s10, s10, 6
	s_add_i32 s9, s9, s10
	s_lshl_b32 s9, s9, 4
	s_lshl_b32 s11, s8, 12
	s_waitcnt lgkmcnt(0)
	s_add_u32 s0, s0, s11
	s_addc_u32 s1, s1, 0
	s_add_u32 s2, s2, s11
	s_addc_u32 s3, s3, 0
	global_load_dwordx4 v[34:37], v114, s[0:1] offset:0
	global_load_dwordx4 v[38:41], v114, s[0:1] offset:1024
	global_load_dwordx4 v[42:45], v114, s[0:1] offset:2048
	global_load_dwordx4 v[46:49], v114, s[0:1] offset:3072
	global_load_dwordx4 v[50:53], v114, s[2:3] offset:0
	global_load_dwordx4 v[54:57], v114, s[2:3] offset:1024
	global_load_dwordx4 v[58:61], v114, s[2:3] offset:2048
	global_load_dwordx4 v[62:65], v114, s[2:3] offset:3072
	s_lshl_b32 s11, s9, 12
	s_add_u32 s0, s4, s11
	s_addc_u32 s1, s5, 0
	s_lshl_b32 s11, s9, 11
	s_add_u32 s11, s11, 0x39c0000
	s_add_u32 s2, s6, s11
	s_addc_u32 s3, s7, 0
	global_load_dwordx4 v[0:3], v114, s[0:1] offset:0
	global_load_dwordx4 v[4:7], v114, s[0:1] offset:1024
	global_load_dwordx4 v[8:11], v114, s[0:1] offset:2048
	global_load_dwordx4 v[12:15], v114, s[0:1] offset:3072
	s_add_u32 s0, s0, 0x1000
	s_addc_u32 s1, s1, 0
	global_load_dwordx4 v[18:21], v114, s[0:1] offset:0
	global_load_dwordx4 v[22:25], v114, s[0:1] offset:1024
	global_load_dwordx4 v[26:29], v114, s[0:1] offset:2048
	global_load_dwordx4 v[30:33], v114, s[0:1] offset:3072
	s_waitcnt vmcnt(4)
	v_pk_add_f32 v[66:67], v[0:1], v[2:3]
	v_pk_add_f32 v[68:69], v[4:5], v[6:7]
	v_pk_add_f32 v[70:71], v[8:9], v[10:11]
	v_pk_add_f32 v[72:73], v[12:13], v[14:15]
	v_pk_add_f32 v[66:67], v[66:67], v[68:69]
	v_pk_add_f32 v[70:71], v[70:71], v[72:73]
	v_pk_add_f32 v[66:67], v[66:67], v[70:71]
	v_add_f32_e32 v66, v66, v67
	s_nop 1
	v_add_f32_dpp v66, v66, v66 row_shr:1 row_mask:0xf bank_mask:0xf bound_ctrl:1
	s_nop 1
	v_add_f32_dpp v66, v66, v66 row_shr:2 row_mask:0xf bank_mask:0xf bound_ctrl:1
	s_nop 1
	v_add_f32_dpp v66, v66, v66 row_shr:4 row_mask:0xf bank_mask:0xf bound_ctrl:1
	s_nop 1
	v_add_f32_dpp v66, v66, v66 row_shr:8 row_mask:0xf bank_mask:0xf bound_ctrl:1
	s_nop 0
	v_readlane_b32 s9, v66, 15
	v_readlane_b32 s10, v66, 31
	v_readlane_b32 s11, v66, 47
	v_readlane_b32 vcc_lo, v66, 63
	s_nop 1
	v_mov_b32_e32 v66, s9
	v_add_f32_e32 v66, s10, v66
	v_add_f32_e32 v66, s11, v66
	v_add_f32_e32 v66, vcc_lo, v66
	v_mul_f32_e32 v116, 0x3a800000, v66
	v_mov_b32_e32 v117, v116
	v_pk_add_f32 v[0:1], v[0:1], v[116:117] neg_lo:[0,1] neg_hi:[0,1]
	v_pk_add_f32 v[2:3], v[2:3], v[116:117] neg_lo:[0,1] neg_hi:[0,1]
	v_pk_add_f32 v[4:5], v[4:5], v[116:117] neg_lo:[0,1] neg_hi:[0,1]
	v_pk_add_f32 v[6:7], v[6:7], v[116:117] neg_lo:[0,1] neg_hi:[0,1]
	v_pk_add_f32 v[8:9], v[8:9], v[116:117] neg_lo:[0,1] neg_hi:[0,1]
	v_pk_add_f32 v[10:11], v[10:11], v[116:117] neg_lo:[0,1] neg_hi:[0,1]
	v_pk_add_f32 v[12:13], v[12:13], v[116:117] neg_lo:[0,1] neg_hi:[0,1]
	v_pk_add_f32 v[14:15], v[14:15], v[116:117] neg_lo:[0,1] neg_hi:[0,1]
	v_pk_mul_f32 v[66:67], v[0:1], v[0:1]
	v_pk_mul_f32 v[68:69], v[2:3], v[2:3]
	v_pk_fma_f32 v[66:67], v[4:5], v[4:5], v[66:67]
	v_pk_fma_f32 v[68:69], v[6:7], v[6:7], v[68:69]
	v_pk_fma_f32 v[66:67], v[8:9], v[8:9], v[66:67]
	v_pk_fma_f32 v[68:69], v[10:11], v[10:11], v[68:69]
	v_pk_fma_f32 v[66:67], v[12:13], v[12:13], v[66:67]
	v_pk_fma_f32 v[68:69], v[14:15], v[14:15], v[68:69]
	v_pk_add_f32 v[66:67], v[66:67], v[68:69]
	v_add_f32_e32 v66, v66, v67
	s_nop 1
	v_add_f32_dpp v66, v66, v66 row_shr:1 row_mask:0xf bank_mask:0xf bound_ctrl:1
	s_nop 1
	v_add_f32_dpp v66, v66, v66 row_shr:2 row_mask:0xf bank_mask:0xf bound_ctrl:1
	s_nop 1
	v_add_f32_dpp v66, v66, v66 row_shr:4 row_mask:0xf bank_mask:0xf bound_ctrl:1
	s_nop 1
	v_add_f32_dpp v66, v66, v66 row_shr:8 row_mask:0xf bank_mask:0xf bound_ctrl:1
	s_nop 0
	v_readlane_b32 s9, v66, 15
	v_readlane_b32 s10, v66, 31
	v_readlane_b32 s11, v66, 47
	v_readlane_b32 vcc_lo, v66, 63
	s_nop 1
	v_mov_b32_e32 v66, s9
	v_add_f32_e32 v66, s10, v66
	v_add_f32_e32 v66, s11, v66
	v_add_f32_e32 v66, vcc_lo, v66
	v_mul_f32_e32 v66, 0x3a800000, v66
	v_add_f32_e32 v66, 0x3727c5ac, v66
	v_rsq_f32_e32 v118, v66
	s_nop 0
	v_mov_b32_e32 v119, v118
	v_pk_mul_f32 v[0:1], v[0:1], v[118:119]
	v_pk_mul_f32 v[2:3], v[2:3], v[118:119]
	v_pk_mul_f32 v[4:5], v[4:5], v[118:119]
	v_pk_mul_f32 v[6:7], v[6:7], v[118:119]
	v_pk_mul_f32 v[8:9], v[8:9], v[118:119]
	v_pk_mul_f32 v[10:11], v[10:11], v[118:119]
	v_pk_mul_f32 v[12:13], v[12:13], v[118:119]
	v_pk_mul_f32 v[14:15], v[14:15], v[118:119]
	v_pk_fma_f32 v[76:77], v[0:1], v[34:35], v[50:51]
	v_pk_fma_f32 v[78:79], v[2:3], v[36:37], v[52:53]
	v_pk_fma_f32 v[80:81], v[4:5], v[38:39], v[54:55]
	v_pk_fma_f32 v[82:83], v[6:7], v[40:41], v[56:57]
	v_pk_fma_f32 v[84:85], v[8:9], v[42:43], v[58:59]
	v_pk_fma_f32 v[86:87], v[10:11], v[44:45], v[60:61]
	v_pk_fma_f32 v[88:89], v[12:13], v[46:47], v[62:63]
	v_pk_fma_f32 v[90:91], v[14:15], v[48:49], v[64:65]
	v_cvt_pk_bf16_f32 v92, v76, v77
	v_cvt_pk_bf16_f32 v93, v78, v79
	v_cvt_pk_bf16_f32 v94, v80, v81
	v_cvt_pk_bf16_f32 v95, v82, v83
	v_cvt_pk_bf16_f32 v96, v84, v85
	v_cvt_pk_bf16_f32 v97, v86, v87
	v_cvt_pk_bf16_f32 v98, v88, v89
	v_cvt_pk_bf16_f32 v99, v90, v91
	global_store_dwordx2 v115, v[92:93], s[2:3] offset:0
	global_store_dwordx2 v115, v[94:95], s[2:3] offset:512
	global_store_dwordx2 v115, v[96:97], s[2:3] offset:1024
	global_store_dwordx2 v115, v[98:99], s[2:3] offset:1536
	s_add_u32 s2, s2, 0x800
	s_addc_u32 s3, s3, 0
	s_add_u32 s0, s0, 0x1000
	s_addc_u32 s1, s1, 0
	global_load_dwordx4 v[0:3], v114, s[0:1] offset:0
	global_load_dwordx4 v[4:7], v114, s[0:1] offset:1024
	global_load_dwordx4 v[8:11], v114, s[0:1] offset:2048
	global_load_dwordx4 v[12:15], v114, s[0:1] offset:3072
	s_waitcnt vmcnt(8)
; __device__ __forceinline__ void phase_ln(float* R, const float* __restrict__ g, const float* __restrict__ b, bf16_t* xbf, float samp_scale, const float* __restrict__ part, int nsplit, bool f32_all) {
;     ...
;   for (int r = gw; r < MT; r += nw) {
;     float* row = R + (size_t)r * 1024;
;     f32x4 v[4];
; #pragma unroll
;     for (int i = 0; i < 4; ++i) v[i] = *(const f32x4*)(row + i * 256 + lane * 4);
;     if (r >= MP) {
;       for (int sp = 0; sp < nsplit; ++sp) {
;         const float* prow = part + ((size_t)sp * MS + (r - MP)) * 1024;
; #pragma unroll
;         for (int i = 0; i < 4; ++i) v[i] = v[i] + *(const f32x4*)(prow + i * 256 + lane * 4);
;       }
;     }
;     float s = 0.f;
; #pragma unroll
;     for (int i = 0; i < 4; ++i) s += v[i][0] + v[i][1] + v[i][2] + v[i][3];
; #pragma unroll
;     for (int o = 32; o >= 1; o >>= 1) s += __shfl_xor(s, o);
;     const float mean = s * (1.f / 1024.f);
;     float ss = 0.f;
; #pragma unroll
;     for (int i = 0; i < 4; ++i) { v[i] = v[i] - mean; ss += v[i][0] * v[i][0] + v[i][1] * v[i][1] + v[i][2] * v[i][2] + v[i][3] * v[i][3]; }
; #pragma unroll
;     for (int o = 32; o >= 1; o >>= 1) ss += __shfl_xor(ss, o);
;     const float rstd = rsqrtf(ss * (1.f / 1024.f) + LN_EPS);
; #pragma unroll
;     for (int i = 0; i < 4; ++i) {
;       const f32x4 y = v[i] * rstd * gv[i] + bv[i];
;       if (r >= MP) *(f32x4*)(row + i * 256 + lane * 4) = y * samp_scale;
;       else if (f32_all) *(f32x4*)(row + i * 256 + lane * 4) = y;
;       if (xbf) {
;         u32x2 wv;
;         wv[0] = cvt_pk_bf16(y[0], y[1]); wv[1] = cvt_pk_bf16(y[2], y[3]);
;         *(u32x2*)(xbf + (size_t)r * 1024 + i * 256 + lane * 4) = wv;
;       }
;     }
	v_pk_add_f32 v[66:67], v[18:19], v[20:21]
	v_pk_add_f32 v[68:69], v[22:23], v[24:25]
	v_pk_add_f32 v[70:71], v[26:27], v[28:29]
	v_pk_add_f32 v[72:73], v[30:31], v[32:33]
	v_pk_add_f32 v[66:67], v[66:67], v[68:69]
	v_pk_add_f32 v[70:71], v[70:71], v[72:73]
	v_pk_add_f32 v[66:67], v[66:67], v[70:71]
	v_add_f32_e32 v66, v66, v67
	s_nop 1
	v_add_f32_dpp v66, v66, v66 row_shr:1 row_mask:0xf bank_mask:0xf bound_ctrl:1
	s_nop 1
	v_add_f32_dpp v66, v66, v66 row_shr:2 row_mask:0xf bank_mask:0xf bound_ctrl:1
	s_nop 1
	v_add_f32_dpp v66, v66, v66 row_shr:4 row_mask:0xf bank_mask:0xf bound_ctrl:1
	s_nop 1
	v_add_f32_dpp v66, v66, v66 row_shr:8 row_mask:0xf bank_mask:0xf bound_ctrl:1
	s_nop 0
	v_readlane_b32 s9, v66, 15
	v_readlane_b32 s10, v66, 31
	v_readlane_b32 s11, v66, 47
	v_readlane_b32 vcc_lo, v66, 63
	s_nop 1
	v_mov_b32_e32 v66, s9
	v_add_f32_e32 v66, s10, v66
	v_add_f32_e32 v66, s11, v66
	v_add_f32_e32 v66, vcc_lo, v66
	v_mul_f32_e32 v116, 0x3a800000, v66
	v_mov_b32_e32 v117, v116
	v_pk_add_f32 v[18:19], v[18:19], v[116:117] neg_lo:[0,1] neg_hi:[0,1]
	v_pk_add_f32 v[20:21], v[20:21], v[116:117] neg_lo:[0,1] neg_hi:[0,1]
	v_pk_add_f32 v[22:23], v[22:23], v[116:117] neg_lo:[0,1] neg_hi:[0,1]
	v_pk_add_f32 v[24:25], v[24:25], v[116:117] neg_lo:[0,1] neg_hi:[0,1]
	v_pk_add_f32 v[26:27], v[26:27], v[116:117] neg_lo:[0,1] neg_hi:[0,1]
	v_pk_add_f32 v[28:29], v[28:29], v[116:117] neg_lo:[0,1] neg_hi:[0,1]
	v_pk_add_f32 v[30:31], v[30:31], v[116:117] neg_lo:[0,1] neg_hi:[0,1]
	v_pk_add_f32 v[32:33], v[32:33], v[116:117] neg_lo:[0,1] neg_hi:[0,1]
	v_pk_mul_f32 v[66:67], v[18:19], v[18:19]
	v_pk_mul_f32 v[68:69], v[20:21], v[20:21]
	v_pk_fma_f32 v[66:67], v[22:23], v[22:23], v[66:67]
	v_pk_fma_f32 v[68:69], v[24:25], v[24:25], v[68:69]
	v_pk_fma_f32 v[66:67], v[26:27], v[26:27], v[66:67]
	v_pk_fma_f32 v[68:69], v[28:29], v[28:29], v[68:69]
	v_pk_fma_f32 v[66:67], v[30:31], v[30:31], v[66:67]
	v_pk_fma_f32 v[68:69], v[32:33], v[32:33], v[68:69]
	v_pk_add_f32 v[66:67], v[66:67], v[68:69]
	v_add_f32_e32 v66, v66, v67
	s_nop 1
	v_add_f32_dpp v66, v66, v66 row_shr:1 row_mask:0xf bank_mask:0xf bound_ctrl:1
	s_nop 1
	v_add_f32_dpp v66, v66, v66 row_shr:2 row_mask:0xf bank_mask:0xf bound_ctrl:1
	s_nop 1
	v_add_f32_dpp v66, v66, v66 row_shr:4 row_mask:0xf bank_mask:0xf bound_ctrl:1
	s_nop 1
	v_add_f32_dpp v66, v66, v66 row_shr:8 row_mask:0xf bank_mask:0xf bound_ctrl:1
	s_nop 0
	v_readlane_b32 s9, v66, 15
	v_readlane_b32 s10, v66, 31
	v_readlane_b32 s11, v66, 47
	v_readlane_b32 vcc_lo, v66, 63
	s_nop 1
	v_mov_b32_e32 v66, s9
	v_add_f32_e32 v66, s10, v66
	v_add_f32_e32 v66, s11, v66
	v_add_f32_e32 v66, vcc_lo, v66
	v_mul_f32_e32 v66, 0x3a800000, v66
	v_add_f32_e32 v66, 0x3727c5ac, v66
	v_rsq_f32_e32 v118, v66
	s_nop 0
	v_mov_b32_e32 v119, v118
	v_pk_mul_f32 v[18:19], v[18:19], v[118:119]
	v_pk_mul_f32 v[20:21], v[20:21], v[118:119]
	v_pk_mul_f32 v[22:23], v[22:23], v[118:119]
	v_pk_mul_f32 v[24:25], v[24:25], v[118:119]
	v_pk_mul_f32 v[26:27], v[26:27], v[118:119]
	v_pk_mul_f32 v[28:29], v[28:29], v[118:119]
	v_pk_mul_f32 v[30:31], v[30:31], v[118:119]
	v_pk_mul_f32 v[32:33], v[32:33], v[118:119]
	v_pk_fma_f32 v[76:77], v[18:19], v[34:35], v[50:51]
	v_pk_fma_f32 v[78:79], v[20:21], v[36:37], v[52:53]
	v_pk_fma_f32 v[80:81], v[22:23], v[38:39], v[54:55]
	v_pk_fma_f32 v[82:83], v[24:25], v[40:41], v[56:57]
	v_pk_fma_f32 v[84:85], v[26:27], v[42:43], v[58:59]
	v_pk_fma_f32 v[86:87], v[28:29], v[44:45], v[60:61]
	v_pk_fma_f32 v[88:89], v[30:31], v[46:47], v[62:63]
	v_pk_fma_f32 v[90:91], v[32:33], v[48:49], v[64:65]
	v_cvt_pk_bf16_f32 v92, v76, v77
	v_cvt_pk_bf16_f32 v93, v78, v79
	v_cvt_pk_bf16_f32 v94, v80, v81
	v_cvt_pk_bf16_f32 v95, v82, v83
	v_cvt_pk_bf16_f32 v96, v84, v85
	v_cvt_pk_bf16_f32 v97, v86, v87
	v_cvt_pk_bf16_f32 v98, v88, v89
	v_cvt_pk_bf16_f32 v99, v90, v91
	global_store_dwordx2 v115, v[92:93], s[2:3] offset:0
	global_store_dwordx2 v115, v[94:95], s[2:3] offset:512
	global_store_dwordx2 v115, v[96:97], s[2:3] offset:1024
	global_store_dwordx2 v115, v[98:99], s[2:3] offset:1536
	s_add_u32 s2, s2, 0x800
	s_addc_u32 s3, s3, 0
	s_add_u32 s0, s0, 0x1000
	s_addc_u32 s1, s1, 0
	global_load_dwordx4 v[18:21], v114, s[0:1] offset:0
	global_load_dwordx4 v[22:25], v114, s[0:1] offset:1024
	global_load_dwordx4 v[26:29], v114, s[0:1] offset:2048
	global_load_dwordx4 v[30:33], v114, s[0:1] offset:3072
	s_waitcnt vmcnt(8)
; __device__ __forceinline__ void phase_ln(float* R, const float* __restrict__ g, const float* __restrict__ b, bf16_t* xbf, float samp_scale, const float* __restrict__ part, int nsplit, bool f32_all) {
;     ...
;   for (int r = gw; r < MT; r += nw) {
;     float* row = R + (size_t)r * 1024;
;     f32x4 v[4];
; #pragma unroll
;     for (int i = 0; i < 4; ++i) v[i] = *(const f32x4*)(row + i * 256 + lane * 4);
;     if (r >= MP) {
;       for (int sp = 0; sp < nsplit; ++sp) {
;         const float* prow = part + ((size_t)sp * MS + (r - MP)) * 1024;
; #pragma unroll
;         for (int i = 0; i < 4; ++i) v[i] = v[i] + *(const f32x4*)(prow + i * 256 + lane * 4);
;       }
;     }
;     float s = 0.f;
; #pragma unroll
;     for (int i = 0; i < 4; ++i) s += v[i][0] + v[i][1] + v[i][2] + v[i][3];
; #pragma unroll
;     for (int o = 32; o >= 1; o >>= 1) s += __shfl_xor(s, o);
;     const float mean = s * (1.f / 1024.f);
;     float ss = 0.f;
; #pragma unroll
;     for (int i = 0; i < 4; ++i) { v[i] = v[i] - mean; ss += v[i][0] * v[i][0] + v[i][1] * v[i][1] + v[i][2] * v[i][2] + v[i][3] * v[i][3]; }
; #pragma unroll
;     for (int o = 32; o >= 1; o >>= 1) ss += __shfl_xor(ss, o);
;     const float rstd = rsqrtf(ss * (1.f / 1024.f) + LN_EPS);
; #pragma unroll
;     for (int i = 0; i < 4; ++i) {
;       const f32x4 y = v[i] * rstd * gv[i] + bv[i];
;       if (r >= MP) *(f32x4*)(row + i * 256 + lane * 4) = y * samp_scale;
;       else if (f32_all) *(f32x4*)(row + i * 256 + lane * 4) = y;
;       if (xbf) {
;         u32x2 wv;
;         wv[0] = cvt_pk_bf16(y[0], y[1]); wv[1] = cvt_pk_bf16(y[2], y[3]);
;         *(u32x2*)(xbf + (size_t)r * 1024 + i * 256 + lane * 4) = wv;
;       }
;     }
	v_pk_add_f32 v[66:67], v[0:1], v[2:3]
	v_pk_add_f32 v[68:69], v[4:5], v[6:7]
	v_pk_add_f32 v[70:71], v[8:9], v[10:11]
	v_pk_add_f32 v[72:73], v[12:13], v[14:15]
	v_pk_add_f32 v[66:67], v[66:67], v[68:69]
	v_pk_add_f32 v[70:71], v[70:71], v[72:73]
	v_pk_add_f32 v[66:67], v[66:67], v[70:71]
	v_add_f32_e32 v66, v66, v67
	s_nop 1
	v_add_f32_dpp v66, v66, v66 row_shr:1 row_mask:0xf bank_mask:0xf bound_ctrl:1
	s_nop 1
	v_add_f32_dpp v66, v66, v66 row_shr:2 row_mask:0xf bank_mask:0xf bound_ctrl:1
	s_nop 1
	v_add_f32_dpp v66, v66, v66 row_shr:4 row_mask:0xf bank_mask:0xf bound_ctrl:1
	s_nop 1
	v_add_f32_dpp v66, v66, v66 row_shr:8 row_mask:0xf bank_mask:0xf bound_ctrl:1
	s_nop 0
	v_readlane_b32 s9, v66, 15
	v_readlane_b32 s10, v66, 31
	v_readlane_b32 s11, v66, 47
	v_readlane_b32 vcc_lo, v66, 63
	s_nop 1
	v_mov_b32_e32 v66, s9
	v_add_f32_e32 v66, s10, v66
	v_add_f32_e32 v66, s11, v66
	v_add_f32_e32 v66, vcc_lo, v66
	v_mul_f32_e32 v116, 0x3a800000, v66
	v_mov_b32_e32 v117, v116
	v_pk_add_f32 v[0:1], v[0:1], v[116:117] neg_lo:[0,1] neg_hi:[0,1]
	v_pk_add_f32 v[2:3], v[2:3], v[116:117] neg_lo:[0,1] neg_hi:[0,1]
	v_pk_add_f32 v[4:5], v[4:5], v[116:117] neg_lo:[0,1] neg_hi:[0,1]
	v_pk_add_f32 v[6:7], v[6:7], v[116:117] neg_lo:[0,1] neg_hi:[0,1]
	v_pk_add_f32 v[8:9], v[8:9], v[116:117] neg_lo:[0,1] neg_hi:[0,1]
	v_pk_add_f32 v[10:11], v[10:11], v[116:117] neg_lo:[0,1] neg_hi:[0,1]
	v_pk_add_f32 v[12:13], v[12:13], v[116:117] neg_lo:[0,1] neg_hi:[0,1]
	v_pk_add_f32 v[14:15], v[14:15], v[116:117] neg_lo:[0,1] neg_hi:[0,1]
	v_pk_mul_f32 v[66:67], v[0:1], v[0:1]
	v_pk_mul_f32 v[68:69], v[2:3], v[2:3]
	v_pk_fma_f32 v[66:67], v[4:5], v[4:5], v[66:67]
	v_pk_fma_f32 v[68:69], v[6:7], v[6:7], v[68:69]
	v_pk_fma_f32 v[66:67], v[8:9], v[8:9], v[66:67]
	v_pk_fma_f32 v[68:69], v[10:11], v[10:11], v[68:69]
	v_pk_fma_f32 v[66:67], v[12:13], v[12:13], v[66:67]
	v_pk_fma_f32 v[68:69], v[14:15], v[14:15], v[68:69]
	v_pk_add_f32 v[66:67], v[66:67], v[68:69]
	v_add_f32_e32 v66, v66, v67
	s_nop 1
	v_add_f32_dpp v66, v66, v66 row_shr:1 row_mask:0xf bank_mask:0xf bound_ctrl:1
	s_nop 1
	v_add_f32_dpp v66, v66, v66 row_shr:2 row_mask:0xf bank_mask:0xf bound_ctrl:1
	s_nop 1
	v_add_f32_dpp v66, v66, v66 row_shr:4 row_mask:0xf bank_mask:0xf bound_ctrl:1
	s_nop 1
	v_add_f32_dpp v66, v66, v66 row_shr:8 row_mask:0xf bank_mask:0xf bound_ctrl:1
	s_nop 0
	v_readlane_b32 s9, v66, 15
	v_readlane_b32 s10, v66, 31
	v_readlane_b32 s11, v66, 47
	v_readlane_b32 vcc_lo, v66, 63
	s_nop 1
	v_mov_b32_e32 v66, s9
	v_add_f32_e32 v66, s10, v66
	v_add_f32_e32 v66, s11, v66
	v_add_f32_e32 v66, vcc_lo, v66
	v_mul_f32_e32 v66, 0x3a800000, v66
	v_add_f32_e32 v66, 0x3727c5ac, v66
	v_rsq_f32_e32 v118, v66
	s_nop 0
	v_mov_b32_e32 v119, v118
	v_pk_mul_f32 v[0:1], v[0:1], v[118:119]
	v_pk_mul_f32 v[2:3], v[2:3], v[118:119]
	v_pk_mul_f32 v[4:5], v[4:5], v[118:119]
	v_pk_mul_f32 v[6:7], v[6:7], v[118:119]
	v_pk_mul_f32 v[8:9], v[8:9], v[118:119]
	v_pk_mul_f32 v[10:11], v[10:11], v[118:119]
	v_pk_mul_f32 v[12:13], v[12:13], v[118:119]
	v_pk_mul_f32 v[14:15], v[14:15], v[118:119]
	v_pk_fma_f32 v[76:77], v[0:1], v[34:35], v[50:51]
	v_pk_fma_f32 v[78:79], v[2:3], v[36:37], v[52:53]
	v_pk_fma_f32 v[80:81], v[4:5], v[38:39], v[54:55]
	v_pk_fma_f32 v[82:83], v[6:7], v[40:41], v[56:57]
	v_pk_fma_f32 v[84:85], v[8:9], v[42:43], v[58:59]
	v_pk_fma_f32 v[86:87], v[10:11], v[44:45], v[60:61]
	v_pk_fma_f32 v[88:89], v[12:13], v[46:47], v[62:63]
	v_pk_fma_f32 v[90:91], v[14:15], v[48:49], v[64:65]
	v_cvt_pk_bf16_f32 v92, v76, v77
	v_cvt_pk_bf16_f32 v93, v78, v79
	v_cvt_pk_bf16_f32 v94, v80, v81
	v_cvt_pk_bf16_f32 v95, v82, v83
	v_cvt_pk_bf16_f32 v96, v84, v85
	v_cvt_pk_bf16_f32 v97, v86, v87
	v_cvt_pk_bf16_f32 v98, v88, v89
	v_cvt_pk_bf16_f32 v99, v90, v91
	global_store_dwordx2 v115, v[92:93], s[2:3] offset:0
	global_store_dwordx2 v115, v[94:95], s[2:3] offset:512
	global_store_dwordx2 v115, v[96:97], s[2:3] offset:1024
	global_store_dwordx2 v115, v[98:99], s[2:3] offset:1536
	s_add_u32 s2, s2, 0x800
	s_addc_u32 s3, s3, 0
	s_add_u32 s0, s0, 0x1000
	s_addc_u32 s1, s1, 0
	global_load_dwordx4 v[0:3], v114, s[0:1] offset:0
	global_load_dwordx4 v[4:7], v114, s[0:1] offset:1024
	global_load_dwordx4 v[8:11], v114, s[0:1] offset:2048
	global_load_dwordx4 v[12:15], v114, s[0:1] offset:3072
	s_waitcnt vmcnt(8)
; __device__ __forceinline__ void phase_ln(float* R, const float* __restrict__ g, const float* __restrict__ b, bf16_t* xbf, float samp_scale, const float* __restrict__ part, int nsplit, bool f32_all) {
;     ...
;   for (int r = gw; r < MT; r += nw) {
;     float* row = R + (size_t)r * 1024;
;     f32x4 v[4];
; #pragma unroll
;     for (int i = 0; i < 4; ++i) v[i] = *(const f32x4*)(row + i * 256 + lane * 4);
;     if (r >= MP) {
;       for (int sp = 0; sp < nsplit; ++sp) {
;         const float* prow = part + ((size_t)sp * MS + (r - MP)) * 1024;
; #pragma unroll
;         for (int i = 0; i < 4; ++i) v[i] = v[i] + *(const f32x4*)(prow + i * 256 + lane * 4);
;       }
;     }
;     float s = 0.f;
; #pragma unroll
;     for (int i = 0; i < 4; ++i) s += v[i][0] + v[i][1] + v[i][2] + v[i][3];
; #pragma unroll
;     for (int o = 32; o >= 1; o >>= 1) s += __shfl_xor(s, o);
;     const float mean = s * (1.f / 1024.f);
;     float ss = 0.f;
; #pragma unroll
;     for (int i = 0; i < 4; ++i) { v[i] = v[i] - mean; ss += v[i][0] * v[i][0] + v[i][1] * v[i][1] + v[i][2] * v[i][2] + v[i][3] * v[i][3]; }
; #pragma unroll
;     for (int o = 32; o >= 1; o >>= 1) ss += __shfl_xor(ss, o);
;     const float rstd = rsqrtf(ss * (1.f / 1024.f) + LN_EPS);
; #pragma unroll
;     for (int i = 0; i < 4; ++i) {
;       const f32x4 y = v[i] * rstd * gv[i] + bv[i];
;       if (r >= MP) *(f32x4*)(row + i * 256 + lane * 4) = y * samp_scale;
;       else if (f32_all) *(f32x4*)(row + i * 256 + lane * 4) = y;
;       if (xbf) {
;         u32x2 wv;
;         wv[0] = cvt_pk_bf16(y[0], y[1]); wv[1] = cvt_pk_bf16(y[2], y[3]);
;         *(u32x2*)(xbf + (size_t)r * 1024 + i * 256 + lane * 4) = wv;
;       }
;     }
	v_pk_add_f32 v[66:67], v[18:19], v[20:21]
	v_pk_add_f32 v[68:69], v[22:23], v[24:25]
	v_pk_add_f32 v[70:71], v[26:27], v[28:29]
	v_pk_add_f32 v[72:73], v[30:31], v[32:33]
	v_pk_add_f32 v[66:67], v[66:67], v[68:69]
	v_pk_add_f32 v[70:71], v[70:71], v[72:73]
	v_pk_add_f32 v[66:67], v[66:67], v[70:71]
	v_add_f32_e32 v66, v66, v67
	s_nop 1
	v_add_f32_dpp v66, v66, v66 row_shr:1 row_mask:0xf bank_mask:0xf bound_ctrl:1
	s_nop 1
	v_add_f32_dpp v66, v66, v66 row_shr:2 row_mask:0xf bank_mask:0xf bound_ctrl:1
	s_nop 1
	v_add_f32_dpp v66, v66, v66 row_shr:4 row_mask:0xf bank_mask:0xf bound_ctrl:1
	s_nop 1
	v_add_f32_dpp v66, v66, v66 row_shr:8 row_mask:0xf bank_mask:0xf bound_ctrl:1
	s_nop 0
	v_readlane_b32 s9, v66, 15
	v_readlane_b32 s10, v66, 31
	v_readlane_b32 s11, v66, 47
	v_readlane_b32 vcc_lo, v66, 63
	s_nop 1
	v_mov_b32_e32 v66, s9
	v_add_f32_e32 v66, s10, v66
	v_add_f32_e32 v66, s11, v66
	v_add_f32_e32 v66, vcc_lo, v66
	v_mul_f32_e32 v116, 0x3a800000, v66
	v_mov_b32_e32 v117, v116
	v_pk_add_f32 v[18:19], v[18:19], v[116:117] neg_lo:[0,1] neg_hi:[0,1]
	v_pk_add_f32 v[20:21], v[20:21], v[116:117] neg_lo:[0,1] neg_hi:[0,1]
	v_pk_add_f32 v[22:23], v[22:23], v[116:117] neg_lo:[0,1] neg_hi:[0,1]
	v_pk_add_f32 v[24:25], v[24:25], v[116:117] neg_lo:[0,1] neg_hi:[0,1]
	v_pk_add_f32 v[26:27], v[26:27], v[116:117] neg_lo:[0,1] neg_hi:[0,1]
	v_pk_add_f32 v[28:29], v[28:29], v[116:117] neg_lo:[0,1] neg_hi:[0,1]
	v_pk_add_f32 v[30:31], v[30:31], v[116:117] neg_lo:[0,1] neg_hi:[0,1]
	v_pk_add_f32 v[32:33], v[32:33], v[116:117] neg_lo:[0,1] neg_hi:[0,1]
	v_pk_mul_f32 v[66:67], v[18:19], v[18:19]
	v_pk_mul_f32 v[68:69], v[20:21], v[20:21]
	v_pk_fma_f32 v[66:67], v[22:23], v[22:23], v[66:67]
	v_pk_fma_f32 v[68:69], v[24:25], v[24:25], v[68:69]
	v_pk_fma_f32 v[66:67], v[26:27], v[26:27], v[66:67]
	v_pk_fma_f32 v[68:69], v[28:29], v[28:29], v[68:69]
	v_pk_fma_f32 v[66:67], v[30:31], v[30:31], v[66:67]
	v_pk_fma_f32 v[68:69], v[32:33], v[32:33], v[68:69]
	v_pk_add_f32 v[66:67], v[66:67], v[68:69]
	v_add_f32_e32 v66, v66, v67
	s_nop 1
	v_add_f32_dpp v66, v66, v66 row_shr:1 row_mask:0xf bank_mask:0xf bound_ctrl:1
	s_nop 1
	v_add_f32_dpp v66, v66, v66 row_shr:2 row_mask:0xf bank_mask:0xf bound_ctrl:1
	s_nop 1
	v_add_f32_dpp v66, v66, v66 row_shr:4 row_mask:0xf bank_mask:0xf bound_ctrl:1
	s_nop 1
	v_add_f32_dpp v66, v66, v66 row_shr:8 row_mask:0xf bank_mask:0xf bound_ctrl:1
	s_nop 0
	v_readlane_b32 s9, v66, 15
	v_readlane_b32 s10, v66, 31
	v_readlane_b32 s11, v66, 47
	v_readlane_b32 vcc_lo, v66, 63
	s_nop 1
	v_mov_b32_e32 v66, s9
	v_add_f32_e32 v66, s10, v66
	v_add_f32_e32 v66, s11, v66
	v_add_f32_e32 v66, vcc_lo, v66
	v_mul_f32_e32 v66, 0x3a800000, v66
	v_add_f32_e32 v66, 0x3727c5ac, v66
	v_rsq_f32_e32 v118, v66
	s_nop 0
	v_mov_b32_e32 v119, v118
	v_pk_mul_f32 v[18:19], v[18:19], v[118:119]
	v_pk_mul_f32 v[20:21], v[20:21], v[118:119]
	v_pk_mul_f32 v[22:23], v[22:23], v[118:119]
	v_pk_mul_f32 v[24:25], v[24:25], v[118:119]
	v_pk_mul_f32 v[26:27], v[26:27], v[118:119]
	v_pk_mul_f32 v[28:29], v[28:29], v[118:119]
	v_pk_mul_f32 v[30:31], v[30:31], v[118:119]
	v_pk_mul_f32 v[32:33], v[32:33], v[118:119]
	v_pk_fma_f32 v[76:77], v[18:19], v[34:35], v[50:51]
	v_pk_fma_f32 v[78:79], v[20:21], v[36:37], v[52:53]
	v_pk_fma_f32 v[80:81], v[22:23], v[38:39], v[54:55]
	v_pk_fma_f32 v[82:83], v[24:25], v[40:41], v[56:57]
	v_pk_fma_f32 v[84:85], v[26:27], v[42:43], v[58:59]
	v_pk_fma_f32 v[86:87], v[28:29], v[44:45], v[60:61]
	v_pk_fma_f32 v[88:89], v[30:31], v[46:47], v[62:63]
	v_pk_fma_f32 v[90:91], v[32:33], v[48:49], v[64:65]
	v_cvt_pk_bf16_f32 v92, v76, v77
	v_cvt_pk_bf16_f32 v93, v78, v79
	v_cvt_pk_bf16_f32 v94, v80, v81
	v_cvt_pk_bf16_f32 v95, v82, v83
	v_cvt_pk_bf16_f32 v96, v84, v85
	v_cvt_pk_bf16_f32 v97, v86, v87
	v_cvt_pk_bf16_f32 v98, v88, v89
	v_cvt_pk_bf16_f32 v99, v90, v91
	global_store_dwordx2 v115, v[92:93], s[2:3] offset:0
	global_store_dwordx2 v115, v[94:95], s[2:3] offset:512
	global_store_dwordx2 v115, v[96:97], s[2:3] offset:1024
	global_store_dwordx2 v115, v[98:99], s[2:3] offset:1536
	s_add_u32 s2, s2, 0x800
	s_addc_u32 s3, s3, 0
	s_add_u32 s0, s0, 0x1000
	s_addc_u32 s1, s1, 0
	global_load_dwordx4 v[18:21], v114, s[0:1] offset:0
	global_load_dwordx4 v[22:25], v114, s[0:1] offset:1024
	global_load_dwordx4 v[26:29], v114, s[0:1] offset:2048
	global_load_dwordx4 v[30:33], v114, s[0:1] offset:3072
	s_waitcnt vmcnt(8)
; __device__ __forceinline__ void phase_ln(float* R, const float* __restrict__ g, const float* __restrict__ b, bf16_t* xbf, float samp_scale, const float* __restrict__ part, int nsplit, bool f32_all) {
;     ...
;   for (int r = gw; r < MT; r += nw) {
;     float* row = R + (size_t)r * 1024;
;     f32x4 v[4];
; #pragma unroll
;     for (int i = 0; i < 4; ++i) v[i] = *(const f32x4*)(row + i * 256 + lane * 4);
;     if (r >= MP) {
;       for (int sp = 0; sp < nsplit; ++sp) {
;         const float* prow = part + ((size_t)sp * MS + (r - MP)) * 1024;
; #pragma unroll
;         for (int i = 0; i < 4; ++i) v[i] = v[i] + *(const f32x4*)(prow + i * 256 + lane * 4);
;       }
;     }
;     float s = 0.f;
; #pragma unroll
;     for (int i = 0; i < 4; ++i) s += v[i][0] + v[i][1] + v[i][2] + v[i][3];
; #pragma unroll
;     for (int o = 32; o >= 1; o >>= 1) s += __shfl_xor(s, o);
;     const float mean = s * (1.f / 1024.f);
;     float ss = 0.f;
; #pragma unroll
;     for (int i = 0; i < 4; ++i) { v[i] = v[i] - mean; ss += v[i][0] * v[i][0] + v[i][1] * v[i][1] + v[i][2] * v[i][2] + v[i][3] * v[i][3]; }
; #pragma unroll
;     for (int o = 32; o >= 1; o >>= 1) ss += __shfl_xor(ss, o);
;     const float rstd = rsqrtf(ss * (1.f / 1024.f) + LN_EPS);
; #pragma unroll
;     for (int i = 0; i < 4; ++i) {
;       const f32x4 y = v[i] * rstd * gv[i] + bv[i];
;       if (r >= MP) *(f32x4*)(row + i * 256 + lane * 4) = y * samp_scale;
;       else if (f32_all) *(f32x4*)(row + i * 256 + lane * 4) = y;
;       if (xbf) {
;         u32x2 wv;
;         wv[0] = cvt_pk_bf16(y[0], y[1]); wv[1] = cvt_pk_bf16(y[2], y[3]);
;         *(u32x2*)(xbf + (size_t)r * 1024 + i * 256 + lane * 4) = wv;
;       }
;     }
	v_pk_add_f32 v[66:67], v[0:1], v[2:3]
	v_pk_add_f32 v[68:69], v[4:5], v[6:7]
	v_pk_add_f32 v[70:71], v[8:9], v[10:11]
	v_pk_add_f32 v[72:73], v[12:13], v[14:15]
	v_pk_add_f32 v[66:67], v[66:67], v[68:69]
	v_pk_add_f32 v[70:71], v[70:71], v[72:73]
	v_pk_add_f32 v[66:67], v[66:67], v[70:71]
	v_add_f32_e32 v66, v66, v67
	s_nop 1
	v_add_f32_dpp v66, v66, v66 row_shr:1 row_mask:0xf bank_mask:0xf bound_ctrl:1
	s_nop 1
	v_add_f32_dpp v66, v66, v66 row_shr:2 row_mask:0xf bank_mask:0xf bound_ctrl:1
	s_nop 1
	v_add_f32_dpp v66, v66, v66 row_shr:4 row_mask:0xf bank_mask:0xf bound_ctrl:1
	s_nop 1
	v_add_f32_dpp v66, v66, v66 row_shr:8 row_mask:0xf bank_mask:0xf bound_ctrl:1
	s_nop 0
	v_readlane_b32 s9, v66, 15
	v_readlane_b32 s10, v66, 31
	v_readlane_b32 s11, v66, 47
	v_readlane_b32 vcc_lo, v66, 63
	s_nop 1
	v_mov_b32_e32 v66, s9
	v_add_f32_e32 v66, s10, v66
	v_add_f32_e32 v66, s11, v66
	v_add_f32_e32 v66, vcc_lo, v66
	v_mul_f32_e32 v116, 0x3a800000, v66
	v_mov_b32_e32 v117, v116
	v_pk_add_f32 v[0:1], v[0:1], v[116:117] neg_lo:[0,1] neg_hi:[0,1]
	v_pk_add_f32 v[2:3], v[2:3], v[116:117] neg_lo:[0,1] neg_hi:[0,1]
	v_pk_add_f32 v[4:5], v[4:5], v[116:117] neg_lo:[0,1] neg_hi:[0,1]
	v_pk_add_f32 v[6:7], v[6:7], v[116:117] neg_lo:[0,1] neg_hi:[0,1]
	v_pk_add_f32 v[8:9], v[8:9], v[116:117] neg_lo:[0,1] neg_hi:[0,1]
	v_pk_add_f32 v[10:11], v[10:11], v[116:117] neg_lo:[0,1] neg_hi:[0,1]
	v_pk_add_f32 v[12:13], v[12:13], v[116:117] neg_lo:[0,1] neg_hi:[0,1]
	v_pk_add_f32 v[14:15], v[14:15], v[116:117] neg_lo:[0,1] neg_hi:[0,1]
	v_pk_mul_f32 v[66:67], v[0:1], v[0:1]
	v_pk_mul_f32 v[68:69], v[2:3], v[2:3]
	v_pk_fma_f32 v[66:67], v[4:5], v[4:5], v[66:67]
	v_pk_fma_f32 v[68:69], v[6:7], v[6:7], v[68:69]
	v_pk_fma_f32 v[66:67], v[8:9], v[8:9], v[66:67]
	v_pk_fma_f32 v[68:69], v[10:11], v[10:11], v[68:69]
	v_pk_fma_f32 v[66:67], v[12:13], v[12:13], v[66:67]
	v_pk_fma_f32 v[68:69], v[14:15], v[14:15], v[68:69]
	v_pk_add_f32 v[66:67], v[66:67], v[68:69]
	v_add_f32_e32 v66, v66, v67
	s_nop 1
	v_add_f32_dpp v66, v66, v66 row_shr:1 row_mask:0xf bank_mask:0xf bound_ctrl:1
	s_nop 1
	v_add_f32_dpp v66, v66, v66 row_shr:2 row_mask:0xf bank_mask:0xf bound_ctrl:1
	s_nop 1
	v_add_f32_dpp v66, v66, v66 row_shr:4 row_mask:0xf bank_mask:0xf bound_ctrl:1
	s_nop 1
	v_add_f32_dpp v66, v66, v66 row_shr:8 row_mask:0xf bank_mask:0xf bound_ctrl:1
	s_nop 0
	v_readlane_b32 s9, v66, 15
	v_readlane_b32 s10, v66, 31
	v_readlane_b32 s11, v66, 47
	v_readlane_b32 vcc_lo, v66, 63
	s_nop 1
	v_mov_b32_e32 v66, s9
	v_add_f32_e32 v66, s10, v66
	v_add_f32_e32 v66, s11, v66
	v_add_f32_e32 v66, vcc_lo, v66
	v_mul_f32_e32 v66, 0x3a800000, v66
	v_add_f32_e32 v66, 0x3727c5ac, v66
	v_rsq_f32_e32 v118, v66
	s_nop 0
	v_mov_b32_e32 v119, v118
	v_pk_mul_f32 v[0:1], v[0:1], v[118:119]
	v_pk_mul_f32 v[2:3], v[2:3], v[118:119]
	v_pk_mul_f32 v[4:5], v[4:5], v[118:119]
	v_pk_mul_f32 v[6:7], v[6:7], v[118:119]
	v_pk_mul_f32 v[8:9], v[8:9], v[118:119]
	v_pk_mul_f32 v[10:11], v[10:11], v[118:119]
	v_pk_mul_f32 v[12:13], v[12:13], v[118:119]
	v_pk_mul_f32 v[14:15], v[14:15], v[118:119]
	v_pk_fma_f32 v[76:77], v[0:1], v[34:35], v[50:51]
	v_pk_fma_f32 v[78:79], v[2:3], v[36:37], v[52:53]
	v_pk_fma_f32 v[80:81], v[4:5], v[38:39], v[54:55]
	v_pk_fma_f32 v[82:83], v[6:7], v[40:41], v[56:57]
	v_pk_fma_f32 v[84:85], v[8:9], v[42:43], v[58:59]
	v_pk_fma_f32 v[86:87], v[10:11], v[44:45], v[60:61]
	v_pk_fma_f32 v[88:89], v[12:13], v[46:47], v[62:63]
	v_pk_fma_f32 v[90:91], v[14:15], v[48:49], v[64:65]
	v_cvt_pk_bf16_f32 v92, v76, v77
	v_cvt_pk_bf16_f32 v93, v78, v79
	v_cvt_pk_bf16_f32 v94, v80, v81
	v_cvt_pk_bf16_f32 v95, v82, v83
	v_cvt_pk_bf16_f32 v96, v84, v85
	v_cvt_pk_bf16_f32 v97, v86, v87
	v_cvt_pk_bf16_f32 v98, v88, v89
	v_cvt_pk_bf16_f32 v99, v90, v91
	global_store_dwordx2 v115, v[92:93], s[2:3] offset:0
	global_store_dwordx2 v115, v[94:95], s[2:3] offset:512
	global_store_dwordx2 v115, v[96:97], s[2:3] offset:1024
	global_store_dwordx2 v115, v[98:99], s[2:3] offset:1536
	s_add_u32 s2, s2, 0x800
	s_addc_u32 s3, s3, 0
	s_add_u32 s0, s0, 0x1000
	s_addc_u32 s1, s1, 0
	global_load_dwordx4 v[0:3], v114, s[0:1] offset:0
	global_load_dwordx4 v[4:7], v114, s[0:1] offset:1024
	global_load_dwordx4 v[8:11], v114, s[0:1] offset:2048
	global_load_dwordx4 v[12:15], v114, s[0:1] offset:3072
	s_waitcnt vmcnt(8)
; __device__ __forceinline__ void phase_ln(float* R, const float* __restrict__ g, const float* __restrict__ b, bf16_t* xbf, float samp_scale, const float* __restrict__ part, int nsplit, bool f32_all) {
;     ...
;   for (int r = gw; r < MT; r += nw) {
;     float* row = R + (size_t)r * 1024;
;     f32x4 v[4];
; #pragma unroll
;     for (int i = 0; i < 4; ++i) v[i] = *(const f32x4*)(row + i * 256 + lane * 4);
;     if (r >= MP) {
;       for (int sp = 0; sp < nsplit; ++sp) {
;         const float* prow = part + ((size_t)sp * MS + (r - MP)) * 1024;
; #pragma unroll
;         for (int i = 0; i < 4; ++i) v[i] = v[i] + *(const f32x4*)(prow + i * 256 + lane * 4);
;       }
;     }
;     float s = 0.f;
; #pragma unroll
;     for (int i = 0; i < 4; ++i) s += v[i][0] + v[i][1] + v[i][2] + v[i][3];
; #pragma unroll
;     for (int o = 32; o >= 1; o >>= 1) s += __shfl_xor(s, o);
;     const float mean = s * (1.f / 1024.f);
;     float ss = 0.f;
; #pragma unroll
;     for (int i = 0; i < 4; ++i) { v[i] = v[i] - mean; ss += v[i][0] * v[i][0] + v[i][1] * v[i][1] + v[i][2] * v[i][2] + v[i][3] * v[i][3]; }
; #pragma unroll
;     for (int o = 32; o >= 1; o >>= 1) ss += __shfl_xor(ss, o);
;     const float rstd = rsqrtf(ss * (1.f / 1024.f) + LN_EPS);
; #pragma unroll
;     for (int i = 0; i < 4; ++i) {
;       const f32x4 y = v[i] * rstd * gv[i] + bv[i];
;       if (r >= MP) *(f32x4*)(row + i * 256 + lane * 4) = y * samp_scale;
;       else if (f32_all) *(f32x4*)(row + i * 256 + lane * 4) = y;
;       if (xbf) {
;         u32x2 wv;
;         wv[0] = cvt_pk_bf16(y[0], y[1]); wv[1] = cvt_pk_bf16(y[2], y[3]);
;         *(u32x2*)(xbf + (size_t)r * 1024 + i * 256 + lane * 4) = wv;
;       }
;     }
	v_pk_add_f32 v[66:67], v[18:19], v[20:21]
	v_pk_add_f32 v[68:69], v[22:23], v[24:25]
	v_pk_add_f32 v[70:71], v[26:27], v[28:29]
	v_pk_add_f32 v[72:73], v[30:31], v[32:33]
	v_pk_add_f32 v[66:67], v[66:67], v[68:69]
	v_pk_add_f32 v[70:71], v[70:71], v[72:73]
	v_pk_add_f32 v[66:67], v[66:67], v[70:71]
	v_add_f32_e32 v66, v66, v67
	s_nop 1
	v_add_f32_dpp v66, v66, v66 row_shr:1 row_mask:0xf bank_mask:0xf bound_ctrl:1
	s_nop 1
	v_add_f32_dpp v66, v66, v66 row_shr:2 row_mask:0xf bank_mask:0xf bound_ctrl:1
	s_nop 1
	v_add_f32_dpp v66, v66, v66 row_shr:4 row_mask:0xf bank_mask:0xf bound_ctrl:1
	s_nop 1
	v_add_f32_dpp v66, v66, v66 row_shr:8 row_mask:0xf bank_mask:0xf bound_ctrl:1
	s_nop 0
	v_readlane_b32 s9, v66, 15
	v_readlane_b32 s10, v66, 31
	v_readlane_b32 s11, v66, 47
	v_readlane_b32 vcc_lo, v66, 63
	s_nop 1
	v_mov_b32_e32 v66, s9
	v_add_f32_e32 v66, s10, v66
	v_add_f32_e32 v66, s11, v66
	v_add_f32_e32 v66, vcc_lo, v66
	v_mul_f32_e32 v116, 0x3a800000, v66
	v_mov_b32_e32 v117, v116
	v_pk_add_f32 v[18:19], v[18:19], v[116:117] neg_lo:[0,1] neg_hi:[0,1]
	v_pk_add_f32 v[20:21], v[20:21], v[116:117] neg_lo:[0,1] neg_hi:[0,1]
	v_pk_add_f32 v[22:23], v[22:23], v[116:117] neg_lo:[0,1] neg_hi:[0,1]
	v_pk_add_f32 v[24:25], v[24:25], v[116:117] neg_lo:[0,1] neg_hi:[0,1]
	v_pk_add_f32 v[26:27], v[26:27], v[116:117] neg_lo:[0,1] neg_hi:[0,1]
	v_pk_add_f32 v[28:29], v[28:29], v[116:117] neg_lo:[0,1] neg_hi:[0,1]
	v_pk_add_f32 v[30:31], v[30:31], v[116:117] neg_lo:[0,1] neg_hi:[0,1]
	v_pk_add_f32 v[32:33], v[32:33], v[116:117] neg_lo:[0,1] neg_hi:[0,1]
	v_pk_mul_f32 v[66:67], v[18:19], v[18:19]
	v_pk_mul_f32 v[68:69], v[20:21], v[20:21]
	v_pk_fma_f32 v[66:67], v[22:23], v[22:23], v[66:67]
	v_pk_fma_f32 v[68:69], v[24:25], v[24:25], v[68:69]
	v_pk_fma_f32 v[66:67], v[26:27], v[26:27], v[66:67]
	v_pk_fma_f32 v[68:69], v[28:29], v[28:29], v[68:69]
	v_pk_fma_f32 v[66:67], v[30:31], v[30:31], v[66:67]
	v_pk_fma_f32 v[68:69], v[32:33], v[32:33], v[68:69]
	v_pk_add_f32 v[66:67], v[66:67], v[68:69]
	v_add_f32_e32 v66, v66, v67
	s_nop 1
	v_add_f32_dpp v66, v66, v66 row_shr:1 row_mask:0xf bank_mask:0xf bound_ctrl:1
	s_nop 1
	v_add_f32_dpp v66, v66, v66 row_shr:2 row_mask:0xf bank_mask:0xf bound_ctrl:1
	s_nop 1
	v_add_f32_dpp v66, v66, v66 row_shr:4 row_mask:0xf bank_mask:0xf bound_ctrl:1
	s_nop 1
	v_add_f32_dpp v66, v66, v66 row_shr:8 row_mask:0xf bank_mask:0xf bound_ctrl:1
	s_nop 0
	v_readlane_b32 s9, v66, 15
	v_readlane_b32 s10, v66, 31
	v_readlane_b32 s11, v66, 47
	v_readlane_b32 vcc_lo, v66, 63
	s_nop 1
	v_mov_b32_e32 v66, s9
	v_add_f32_e32 v66, s10, v66
	v_add_f32_e32 v66, s11, v66
	v_add_f32_e32 v66, vcc_lo, v66
	v_mul_f32_e32 v66, 0x3a800000, v66
	v_add_f32_e32 v66, 0x3727c5ac, v66
	v_rsq_f32_e32 v118, v66
	s_nop 0
	v_mov_b32_e32 v119, v118
	v_pk_mul_f32 v[18:19], v[18:19], v[118:119]
	v_pk_mul_f32 v[20:21], v[20:21], v[118:119]
	v_pk_mul_f32 v[22:23], v[22:23], v[118:119]
	v_pk_mul_f32 v[24:25], v[24:25], v[118:119]
	v_pk_mul_f32 v[26:27], v[26:27], v[118:119]
	v_pk_mul_f32 v[28:29], v[28:29], v[118:119]
	v_pk_mul_f32 v[30:31], v[30:31], v[118:119]
	v_pk_mul_f32 v[32:33], v[32:33], v[118:119]
	v_pk_fma_f32 v[76:77], v[18:19], v[34:35], v[50:51]
	v_pk_fma_f32 v[78:79], v[20:21], v[36:37], v[52:53]
	v_pk_fma_f32 v[80:81], v[22:23], v[38:39], v[54:55]
	v_pk_fma_f32 v[82:83], v[24:25], v[40:41], v[56:57]
	v_pk_fma_f32 v[84:85], v[26:27], v[42:43], v[58:59]
	v_pk_fma_f32 v[86:87], v[28:29], v[44:45], v[60:61]
	v_pk_fma_f32 v[88:89], v[30:31], v[46:47], v[62:63]
	v_pk_fma_f32 v[90:91], v[32:33], v[48:49], v[64:65]
	v_cvt_pk_bf16_f32 v92, v76, v77
	v_cvt_pk_bf16_f32 v93, v78, v79
	v_cvt_pk_bf16_f32 v94, v80, v81
	v_cvt_pk_bf16_f32 v95, v82, v83
	v_cvt_pk_bf16_f32 v96, v84, v85
	v_cvt_pk_bf16_f32 v97, v86, v87
	v_cvt_pk_bf16_f32 v98, v88, v89
	v_cvt_pk_bf16_f32 v99, v90, v91
	global_store_dwordx2 v115, v[92:93], s[2:3] offset:0
	global_store_dwordx2 v115, v[94:95], s[2:3] offset:512
	global_store_dwordx2 v115, v[96:97], s[2:3] offset:1024
	global_store_dwordx2 v115, v[98:99], s[2:3] offset:1536
	s_add_u32 s2, s2, 0x800
	s_addc_u32 s3, s3, 0
	s_add_u32 s0, s0, 0x1000
	s_addc_u32 s1, s1, 0
	global_load_dwordx4 v[18:21], v114, s[0:1] offset:0
	global_load_dwordx4 v[22:25], v114, s[0:1] offset:1024
	global_load_dwordx4 v[26:29], v114, s[0:1] offset:2048
	global_load_dwordx4 v[30:33], v114, s[0:1] offset:3072
	s_waitcnt vmcnt(8)
; __device__ __forceinline__ void phase_ln(float* R, const float* __restrict__ g, const float* __restrict__ b, bf16_t* xbf, float samp_scale, const float* __restrict__ part, int nsplit, bool f32_all) {
;     ...
;   for (int r = gw; r < MT; r += nw) {
;     float* row = R + (size_t)r * 1024;
;     f32x4 v[4];
; #pragma unroll
;     for (int i = 0; i < 4; ++i) v[i] = *(const f32x4*)(row + i * 256 + lane * 4);
;     if (r >= MP) {
;       for (int sp = 0; sp < nsplit; ++sp) {
;         const float* prow = part + ((size_t)sp * MS + (r - MP)) * 1024;
; #pragma unroll
;         for (int i = 0; i < 4; ++i) v[i] = v[i] + *(const f32x4*)(prow + i * 256 + lane * 4);
;       }
;     }
;     float s = 0.f;
; #pragma unroll
;     for (int i = 0; i < 4; ++i) s += v[i][0] + v[i][1] + v[i][2] + v[i][3];
; #pragma unroll
;     for (int o = 32; o >= 1; o >>= 1) s += __shfl_xor(s, o);
;     const float mean = s * (1.f / 1024.f);
;     float ss = 0.f;
; #pragma unroll
;     for (int i = 0; i < 4; ++i) { v[i] = v[i] - mean; ss += v[i][0] * v[i][0] + v[i][1] * v[i][1] + v[i][2] * v[i][2] + v[i][3] * v[i][3]; }
; #pragma unroll
;     for (int o = 32; o >= 1; o >>= 1) ss += __shfl_xor(ss, o);
;     const float rstd = rsqrtf(ss * (1.f / 1024.f) + LN_EPS);
; #pragma unroll
;     for (int i = 0; i < 4; ++i) {
;       const f32x4 y = v[i] * rstd * gv[i] + bv[i];
;       if (r >= MP) *(f32x4*)(row + i * 256 + lane * 4) = y * samp_scale;
;       else if (f32_all) *(f32x4*)(row + i * 256 + lane * 4) = y;
;       if (xbf) {
;         u32x2 wv;
;         wv[0] = cvt_pk_bf16(y[0], y[1]); wv[1] = cvt_pk_bf16(y[2], y[3]);
;         *(u32x2*)(xbf + (size_t)r * 1024 + i * 256 + lane * 4) = wv;
;       }
;     }
	v_pk_add_f32 v[66:67], v[0:1], v[2:3]
	v_pk_add_f32 v[68:69], v[4:5], v[6:7]
	v_pk_add_f32 v[70:71], v[8:9], v[10:11]
	v_pk_add_f32 v[72:73], v[12:13], v[14:15]
	v_pk_add_f32 v[66:67], v[66:67], v[68:69]
	v_pk_add_f32 v[70:71], v[70:71], v[72:73]
	v_pk_add_f32 v[66:67], v[66:67], v[70:71]
	v_add_f32_e32 v66, v66, v67
	s_nop 1
	v_add_f32_dpp v66, v66, v66 row_shr:1 row_mask:0xf bank_mask:0xf bound_ctrl:1
	s_nop 1
	v_add_f32_dpp v66, v66, v66 row_shr:2 row_mask:0xf bank_mask:0xf bound_ctrl:1
	s_nop 1
	v_add_f32_dpp v66, v66, v66 row_shr:4 row_mask:0xf bank_mask:0xf bound_ctrl:1
	s_nop 1
	v_add_f32_dpp v66, v66, v66 row_shr:8 row_mask:0xf bank_mask:0xf bound_ctrl:1
	s_nop 0
	v_readlane_b32 s9, v66, 15
	v_readlane_b32 s10, v66, 31
	v_readlane_b32 s11, v66, 47
	v_readlane_b32 vcc_lo, v66, 63
	s_nop 1
	v_mov_b32_e32 v66, s9
	v_add_f32_e32 v66, s10, v66
	v_add_f32_e32 v66, s11, v66
	v_add_f32_e32 v66, vcc_lo, v66
	v_mul_f32_e32 v116, 0x3a800000, v66
	v_mov_b32_e32 v117, v116
	v_pk_add_f32 v[0:1], v[0:1], v[116:117] neg_lo:[0,1] neg_hi:[0,1]
	v_pk_add_f32 v[2:3], v[2:3], v[116:117] neg_lo:[0,1] neg_hi:[0,1]
	v_pk_add_f32 v[4:5], v[4:5], v[116:117] neg_lo:[0,1] neg_hi:[0,1]
	v_pk_add_f32 v[6:7], v[6:7], v[116:117] neg_lo:[0,1] neg_hi:[0,1]
	v_pk_add_f32 v[8:9], v[8:9], v[116:117] neg_lo:[0,1] neg_hi:[0,1]
	v_pk_add_f32 v[10:11], v[10:11], v[116:117] neg_lo:[0,1] neg_hi:[0,1]
	v_pk_add_f32 v[12:13], v[12:13], v[116:117] neg_lo:[0,1] neg_hi:[0,1]
	v_pk_add_f32 v[14:15], v[14:15], v[116:117] neg_lo:[0,1] neg_hi:[0,1]
	v_pk_mul_f32 v[66:67], v[0:1], v[0:1]
	v_pk_mul_f32 v[68:69], v[2:3], v[2:3]
	v_pk_fma_f32 v[66:67], v[4:5], v[4:5], v[66:67]
	v_pk_fma_f32 v[68:69], v[6:7], v[6:7], v[68:69]
	v_pk_fma_f32 v[66:67], v[8:9], v[8:9], v[66:67]
	v_pk_fma_f32 v[68:69], v[10:11], v[10:11], v[68:69]
	v_pk_fma_f32 v[66:67], v[12:13], v[12:13], v[66:67]
	v_pk_fma_f32 v[68:69], v[14:15], v[14:15], v[68:69]
	v_pk_add_f32 v[66:67], v[66:67], v[68:69]
	v_add_f32_e32 v66, v66, v67
	s_nop 1
	v_add_f32_dpp v66, v66, v66 row_shr:1 row_mask:0xf bank_mask:0xf bound_ctrl:1
	s_nop 1
	v_add_f32_dpp v66, v66, v66 row_shr:2 row_mask:0xf bank_mask:0xf bound_ctrl:1
	s_nop 1
	v_add_f32_dpp v66, v66, v66 row_shr:4 row_mask:0xf bank_mask:0xf bound_ctrl:1
	s_nop 1
	v_add_f32_dpp v66, v66, v66 row_shr:8 row_mask:0xf bank_mask:0xf bound_ctrl:1
	s_nop 0
	v_readlane_b32 s9, v66, 15
	v_readlane_b32 s10, v66, 31
	v_readlane_b32 s11, v66, 47
	v_readlane_b32 vcc_lo, v66, 63
	s_nop 1
	v_mov_b32_e32 v66, s9
	v_add_f32_e32 v66, s10, v66
	v_add_f32_e32 v66, s11, v66
	v_add_f32_e32 v66, vcc_lo, v66
	v_mul_f32_e32 v66, 0x3a800000, v66
	v_add_f32_e32 v66, 0x3727c5ac, v66
	v_rsq_f32_e32 v118, v66
	s_nop 0
	v_mov_b32_e32 v119, v118
	v_pk_mul_f32 v[0:1], v[0:1], v[118:119]
	v_pk_mul_f32 v[2:3], v[2:3], v[118:119]
	v_pk_mul_f32 v[4:5], v[4:5], v[118:119]
	v_pk_mul_f32 v[6:7], v[6:7], v[118:119]
	v_pk_mul_f32 v[8:9], v[8:9], v[118:119]
	v_pk_mul_f32 v[10:11], v[10:11], v[118:119]
	v_pk_mul_f32 v[12:13], v[12:13], v[118:119]
	v_pk_mul_f32 v[14:15], v[14:15], v[118:119]
	v_pk_fma_f32 v[76:77], v[0:1], v[34:35], v[50:51]
	v_pk_fma_f32 v[78:79], v[2:3], v[36:37], v[52:53]
	v_pk_fma_f32 v[80:81], v[4:5], v[38:39], v[54:55]
	v_pk_fma_f32 v[82:83], v[6:7], v[40:41], v[56:57]
	v_pk_fma_f32 v[84:85], v[8:9], v[42:43], v[58:59]
	v_pk_fma_f32 v[86:87], v[10:11], v[44:45], v[60:61]
	v_pk_fma_f32 v[88:89], v[12:13], v[46:47], v[62:63]
	v_pk_fma_f32 v[90:91], v[14:15], v[48:49], v[64:65]
	v_cvt_pk_bf16_f32 v92, v76, v77
	v_cvt_pk_bf16_f32 v93, v78, v79
	v_cvt_pk_bf16_f32 v94, v80, v81
	v_cvt_pk_bf16_f32 v95, v82, v83
	v_cvt_pk_bf16_f32 v96, v84, v85
	v_cvt_pk_bf16_f32 v97, v86, v87
	v_cvt_pk_bf16_f32 v98, v88, v89
	v_cvt_pk_bf16_f32 v99, v90, v91
	global_store_dwordx2 v115, v[92:93], s[2:3] offset:0
	global_store_dwordx2 v115, v[94:95], s[2:3] offset:512
	global_store_dwordx2 v115, v[96:97], s[2:3] offset:1024
	global_store_dwordx2 v115, v[98:99], s[2:3] offset:1536
	s_add_u32 s2, s2, 0x800
	s_addc_u32 s3, s3, 0
	s_add_u32 s0, s0, 0x1000
	s_addc_u32 s1, s1, 0
	global_load_dwordx4 v[0:3], v114, s[0:1] offset:0
	global_load_dwordx4 v[4:7], v114, s[0:1] offset:1024
	global_load_dwordx4 v[8:11], v114, s[0:1] offset:2048
	global_load_dwordx4 v[12:15], v114, s[0:1] offset:3072
	s_waitcnt vmcnt(8)
; __device__ __forceinline__ void phase_ln(float* R, const float* __restrict__ g, const float* __restrict__ b, bf16_t* xbf, float samp_scale, const float* __restrict__ part, int nsplit, bool f32_all) {
;     ...
;   for (int r = gw; r < MT; r += nw) {
;     float* row = R + (size_t)r * 1024;
;     f32x4 v[4];
; #pragma unroll
;     for (int i = 0; i < 4; ++i) v[i] = *(const f32x4*)(row + i * 256 + lane * 4);
;     if (r >= MP) {
;       for (int sp = 0; sp < nsplit; ++sp) {
;         const float* prow = part + ((size_t)sp * MS + (r - MP)) * 1024;
; #pragma unroll
;         for (int i = 0; i < 4; ++i) v[i] = v[i] + *(const f32x4*)(prow + i * 256 + lane * 4);
;       }
;     }
;     float s = 0.f;
; #pragma unroll
;     for (int i = 0; i < 4; ++i) s += v[i][0] + v[i][1] + v[i][2] + v[i][3];
; #pragma unroll
;     for (int o = 32; o >= 1; o >>= 1) s += __shfl_xor(s, o);
;     const float mean = s * (1.f / 1024.f);
;     float ss = 0.f;
; #pragma unroll
;     for (int i = 0; i < 4; ++i) { v[i] = v[i] - mean; ss += v[i][0] * v[i][0] + v[i][1] * v[i][1] + v[i][2] * v[i][2] + v[i][3] * v[i][3]; }
; #pragma unroll
;     for (int o = 32; o >= 1; o >>= 1) ss += __shfl_xor(ss, o);
;     const float rstd = rsqrtf(ss * (1.f / 1024.f) + LN_EPS);
; #pragma unroll
;     for (int i = 0; i < 4; ++i) {
;       const f32x4 y = v[i] * rstd * gv[i] + bv[i];
;       if (r >= MP) *(f32x4*)(row + i * 256 + lane * 4) = y * samp_scale;
;       else if (f32_all) *(f32x4*)(row + i * 256 + lane * 4) = y;
;       if (xbf) {
;         u32x2 wv;
;         wv[0] = cvt_pk_bf16(y[0], y[1]); wv[1] = cvt_pk_bf16(y[2], y[3]);
;         *(u32x2*)(xbf + (size_t)r * 1024 + i * 256 + lane * 4) = wv;
;       }
;     }
	v_pk_add_f32 v[66:67], v[18:19], v[20:21]
	v_pk_add_f32 v[68:69], v[22:23], v[24:25]
	v_pk_add_f32 v[70:71], v[26:27], v[28:29]
	v_pk_add_f32 v[72:73], v[30:31], v[32:33]
	v_pk_add_f32 v[66:67], v[66:67], v[68:69]
	v_pk_add_f32 v[70:71], v[70:71], v[72:73]
	v_pk_add_f32 v[66:67], v[66:67], v[70:71]
	v_add_f32_e32 v66, v66, v67
	s_nop 1
	v_add_f32_dpp v66, v66, v66 row_shr:1 row_mask:0xf bank_mask:0xf bound_ctrl:1
	s_nop 1
	v_add_f32_dpp v66, v66, v66 row_shr:2 row_mask:0xf bank_mask:0xf bound_ctrl:1
	s_nop 1
	v_add_f32_dpp v66, v66, v66 row_shr:4 row_mask:0xf bank_mask:0xf bound_ctrl:1
	s_nop 1
	v_add_f32_dpp v66, v66, v66 row_shr:8 row_mask:0xf bank_mask:0xf bound_ctrl:1
	s_nop 0
	v_readlane_b32 s9, v66, 15
	v_readlane_b32 s10, v66, 31
	v_readlane_b32 s11, v66, 47
	v_readlane_b32 vcc_lo, v66, 63
	s_nop 1
	v_mov_b32_e32 v66, s9
	v_add_f32_e32 v66, s10, v66
	v_add_f32_e32 v66, s11, v66
	v_add_f32_e32 v66, vcc_lo, v66
	v_mul_f32_e32 v116, 0x3a800000, v66
	v_mov_b32_e32 v117, v116
	v_pk_add_f32 v[18:19], v[18:19], v[116:117] neg_lo:[0,1] neg_hi:[0,1]
	v_pk_add_f32 v[20:21], v[20:21], v[116:117] neg_lo:[0,1] neg_hi:[0,1]
	v_pk_add_f32 v[22:23], v[22:23], v[116:117] neg_lo:[0,1] neg_hi:[0,1]
	v_pk_add_f32 v[24:25], v[24:25], v[116:117] neg_lo:[0,1] neg_hi:[0,1]
	v_pk_add_f32 v[26:27], v[26:27], v[116:117] neg_lo:[0,1] neg_hi:[0,1]
	v_pk_add_f32 v[28:29], v[28:29], v[116:117] neg_lo:[0,1] neg_hi:[0,1]
	v_pk_add_f32 v[30:31], v[30:31], v[116:117] neg_lo:[0,1] neg_hi:[0,1]
	v_pk_add_f32 v[32:33], v[32:33], v[116:117] neg_lo:[0,1] neg_hi:[0,1]
	v_pk_mul_f32 v[66:67], v[18:19], v[18:19]
	v_pk_mul_f32 v[68:69], v[20:21], v[20:21]
	v_pk_fma_f32 v[66:67], v[22:23], v[22:23], v[66:67]
	v_pk_fma_f32 v[68:69], v[24:25], v[24:25], v[68:69]
	v_pk_fma_f32 v[66:67], v[26:27], v[26:27], v[66:67]
	v_pk_fma_f32 v[68:69], v[28:29], v[28:29], v[68:69]
	v_pk_fma_f32 v[66:67], v[30:31], v[30:31], v[66:67]
	v_pk_fma_f32 v[68:69], v[32:33], v[32:33], v[68:69]
	v_pk_add_f32 v[66:67], v[66:67], v[68:69]
	v_add_f32_e32 v66, v66, v67
	s_nop 1
	v_add_f32_dpp v66, v66, v66 row_shr:1 row_mask:0xf bank_mask:0xf bound_ctrl:1
	s_nop 1
	v_add_f32_dpp v66, v66, v66 row_shr:2 row_mask:0xf bank_mask:0xf bound_ctrl:1
	s_nop 1
	v_add_f32_dpp v66, v66, v66 row_shr:4 row_mask:0xf bank_mask:0xf bound_ctrl:1
	s_nop 1
	v_add_f32_dpp v66, v66, v66 row_shr:8 row_mask:0xf bank_mask:0xf bound_ctrl:1
	s_nop 0
	v_readlane_b32 s9, v66, 15
	v_readlane_b32 s10, v66, 31
	v_readlane_b32 s11, v66, 47
	v_readlane_b32 vcc_lo, v66, 63
	s_nop 1
	v_mov_b32_e32 v66, s9
	v_add_f32_e32 v66, s10, v66
	v_add_f32_e32 v66, s11, v66
	v_add_f32_e32 v66, vcc_lo, v66
	v_mul_f32_e32 v66, 0x3a800000, v66
	v_add_f32_e32 v66, 0x3727c5ac, v66
	v_rsq_f32_e32 v118, v66
	s_nop 0
	v_mov_b32_e32 v119, v118
	v_pk_mul_f32 v[18:19], v[18:19], v[118:119]
	v_pk_mul_f32 v[20:21], v[20:21], v[118:119]
	v_pk_mul_f32 v[22:23], v[22:23], v[118:119]
	v_pk_mul_f32 v[24:25], v[24:25], v[118:119]
	v_pk_mul_f32 v[26:27], v[26:27], v[118:119]
	v_pk_mul_f32 v[28:29], v[28:29], v[118:119]
	v_pk_mul_f32 v[30:31], v[30:31], v[118:119]
	v_pk_mul_f32 v[32:33], v[32:33], v[118:119]
	v_pk_fma_f32 v[76:77], v[18:19], v[34:35], v[50:51]
	v_pk_fma_f32 v[78:79], v[20:21], v[36:37], v[52:53]
	v_pk_fma_f32 v[80:81], v[22:23], v[38:39], v[54:55]
	v_pk_fma_f32 v[82:83], v[24:25], v[40:41], v[56:57]
	v_pk_fma_f32 v[84:85], v[26:27], v[42:43], v[58:59]
	v_pk_fma_f32 v[86:87], v[28:29], v[44:45], v[60:61]
	v_pk_fma_f32 v[88:89], v[30:31], v[46:47], v[62:63]
	v_pk_fma_f32 v[90:91], v[32:33], v[48:49], v[64:65]
	v_cvt_pk_bf16_f32 v92, v76, v77
	v_cvt_pk_bf16_f32 v93, v78, v79
	v_cvt_pk_bf16_f32 v94, v80, v81
	v_cvt_pk_bf16_f32 v95, v82, v83
	v_cvt_pk_bf16_f32 v96, v84, v85
	v_cvt_pk_bf16_f32 v97, v86, v87
	v_cvt_pk_bf16_f32 v98, v88, v89
	v_cvt_pk_bf16_f32 v99, v90, v91
	global_store_dwordx2 v115, v[92:93], s[2:3] offset:0
	global_store_dwordx2 v115, v[94:95], s[2:3] offset:512
	global_store_dwordx2 v115, v[96:97], s[2:3] offset:1024
	global_store_dwordx2 v115, v[98:99], s[2:3] offset:1536
	s_add_u32 s2, s2, 0x800
	s_addc_u32 s3, s3, 0
	s_add_u32 s0, s0, 0x1000
	s_addc_u32 s1, s1, 0
	global_load_dwordx4 v[18:21], v114, s[0:1] offset:0
	global_load_dwordx4 v[22:25], v114, s[0:1] offset:1024
	global_load_dwordx4 v[26:29], v114, s[0:1] offset:2048
	global_load_dwordx4 v[30:33], v114, s[0:1] offset:3072
	s_waitcnt vmcnt(8)
; __device__ __forceinline__ void phase_ln(float* R, const float* __restrict__ g, const float* __restrict__ b, bf16_t* xbf, float samp_scale, const float* __restrict__ part, int nsplit, bool f32_all) {
;     ...
;   for (int r = gw; r < MT; r += nw) {
;     float* row = R + (size_t)r * 1024;
;     f32x4 v[4];
; #pragma unroll
;     for (int i = 0; i < 4; ++i) v[i] = *(const f32x4*)(row + i * 256 + lane * 4);
;     if (r >= MP) {
;       for (int sp = 0; sp < nsplit; ++sp) {
;         const float* prow = part + ((size_t)sp * MS + (r - MP)) * 1024;
; #pragma unroll
;         for (int i = 0; i < 4; ++i) v[i] = v[i] + *(const f32x4*)(prow + i * 256 + lane * 4);
;       }
;     }
;     float s = 0.f;
; #pragma unroll
;     for (int i = 0; i < 4; ++i) s += v[i][0] + v[i][1] + v[i][2] + v[i][3];
; #pragma unroll
;     for (int o = 32; o >= 1; o >>= 1) s += __shfl_xor(s, o);
;     const float mean = s * (1.f / 1024.f);
;     float ss = 0.f;
; #pragma unroll
;     for (int i = 0; i < 4; ++i) { v[i] = v[i] - mean; ss += v[i][0] * v[i][0] + v[i][1] * v[i][1] + v[i][2] * v[i][2] + v[i][3] * v[i][3]; }
; #pragma unroll
;     for (int o = 32; o >= 1; o >>= 1) ss += __shfl_xor(ss, o);
;     const float rstd = rsqrtf(ss * (1.f / 1024.f) + LN_EPS);
; #pragma unroll
;     for (int i = 0; i < 4; ++i) {
;       const f32x4 y = v[i] * rstd * gv[i] + bv[i];
;       if (r >= MP) *(f32x4*)(row + i * 256 + lane * 4) = y * samp_scale;
;       else if (f32_all) *(f32x4*)(row + i * 256 + lane * 4) = y;
;       if (xbf) {
;         u32x2 wv;
;         wv[0] = cvt_pk_bf16(y[0], y[1]); wv[1] = cvt_pk_bf16(y[2], y[3]);
;         *(u32x2*)(xbf + (size_t)r * 1024 + i * 256 + lane * 4) = wv;
;       }
;     }
	v_pk_add_f32 v[66:67], v[0:1], v[2:3]
	v_pk_add_f32 v[68:69], v[4:5], v[6:7]
	v_pk_add_f32 v[70:71], v[8:9], v[10:11]
	v_pk_add_f32 v[72:73], v[12:13], v[14:15]
	v_pk_add_f32 v[66:67], v[66:67], v[68:69]
	v_pk_add_f32 v[70:71], v[70:71], v[72:73]
	v_pk_add_f32 v[66:67], v[66:67], v[70:71]
	v_add_f32_e32 v66, v66, v67
	s_nop 1
	v_add_f32_dpp v66, v66, v66 row_shr:1 row_mask:0xf bank_mask:0xf bound_ctrl:1
	s_nop 1
	v_add_f32_dpp v66, v66, v66 row_shr:2 row_mask:0xf bank_mask:0xf bound_ctrl:1
	s_nop 1
	v_add_f32_dpp v66, v66, v66 row_shr:4 row_mask:0xf bank_mask:0xf bound_ctrl:1
	s_nop 1
	v_add_f32_dpp v66, v66, v66 row_shr:8 row_mask:0xf bank_mask:0xf bound_ctrl:1
	s_nop 0
	v_readlane_b32 s9, v66, 15
	v_readlane_b32 s10, v66, 31
	v_readlane_b32 s11, v66, 47
	v_readlane_b32 vcc_lo, v66, 63
	s_nop 1
	v_mov_b32_e32 v66, s9
	v_add_f32_e32 v66, s10, v66
	v_add_f32_e32 v66, s11, v66
	v_add_f32_e32 v66, vcc_lo, v66
	v_mul_f32_e32 v116, 0x3a800000, v66
	v_mov_b32_e32 v117, v116
	v_pk_add_f32 v[0:1], v[0:1], v[116:117] neg_lo:[0,1] neg_hi:[0,1]
	v_pk_add_f32 v[2:3], v[2:3], v[116:117] neg_lo:[0,1] neg_hi:[0,1]
	v_pk_add_f32 v[4:5], v[4:5], v[116:117] neg_lo:[0,1] neg_hi:[0,1]
	v_pk_add_f32 v[6:7], v[6:7], v[116:117] neg_lo:[0,1] neg_hi:[0,1]
	v_pk_add_f32 v[8:9], v[8:9], v[116:117] neg_lo:[0,1] neg_hi:[0,1]
	v_pk_add_f32 v[10:11], v[10:11], v[116:117] neg_lo:[0,1] neg_hi:[0,1]
	v_pk_add_f32 v[12:13], v[12:13], v[116:117] neg_lo:[0,1] neg_hi:[0,1]
	v_pk_add_f32 v[14:15], v[14:15], v[116:117] neg_lo:[0,1] neg_hi:[0,1]
	v_pk_mul_f32 v[66:67], v[0:1], v[0:1]
	v_pk_mul_f32 v[68:69], v[2:3], v[2:3]
	v_pk_fma_f32 v[66:67], v[4:5], v[4:5], v[66:67]
	v_pk_fma_f32 v[68:69], v[6:7], v[6:7], v[68:69]
	v_pk_fma_f32 v[66:67], v[8:9], v[8:9], v[66:67]
	v_pk_fma_f32 v[68:69], v[10:11], v[10:11], v[68:69]
	v_pk_fma_f32 v[66:67], v[12:13], v[12:13], v[66:67]
	v_pk_fma_f32 v[68:69], v[14:15], v[14:15], v[68:69]
	v_pk_add_f32 v[66:67], v[66:67], v[68:69]
	v_add_f32_e32 v66, v66, v67
	s_nop 1
	v_add_f32_dpp v66, v66, v66 row_shr:1 row_mask:0xf bank_mask:0xf bound_ctrl:1
	s_nop 1
	v_add_f32_dpp v66, v66, v66 row_shr:2 row_mask:0xf bank_mask:0xf bound_ctrl:1
	s_nop 1
	v_add_f32_dpp v66, v66, v66 row_shr:4 row_mask:0xf bank_mask:0xf bound_ctrl:1
	s_nop 1
	v_add_f32_dpp v66, v66, v66 row_shr:8 row_mask:0xf bank_mask:0xf bound_ctrl:1
	s_nop 0
	v_readlane_b32 s9, v66, 15
	v_readlane_b32 s10, v66, 31
	v_readlane_b32 s11, v66, 47
	v_readlane_b32 vcc_lo, v66, 63
	s_nop 1
	v_mov_b32_e32 v66, s9
	v_add_f32_e32 v66, s10, v66
	v_add_f32_e32 v66, s11, v66
	v_add_f32_e32 v66, vcc_lo, v66
	v_mul_f32_e32 v66, 0x3a800000, v66
	v_add_f32_e32 v66, 0x3727c5ac, v66
	v_rsq_f32_e32 v118, v66
	s_nop 0
	v_mov_b32_e32 v119, v118
	v_pk_mul_f32 v[0:1], v[0:1], v[118:119]
	v_pk_mul_f32 v[2:3], v[2:3], v[118:119]
	v_pk_mul_f32 v[4:5], v[4:5], v[118:119]
	v_pk_mul_f32 v[6:7], v[6:7], v[118:119]
	v_pk_mul_f32 v[8:9], v[8:9], v[118:119]
	v_pk_mul_f32 v[10:11], v[10:11], v[118:119]
	v_pk_mul_f32 v[12:13], v[12:13], v[118:119]
	v_pk_mul_f32 v[14:15], v[14:15], v[118:119]
	v_pk_fma_f32 v[76:77], v[0:1], v[34:35], v[50:51]
	v_pk_fma_f32 v[78:79], v[2:3], v[36:37], v[52:53]
	v_pk_fma_f32 v[80:81], v[4:5], v[38:39], v[54:55]
	v_pk_fma_f32 v[82:83], v[6:7], v[40:41], v[56:57]
	v_pk_fma_f32 v[84:85], v[8:9], v[42:43], v[58:59]
	v_pk_fma_f32 v[86:87], v[10:11], v[44:45], v[60:61]
	v_pk_fma_f32 v[88:89], v[12:13], v[46:47], v[62:63]
	v_pk_fma_f32 v[90:91], v[14:15], v[48:49], v[64:65]
	v_cvt_pk_bf16_f32 v92, v76, v77
	v_cvt_pk_bf16_f32 v93, v78, v79
	v_cvt_pk_bf16_f32 v94, v80, v81
	v_cvt_pk_bf16_f32 v95, v82, v83
	v_cvt_pk_bf16_f32 v96, v84, v85
	v_cvt_pk_bf16_f32 v97, v86, v87
	v_cvt_pk_bf16_f32 v98, v88, v89
	v_cvt_pk_bf16_f32 v99, v90, v91
	global_store_dwordx2 v115, v[92:93], s[2:3] offset:0
	global_store_dwordx2 v115, v[94:95], s[2:3] offset:512
	global_store_dwordx2 v115, v[96:97], s[2:3] offset:1024
	global_store_dwordx2 v115, v[98:99], s[2:3] offset:1536
	s_add_u32 s2, s2, 0x800
	s_addc_u32 s3, s3, 0
	s_add_u32 s0, s0, 0x1000
	s_addc_u32 s1, s1, 0
	global_load_dwordx4 v[0:3], v114, s[0:1] offset:0
	global_load_dwordx4 v[4:7], v114, s[0:1] offset:1024
	global_load_dwordx4 v[8:11], v114, s[0:1] offset:2048
	global_load_dwordx4 v[12:15], v114, s[0:1] offset:3072
	s_waitcnt vmcnt(8)
; __device__ __forceinline__ void phase_ln(float* R, const float* __restrict__ g, const float* __restrict__ b, bf16_t* xbf, float samp_scale, const float* __restrict__ part, int nsplit, bool f32_all) {
;     ...
;   for (int r = gw; r < MT; r += nw) {
;     float* row = R + (size_t)r * 1024;
;     f32x4 v[4];
; #pragma unroll
;     for (int i = 0; i < 4; ++i) v[i] = *(const f32x4*)(row + i * 256 + lane * 4);
;     if (r >= MP) {
;       for (int sp = 0; sp < nsplit; ++sp) {
;         const float* prow = part + ((size_t)sp * MS + (r - MP)) * 1024;
; #pragma unroll
;         for (int i = 0; i < 4; ++i) v[i] = v[i] + *(const f32x4*)(prow + i * 256 + lane * 4);
;       }
;     }
;     float s = 0.f;
; #pragma unroll
;     for (int i = 0; i < 4; ++i) s += v[i][0] + v[i][1] + v[i][2] + v[i][3];
; #pragma unroll
;     for (int o = 32; o >= 1; o >>= 1) s += __shfl_xor(s, o);
;     const float mean = s * (1.f / 1024.f);
;     float ss = 0.f;
; #pragma unroll
;     for (int i = 0; i < 4; ++i) { v[i] = v[i] - mean; ss += v[i][0] * v[i][0] + v[i][1] * v[i][1] + v[i][2] * v[i][2] + v[i][3] * v[i][3]; }
; #pragma unroll
;     for (int o = 32; o >= 1; o >>= 1) ss += __shfl_xor(ss, o);
;     const float rstd = rsqrtf(ss * (1.f / 1024.f) + LN_EPS);
; #pragma unroll
;     for (int i = 0; i < 4; ++i) {
;       const f32x4 y = v[i] * rstd * gv[i] + bv[i];
;       if (r >= MP) *(f32x4*)(row + i * 256 + lane * 4) = y * samp_scale;
;       else if (f32_all) *(f32x4*)(row + i * 256 + lane * 4) = y;
;       if (xbf) {
;         u32x2 wv;
;         wv[0] = cvt_pk_bf16(y[0], y[1]); wv[1] = cvt_pk_bf16(y[2], y[3]);
;         *(u32x2*)(xbf + (size_t)r * 1024 + i * 256 + lane * 4) = wv;
;       }
;     }
	v_pk_add_f32 v[66:67], v[18:19], v[20:21]
	v_pk_add_f32 v[68:69], v[22:23], v[24:25]
	v_pk_add_f32 v[70:71], v[26:27], v[28:29]
	v_pk_add_f32 v[72:73], v[30:31], v[32:33]
	v_pk_add_f32 v[66:67], v[66:67], v[68:69]
	v_pk_add_f32 v[70:71], v[70:71], v[72:73]
	v_pk_add_f32 v[66:67], v[66:67], v[70:71]
	v_add_f32_e32 v66, v66, v67
	s_nop 1
	v_add_f32_dpp v66, v66, v66 row_shr:1 row_mask:0xf bank_mask:0xf bound_ctrl:1
	s_nop 1
	v_add_f32_dpp v66, v66, v66 row_shr:2 row_mask:0xf bank_mask:0xf bound_ctrl:1
	s_nop 1
	v_add_f32_dpp v66, v66, v66 row_shr:4 row_mask:0xf bank_mask:0xf bound_ctrl:1
	s_nop 1
	v_add_f32_dpp v66, v66, v66 row_shr:8 row_mask:0xf bank_mask:0xf bound_ctrl:1
	s_nop 0
	v_readlane_b32 s9, v66, 15
	v_readlane_b32 s10, v66, 31
	v_readlane_b32 s11, v66, 47
	v_readlane_b32 vcc_lo, v66, 63
	s_nop 1
	v_mov_b32_e32 v66, s9
	v_add_f32_e32 v66, s10, v66
	v_add_f32_e32 v66, s11, v66
	v_add_f32_e32 v66, vcc_lo, v66
	v_mul_f32_e32 v116, 0x3a800000, v66
	v_mov_b32_e32 v117, v116
	v_pk_add_f32 v[18:19], v[18:19], v[116:117] neg_lo:[0,1] neg_hi:[0,1]
	v_pk_add_f32 v[20:21], v[20:21], v[116:117] neg_lo:[0,1] neg_hi:[0,1]
	v_pk_add_f32 v[22:23], v[22:23], v[116:117] neg_lo:[0,1] neg_hi:[0,1]
	v_pk_add_f32 v[24:25], v[24:25], v[116:117] neg_lo:[0,1] neg_hi:[0,1]
	v_pk_add_f32 v[26:27], v[26:27], v[116:117] neg_lo:[0,1] neg_hi:[0,1]
	v_pk_add_f32 v[28:29], v[28:29], v[116:117] neg_lo:[0,1] neg_hi:[0,1]
	v_pk_add_f32 v[30:31], v[30:31], v[116:117] neg_lo:[0,1] neg_hi:[0,1]
	v_pk_add_f32 v[32:33], v[32:33], v[116:117] neg_lo:[0,1] neg_hi:[0,1]
	v_pk_mul_f32 v[66:67], v[18:19], v[18:19]
	v_pk_mul_f32 v[68:69], v[20:21], v[20:21]
	v_pk_fma_f32 v[66:67], v[22:23], v[22:23], v[66:67]
	v_pk_fma_f32 v[68:69], v[24:25], v[24:25], v[68:69]
	v_pk_fma_f32 v[66:67], v[26:27], v[26:27], v[66:67]
	v_pk_fma_f32 v[68:69], v[28:29], v[28:29], v[68:69]
	v_pk_fma_f32 v[66:67], v[30:31], v[30:31], v[66:67]
	v_pk_fma_f32 v[68:69], v[32:33], v[32:33], v[68:69]
	v_pk_add_f32 v[66:67], v[66:67], v[68:69]
	v_add_f32_e32 v66, v66, v67
	s_nop 1
	v_add_f32_dpp v66, v66, v66 row_shr:1 row_mask:0xf bank_mask:0xf bound_ctrl:1
	s_nop 1
	v_add_f32_dpp v66, v66, v66 row_shr:2 row_mask:0xf bank_mask:0xf bound_ctrl:1
	s_nop 1
	v_add_f32_dpp v66, v66, v66 row_shr:4 row_mask:0xf bank_mask:0xf bound_ctrl:1
	s_nop 1
	v_add_f32_dpp v66, v66, v66 row_shr:8 row_mask:0xf bank_mask:0xf bound_ctrl:1
	s_nop 0
	v_readlane_b32 s9, v66, 15
	v_readlane_b32 s10, v66, 31
	v_readlane_b32 s11, v66, 47
	v_readlane_b32 vcc_lo, v66, 63
	s_nop 1
	v_mov_b32_e32 v66, s9
	v_add_f32_e32 v66, s10, v66
	v_add_f32_e32 v66, s11, v66
	v_add_f32_e32 v66, vcc_lo, v66
	v_mul_f32_e32 v66, 0x3a800000, v66
	v_add_f32_e32 v66, 0x3727c5ac, v66
	v_rsq_f32_e32 v118, v66
	s_nop 0
	v_mov_b32_e32 v119, v118
	v_pk_mul_f32 v[18:19], v[18:19], v[118:119]
	v_pk_mul_f32 v[20:21], v[20:21], v[118:119]
	v_pk_mul_f32 v[22:23], v[22:23], v[118:119]
	v_pk_mul_f32 v[24:25], v[24:25], v[118:119]
	v_pk_mul_f32 v[26:27], v[26:27], v[118:119]
	v_pk_mul_f32 v[28:29], v[28:29], v[118:119]
	v_pk_mul_f32 v[30:31], v[30:31], v[118:119]
	v_pk_mul_f32 v[32:33], v[32:33], v[118:119]
	v_pk_fma_f32 v[76:77], v[18:19], v[34:35], v[50:51]
	v_pk_fma_f32 v[78:79], v[20:21], v[36:37], v[52:53]
	v_pk_fma_f32 v[80:81], v[22:23], v[38:39], v[54:55]
	v_pk_fma_f32 v[82:83], v[24:25], v[40:41], v[56:57]
	v_pk_fma_f32 v[84:85], v[26:27], v[42:43], v[58:59]
	v_pk_fma_f32 v[86:87], v[28:29], v[44:45], v[60:61]
	v_pk_fma_f32 v[88:89], v[30:31], v[46:47], v[62:63]
	v_pk_fma_f32 v[90:91], v[32:33], v[48:49], v[64:65]
	v_cvt_pk_bf16_f32 v92, v76, v77
	v_cvt_pk_bf16_f32 v93, v78, v79
	v_cvt_pk_bf16_f32 v94, v80, v81
	v_cvt_pk_bf16_f32 v95, v82, v83
	v_cvt_pk_bf16_f32 v96, v84, v85
	v_cvt_pk_bf16_f32 v97, v86, v87
	v_cvt_pk_bf16_f32 v98, v88, v89
	v_cvt_pk_bf16_f32 v99, v90, v91
	global_store_dwordx2 v115, v[92:93], s[2:3] offset:0
	global_store_dwordx2 v115, v[94:95], s[2:3] offset:512
	global_store_dwordx2 v115, v[96:97], s[2:3] offset:1024
	global_store_dwordx2 v115, v[98:99], s[2:3] offset:1536
	s_add_u32 s2, s2, 0x800
	s_addc_u32 s3, s3, 0
	s_add_u32 s0, s0, 0x1000
	s_addc_u32 s1, s1, 0
	global_load_dwordx4 v[18:21], v114, s[0:1] offset:0
	global_load_dwordx4 v[22:25], v114, s[0:1] offset:1024
	global_load_dwordx4 v[26:29], v114, s[0:1] offset:2048
	global_load_dwordx4 v[30:33], v114, s[0:1] offset:3072
	s_waitcnt vmcnt(8)
; __device__ __forceinline__ void phase_ln(float* R, const float* __restrict__ g, const float* __restrict__ b, bf16_t* xbf, float samp_scale, const float* __restrict__ part, int nsplit, bool f32_all) {
;     ...
;   for (int r = gw; r < MT; r += nw) {
;     float* row = R + (size_t)r * 1024;
;     f32x4 v[4];
; #pragma unroll
;     for (int i = 0; i < 4; ++i) v[i] = *(const f32x4*)(row + i * 256 + lane * 4);
;     if (r >= MP) {
;       for (int sp = 0; sp < nsplit; ++sp) {
;         const float* prow = part + ((size_t)sp * MS + (r - MP)) * 1024;
; #pragma unroll
;         for (int i = 0; i < 4; ++i) v[i] = v[i] + *(const f32x4*)(prow + i * 256 + lane * 4);
;       }
;     }
;     float s = 0.f;
; #pragma unroll
;     for (int i = 0; i < 4; ++i) s += v[i][0] + v[i][1] + v[i][2] + v[i][3];
; #pragma unroll
;     for (int o = 32; o >= 1; o >>= 1) s += __shfl_xor(s, o);
;     const float mean = s * (1.f / 1024.f);
;     float ss = 0.f;
; #pragma unroll
;     for (int i = 0; i < 4; ++i) { v[i] = v[i] - mean; ss += v[i][0] * v[i][0] + v[i][1] * v[i][1] + v[i][2] * v[i][2] + v[i][3] * v[i][3]; }
; #pragma unroll
;     for (int o = 32; o >= 1; o >>= 1) ss += __shfl_xor(ss, o);
;     const float rstd = rsqrtf(ss * (1.f / 1024.f) + LN_EPS);
; #pragma unroll
;     for (int i = 0; i < 4; ++i) {
;       const f32x4 y = v[i] * rstd * gv[i] + bv[i];
;       if (r >= MP) *(f32x4*)(row + i * 256 + lane * 4) = y * samp_scale;
;       else if (f32_all) *(f32x4*)(row + i * 256 + lane * 4) = y;
;       if (xbf) {
;         u32x2 wv;
;         wv[0] = cvt_pk_bf16(y[0], y[1]); wv[1] = cvt_pk_bf16(y[2], y[3]);
;         *(u32x2*)(xbf + (size_t)r * 1024 + i * 256 + lane * 4) = wv;
;       }
;     }
	v_pk_add_f32 v[66:67], v[0:1], v[2:3]
	v_pk_add_f32 v[68:69], v[4:5], v[6:7]
	v_pk_add_f32 v[70:71], v[8:9], v[10:11]
	v_pk_add_f32 v[72:73], v[12:13], v[14:15]
	v_pk_add_f32 v[66:67], v[66:67], v[68:69]
	v_pk_add_f32 v[70:71], v[70:71], v[72:73]
	v_pk_add_f32 v[66:67], v[66:67], v[70:71]
	v_add_f32_e32 v66, v66, v67
	s_nop 1
	v_add_f32_dpp v66, v66, v66 row_shr:1 row_mask:0xf bank_mask:0xf bound_ctrl:1
	s_nop 1
	v_add_f32_dpp v66, v66, v66 row_shr:2 row_mask:0xf bank_mask:0xf bound_ctrl:1
	s_nop 1
	v_add_f32_dpp v66, v66, v66 row_shr:4 row_mask:0xf bank_mask:0xf bound_ctrl:1
	s_nop 1
	v_add_f32_dpp v66, v66, v66 row_shr:8 row_mask:0xf bank_mask:0xf bound_ctrl:1
	s_nop 0
	v_readlane_b32 s9, v66, 15
	v_readlane_b32 s10, v66, 31
	v_readlane_b32 s11, v66, 47
	v_readlane_b32 vcc_lo, v66, 63
	s_nop 1
	v_mov_b32_e32 v66, s9
	v_add_f32_e32 v66, s10, v66
	v_add_f32_e32 v66, s11, v66
	v_add_f32_e32 v66, vcc_lo, v66
	v_mul_f32_e32 v116, 0x3a800000, v66
	v_mov_b32_e32 v117, v116
	v_pk_add_f32 v[0:1], v[0:1], v[116:117] neg_lo:[0,1] neg_hi:[0,1]
	v_pk_add_f32 v[2:3], v[2:3], v[116:117] neg_lo:[0,1] neg_hi:[0,1]
	v_pk_add_f32 v[4:5], v[4:5], v[116:117] neg_lo:[0,1] neg_hi:[0,1]
	v_pk_add_f32 v[6:7], v[6:7], v[116:117] neg_lo:[0,1] neg_hi:[0,1]
	v_pk_add_f32 v[8:9], v[8:9], v[116:117] neg_lo:[0,1] neg_hi:[0,1]
	v_pk_add_f32 v[10:11], v[10:11], v[116:117] neg_lo:[0,1] neg_hi:[0,1]
	v_pk_add_f32 v[12:13], v[12:13], v[116:117] neg_lo:[0,1] neg_hi:[0,1]
	v_pk_add_f32 v[14:15], v[14:15], v[116:117] neg_lo:[0,1] neg_hi:[0,1]
	v_pk_mul_f32 v[66:67], v[0:1], v[0:1]
	v_pk_mul_f32 v[68:69], v[2:3], v[2:3]
	v_pk_fma_f32 v[66:67], v[4:5], v[4:5], v[66:67]
	v_pk_fma_f32 v[68:69], v[6:7], v[6:7], v[68:69]
	v_pk_fma_f32 v[66:67], v[8:9], v[8:9], v[66:67]
	v_pk_fma_f32 v[68:69], v[10:11], v[10:11], v[68:69]
	v_pk_fma_f32 v[66:67], v[12:13], v[12:13], v[66:67]
	v_pk_fma_f32 v[68:69], v[14:15], v[14:15], v[68:69]
	v_pk_add_f32 v[66:67], v[66:67], v[68:69]
	v_add_f32_e32 v66, v66, v67
	s_nop 1
	v_add_f32_dpp v66, v66, v66 row_shr:1 row_mask:0xf bank_mask:0xf bound_ctrl:1
	s_nop 1
	v_add_f32_dpp v66, v66, v66 row_shr:2 row_mask:0xf bank_mask:0xf bound_ctrl:1
	s_nop 1
	v_add_f32_dpp v66, v66, v66 row_shr:4 row_mask:0xf bank_mask:0xf bound_ctrl:1
	s_nop 1
	v_add_f32_dpp v66, v66, v66 row_shr:8 row_mask:0xf bank_mask:0xf bound_ctrl:1
	s_nop 0
	v_readlane_b32 s9, v66, 15
	v_readlane_b32 s10, v66, 31
	v_readlane_b32 s11, v66, 47
	v_readlane_b32 vcc_lo, v66, 63
	s_nop 1
	v_mov_b32_e32 v66, s9
	v_add_f32_e32 v66, s10, v66
	v_add_f32_e32 v66, s11, v66
	v_add_f32_e32 v66, vcc_lo, v66
	v_mul_f32_e32 v66, 0x3a800000, v66
	v_add_f32_e32 v66, 0x3727c5ac, v66
	v_rsq_f32_e32 v118, v66
	s_nop 0
	v_mov_b32_e32 v119, v118
	v_pk_mul_f32 v[0:1], v[0:1], v[118:119]
	v_pk_mul_f32 v[2:3], v[2:3], v[118:119]
	v_pk_mul_f32 v[4:5], v[4:5], v[118:119]
	v_pk_mul_f32 v[6:7], v[6:7], v[118:119]
	v_pk_mul_f32 v[8:9], v[8:9], v[118:119]
	v_pk_mul_f32 v[10:11], v[10:11], v[118:119]
	v_pk_mul_f32 v[12:13], v[12:13], v[118:119]
	v_pk_mul_f32 v[14:15], v[14:15], v[118:119]
	v_pk_fma_f32 v[76:77], v[0:1], v[34:35], v[50:51]
	v_pk_fma_f32 v[78:79], v[2:3], v[36:37], v[52:53]
	v_pk_fma_f32 v[80:81], v[4:5], v[38:39], v[54:55]
	v_pk_fma_f32 v[82:83], v[6:7], v[40:41], v[56:57]
	v_pk_fma_f32 v[84:85], v[8:9], v[42:43], v[58:59]
	v_pk_fma_f32 v[86:87], v[10:11], v[44:45], v[60:61]
	v_pk_fma_f32 v[88:89], v[12:13], v[46:47], v[62:63]
	v_pk_fma_f32 v[90:91], v[14:15], v[48:49], v[64:65]
	v_cvt_pk_bf16_f32 v92, v76, v77
	v_cvt_pk_bf16_f32 v93, v78, v79
	v_cvt_pk_bf16_f32 v94, v80, v81
	v_cvt_pk_bf16_f32 v95, v82, v83
	v_cvt_pk_bf16_f32 v96, v84, v85
	v_cvt_pk_bf16_f32 v97, v86, v87
	v_cvt_pk_bf16_f32 v98, v88, v89
	v_cvt_pk_bf16_f32 v99, v90, v91
	global_store_dwordx2 v115, v[92:93], s[2:3] offset:0
	global_store_dwordx2 v115, v[94:95], s[2:3] offset:512
	global_store_dwordx2 v115, v[96:97], s[2:3] offset:1024
	global_store_dwordx2 v115, v[98:99], s[2:3] offset:1536
	s_add_u32 s2, s2, 0x800
	s_addc_u32 s3, s3, 0
	s_add_u32 s0, s0, 0x1000
	s_addc_u32 s1, s1, 0
	global_load_dwordx4 v[0:3], v114, s[0:1] offset:0
	global_load_dwordx4 v[4:7], v114, s[0:1] offset:1024
	global_load_dwordx4 v[8:11], v114, s[0:1] offset:2048
	global_load_dwordx4 v[12:15], v114, s[0:1] offset:3072
	s_waitcnt vmcnt(8)
; __device__ __forceinline__ void phase_ln(float* R, const float* __restrict__ g, const float* __restrict__ b, bf16_t* xbf, float samp_scale, const float* __restrict__ part, int nsplit, bool f32_all) {
;     ...
;   for (int r = gw; r < MT; r += nw) {
;     float* row = R + (size_t)r * 1024;
;     f32x4 v[4];
; #pragma unroll
;     for (int i = 0; i < 4; ++i) v[i] = *(const f32x4*)(row + i * 256 + lane * 4);
;     if (r >= MP) {
;       for (int sp = 0; sp < nsplit; ++sp) {
;         const float* prow = part + ((size_t)sp * MS + (r - MP)) * 1024;
; #pragma unroll
;         for (int i = 0; i < 4; ++i) v[i] = v[i] + *(const f32x4*)(prow + i * 256 + lane * 4);
;       }
;     }
;     float s = 0.f;
; #pragma unroll
;     for (int i = 0; i < 4; ++i) s += v[i][0] + v[i][1] + v[i][2] + v[i][3];
; #pragma unroll
;     for (int o = 32; o >= 1; o >>= 1) s += __shfl_xor(s, o);
;     const float mean = s * (1.f / 1024.f);
;     float ss = 0.f;
; #pragma unroll
;     for (int i = 0; i < 4; ++i) { v[i] = v[i] - mean; ss += v[i][0] * v[i][0] + v[i][1] * v[i][1] + v[i][2] * v[i][2] + v[i][3] * v[i][3]; }
; #pragma unroll
;     for (int o = 32; o >= 1; o >>= 1) ss += __shfl_xor(ss, o);
;     const float rstd = rsqrtf(ss * (1.f / 1024.f) + LN_EPS);
; #pragma unroll
;     for (int i = 0; i < 4; ++i) {
;       const f32x4 y = v[i] * rstd * gv[i] + bv[i];
;       if (r >= MP) *(f32x4*)(row + i * 256 + lane * 4) = y * samp_scale;
;       else if (f32_all) *(f32x4*)(row + i * 256 + lane * 4) = y;
;       if (xbf) {
;         u32x2 wv;
;         wv[0] = cvt_pk_bf16(y[0], y[1]); wv[1] = cvt_pk_bf16(y[2], y[3]);
;         *(u32x2*)(xbf + (size_t)r * 1024 + i * 256 + lane * 4) = wv;
;       }
;     }
	v_pk_add_f32 v[66:67], v[18:19], v[20:21]
	v_pk_add_f32 v[68:69], v[22:23], v[24:25]
	v_pk_add_f32 v[70:71], v[26:27], v[28:29]
	v_pk_add_f32 v[72:73], v[30:31], v[32:33]
	v_pk_add_f32 v[66:67], v[66:67], v[68:69]
	v_pk_add_f32 v[70:71], v[70:71], v[72:73]
	v_pk_add_f32 v[66:67], v[66:67], v[70:71]
	v_add_f32_e32 v66, v66, v67
	s_nop 1
	v_add_f32_dpp v66, v66, v66 row_shr:1 row_mask:0xf bank_mask:0xf bound_ctrl:1
	s_nop 1
	v_add_f32_dpp v66, v66, v66 row_shr:2 row_mask:0xf bank_mask:0xf bound_ctrl:1
	s_nop 1
	v_add_f32_dpp v66, v66, v66 row_shr:4 row_mask:0xf bank_mask:0xf bound_ctrl:1
	s_nop 1
	v_add_f32_dpp v66, v66, v66 row_shr:8 row_mask:0xf bank_mask:0xf bound_ctrl:1
	s_nop 0
	v_readlane_b32 s9, v66, 15
	v_readlane_b32 s10, v66, 31
	v_readlane_b32 s11, v66, 47
	v_readlane_b32 vcc_lo, v66, 63
	s_nop 1
	v_mov_b32_e32 v66, s9
	v_add_f32_e32 v66, s10, v66
	v_add_f32_e32 v66, s11, v66
	v_add_f32_e32 v66, vcc_lo, v66
	v_mul_f32_e32 v116, 0x3a800000, v66
	v_mov_b32_e32 v117, v116
	v_pk_add_f32 v[18:19], v[18:19], v[116:117] neg_lo:[0,1] neg_hi:[0,1]
	v_pk_add_f32 v[20:21], v[20:21], v[116:117] neg_lo:[0,1] neg_hi:[0,1]
	v_pk_add_f32 v[22:23], v[22:23], v[116:117] neg_lo:[0,1] neg_hi:[0,1]
	v_pk_add_f32 v[24:25], v[24:25], v[116:117] neg_lo:[0,1] neg_hi:[0,1]
	v_pk_add_f32 v[26:27], v[26:27], v[116:117] neg_lo:[0,1] neg_hi:[0,1]
	v_pk_add_f32 v[28:29], v[28:29], v[116:117] neg_lo:[0,1] neg_hi:[0,1]
	v_pk_add_f32 v[30:31], v[30:31], v[116:117] neg_lo:[0,1] neg_hi:[0,1]
	v_pk_add_f32 v[32:33], v[32:33], v[116:117] neg_lo:[0,1] neg_hi:[0,1]
	v_pk_mul_f32 v[66:67], v[18:19], v[18:19]
	v_pk_mul_f32 v[68:69], v[20:21], v[20:21]
	v_pk_fma_f32 v[66:67], v[22:23], v[22:23], v[66:67]
	v_pk_fma_f32 v[68:69], v[24:25], v[24:25], v[68:69]
	v_pk_fma_f32 v[66:67], v[26:27], v[26:27], v[66:67]
	v_pk_fma_f32 v[68:69], v[28:29], v[28:29], v[68:69]
	v_pk_fma_f32 v[66:67], v[30:31], v[30:31], v[66:67]
	v_pk_fma_f32 v[68:69], v[32:33], v[32:33], v[68:69]
	v_pk_add_f32 v[66:67], v[66:67], v[68:69]
	v_add_f32_e32 v66, v66, v67
	s_nop 1
	v_add_f32_dpp v66, v66, v66 row_shr:1 row_mask:0xf bank_mask:0xf bound_ctrl:1
	s_nop 1
	v_add_f32_dpp v66, v66, v66 row_shr:2 row_mask:0xf bank_mask:0xf bound_ctrl:1
	s_nop 1
	v_add_f32_dpp v66, v66, v66 row_shr:4 row_mask:0xf bank_mask:0xf bound_ctrl:1
	s_nop 1
	v_add_f32_dpp v66, v66, v66 row_shr:8 row_mask:0xf bank_mask:0xf bound_ctrl:1
	s_nop 0
	v_readlane_b32 s9, v66, 15
	v_readlane_b32 s10, v66, 31
	v_readlane_b32 s11, v66, 47
	v_readlane_b32 vcc_lo, v66, 63
	s_nop 1
	v_mov_b32_e32 v66, s9
	v_add_f32_e32 v66, s10, v66
	v_add_f32_e32 v66, s11, v66
	v_add_f32_e32 v66, vcc_lo, v66
	v_mul_f32_e32 v66, 0x3a800000, v66
	v_add_f32_e32 v66, 0x3727c5ac, v66
	v_rsq_f32_e32 v118, v66
	s_nop 0
	v_mov_b32_e32 v119, v118
	v_pk_mul_f32 v[18:19], v[18:19], v[118:119]
	v_pk_mul_f32 v[20:21], v[20:21], v[118:119]
	v_pk_mul_f32 v[22:23], v[22:23], v[118:119]
	v_pk_mul_f32 v[24:25], v[24:25], v[118:119]
	v_pk_mul_f32 v[26:27], v[26:27], v[118:119]
	v_pk_mul_f32 v[28:29], v[28:29], v[118:119]
	v_pk_mul_f32 v[30:31], v[30:31], v[118:119]
	v_pk_mul_f32 v[32:33], v[32:33], v[118:119]
	v_pk_fma_f32 v[76:77], v[18:19], v[34:35], v[50:51]
	v_pk_fma_f32 v[78:79], v[20:21], v[36:37], v[52:53]
	v_pk_fma_f32 v[80:81], v[22:23], v[38:39], v[54:55]
	v_pk_fma_f32 v[82:83], v[24:25], v[40:41], v[56:57]
	v_pk_fma_f32 v[84:85], v[26:27], v[42:43], v[58:59]
	v_pk_fma_f32 v[86:87], v[28:29], v[44:45], v[60:61]
	v_pk_fma_f32 v[88:89], v[30:31], v[46:47], v[62:63]
	v_pk_fma_f32 v[90:91], v[32:33], v[48:49], v[64:65]
	v_cvt_pk_bf16_f32 v92, v76, v77
	v_cvt_pk_bf16_f32 v93, v78, v79
	v_cvt_pk_bf16_f32 v94, v80, v81
	v_cvt_pk_bf16_f32 v95, v82, v83
	v_cvt_pk_bf16_f32 v96, v84, v85
	v_cvt_pk_bf16_f32 v97, v86, v87
	v_cvt_pk_bf16_f32 v98, v88, v89
	v_cvt_pk_bf16_f32 v99, v90, v91
	global_store_dwordx2 v115, v[92:93], s[2:3] offset:0
	global_store_dwordx2 v115, v[94:95], s[2:3] offset:512
	global_store_dwordx2 v115, v[96:97], s[2:3] offset:1024
	global_store_dwordx2 v115, v[98:99], s[2:3] offset:1536
	s_add_u32 s2, s2, 0x800
	s_addc_u32 s3, s3, 0
	s_add_u32 s0, s0, 0x1000
	s_addc_u32 s1, s1, 0
	global_load_dwordx4 v[18:21], v114, s[0:1] offset:0
	global_load_dwordx4 v[22:25], v114, s[0:1] offset:1024
	global_load_dwordx4 v[26:29], v114, s[0:1] offset:2048
	global_load_dwordx4 v[30:33], v114, s[0:1] offset:3072
	s_waitcnt vmcnt(8)
; __device__ __forceinline__ void phase_ln(float* R, const float* __restrict__ g, const float* __restrict__ b, bf16_t* xbf, float samp_scale, const float* __restrict__ part, int nsplit, bool f32_all) {
;     ...
;   for (int r = gw; r < MT; r += nw) {
;     float* row = R + (size_t)r * 1024;
;     f32x4 v[4];
; #pragma unroll
;     for (int i = 0; i < 4; ++i) v[i] = *(const f32x4*)(row + i * 256 + lane * 4);
;     if (r >= MP) {
;       for (int sp = 0; sp < nsplit; ++sp) {
;         const float* prow = part + ((size_t)sp * MS + (r - MP)) * 1024;
; #pragma unroll
;         for (int i = 0; i < 4; ++i) v[i] = v[i] + *(const f32x4*)(prow + i * 256 + lane * 4);
;       }
;     }
;     float s = 0.f;
; #pragma unroll
;     for (int i = 0; i < 4; ++i) s += v[i][0] + v[i][1] + v[i][2] + v[i][3];
; #pragma unroll
;     for (int o = 32; o >= 1; o >>= 1) s += __shfl_xor(s, o);
;     const float mean = s * (1.f / 1024.f);
;     float ss = 0.f;
; #pragma unroll
;     for (int i = 0; i < 4; ++i) { v[i] = v[i] - mean; ss += v[i][0] * v[i][0] + v[i][1] * v[i][1] + v[i][2] * v[i][2] + v[i][3] * v[i][3]; }
; #pragma unroll
;     for (int o = 32; o >= 1; o >>= 1) ss += __shfl_xor(ss, o);
;     const float rstd = rsqrtf(ss * (1.f / 1024.f) + LN_EPS);
; #pragma unroll
;     for (int i = 0; i < 4; ++i) {
;       const f32x4 y = v[i] * rstd * gv[i] + bv[i];
;       if (r >= MP) *(f32x4*)(row + i * 256 + lane * 4) = y * samp_scale;
;       else if (f32_all) *(f32x4*)(row + i * 256 + lane * 4) = y;
;       if (xbf) {
;         u32x2 wv;
;         wv[0] = cvt_pk_bf16(y[0], y[1]); wv[1] = cvt_pk_bf16(y[2], y[3]);
;         *(u32x2*)(xbf + (size_t)r * 1024 + i * 256 + lane * 4) = wv;
;       }
;     }
	v_pk_add_f32 v[66:67], v[0:1], v[2:3]
	v_pk_add_f32 v[68:69], v[4:5], v[6:7]
	v_pk_add_f32 v[70:71], v[8:9], v[10:11]
	v_pk_add_f32 v[72:73], v[12:13], v[14:15]
	v_pk_add_f32 v[66:67], v[66:67], v[68:69]
	v_pk_add_f32 v[70:71], v[70:71], v[72:73]
	v_pk_add_f32 v[66:67], v[66:67], v[70:71]
	v_add_f32_e32 v66, v66, v67
	s_nop 1
	v_add_f32_dpp v66, v66, v66 row_shr:1 row_mask:0xf bank_mask:0xf bound_ctrl:1
	s_nop 1
	v_add_f32_dpp v66, v66, v66 row_shr:2 row_mask:0xf bank_mask:0xf bound_ctrl:1
	s_nop 1
	v_add_f32_dpp v66, v66, v66 row_shr:4 row_mask:0xf bank_mask:0xf bound_ctrl:1
	s_nop 1
	v_add_f32_dpp v66, v66, v66 row_shr:8 row_mask:0xf bank_mask:0xf bound_ctrl:1
	s_nop 0
	v_readlane_b32 s9, v66, 15
	v_readlane_b32 s10, v66, 31
	v_readlane_b32 s11, v66, 47
	v_readlane_b32 vcc_lo, v66, 63
	s_nop 1
	v_mov_b32_e32 v66, s9
	v_add_f32_e32 v66, s10, v66
	v_add_f32_e32 v66, s11, v66
	v_add_f32_e32 v66, vcc_lo, v66
	v_mul_f32_e32 v116, 0x3a800000, v66
	v_mov_b32_e32 v117, v116
	v_pk_add_f32 v[0:1], v[0:1], v[116:117] neg_lo:[0,1] neg_hi:[0,1]
	v_pk_add_f32 v[2:3], v[2:3], v[116:117] neg_lo:[0,1] neg_hi:[0,1]
	v_pk_add_f32 v[4:5], v[4:5], v[116:117] neg_lo:[0,1] neg_hi:[0,1]
	v_pk_add_f32 v[6:7], v[6:7], v[116:117] neg_lo:[0,1] neg_hi:[0,1]
	v_pk_add_f32 v[8:9], v[8:9], v[116:117] neg_lo:[0,1] neg_hi:[0,1]
	v_pk_add_f32 v[10:11], v[10:11], v[116:117] neg_lo:[0,1] neg_hi:[0,1]
	v_pk_add_f32 v[12:13], v[12:13], v[116:117] neg_lo:[0,1] neg_hi:[0,1]
	v_pk_add_f32 v[14:15], v[14:15], v[116:117] neg_lo:[0,1] neg_hi:[0,1]
	v_pk_mul_f32 v[66:67], v[0:1], v[0:1]
	v_pk_mul_f32 v[68:69], v[2:3], v[2:3]
	v_pk_fma_f32 v[66:67], v[4:5], v[4:5], v[66:67]
	v_pk_fma_f32 v[68:69], v[6:7], v[6:7], v[68:69]
	v_pk_fma_f32 v[66:67], v[8:9], v[8:9], v[66:67]
	v_pk_fma_f32 v[68:69], v[10:11], v[10:11], v[68:69]
	v_pk_fma_f32 v[66:67], v[12:13], v[12:13], v[66:67]
	v_pk_fma_f32 v[68:69], v[14:15], v[14:15], v[68:69]
	v_pk_add_f32 v[66:67], v[66:67], v[68:69]
	v_add_f32_e32 v66, v66, v67
	s_nop 1
	v_add_f32_dpp v66, v66, v66 row_shr:1 row_mask:0xf bank_mask:0xf bound_ctrl:1
	s_nop 1
	v_add_f32_dpp v66, v66, v66 row_shr:2 row_mask:0xf bank_mask:0xf bound_ctrl:1
	s_nop 1
	v_add_f32_dpp v66, v66, v66 row_shr:4 row_mask:0xf bank_mask:0xf bound_ctrl:1
	s_nop 1
	v_add_f32_dpp v66, v66, v66 row_shr:8 row_mask:0xf bank_mask:0xf bound_ctrl:1
	s_nop 0
	v_readlane_b32 s9, v66, 15
	v_readlane_b32 s10, v66, 31
	v_readlane_b32 s11, v66, 47
	v_readlane_b32 vcc_lo, v66, 63
	s_nop 1
	v_mov_b32_e32 v66, s9
	v_add_f32_e32 v66, s10, v66
	v_add_f32_e32 v66, s11, v66
	v_add_f32_e32 v66, vcc_lo, v66
	v_mul_f32_e32 v66, 0x3a800000, v66
	v_add_f32_e32 v66, 0x3727c5ac, v66
	v_rsq_f32_e32 v118, v66
	s_nop 0
	v_mov_b32_e32 v119, v118
	v_pk_mul_f32 v[0:1], v[0:1], v[118:119]
	v_pk_mul_f32 v[2:3], v[2:3], v[118:119]
	v_pk_mul_f32 v[4:5], v[4:5], v[118:119]
	v_pk_mul_f32 v[6:7], v[6:7], v[118:119]
	v_pk_mul_f32 v[8:9], v[8:9], v[118:119]
	v_pk_mul_f32 v[10:11], v[10:11], v[118:119]
	v_pk_mul_f32 v[12:13], v[12:13], v[118:119]
	v_pk_mul_f32 v[14:15], v[14:15], v[118:119]
	v_pk_fma_f32 v[76:77], v[0:1], v[34:35], v[50:51]
	v_pk_fma_f32 v[78:79], v[2:3], v[36:37], v[52:53]
	v_pk_fma_f32 v[80:81], v[4:5], v[38:39], v[54:55]
	v_pk_fma_f32 v[82:83], v[6:7], v[40:41], v[56:57]
	v_pk_fma_f32 v[84:85], v[8:9], v[42:43], v[58:59]
	v_pk_fma_f32 v[86:87], v[10:11], v[44:45], v[60:61]
	v_pk_fma_f32 v[88:89], v[12:13], v[46:47], v[62:63]
	v_pk_fma_f32 v[90:91], v[14:15], v[48:49], v[64:65]
	v_cvt_pk_bf16_f32 v92, v76, v77
	v_cvt_pk_bf16_f32 v93, v78, v79
	v_cvt_pk_bf16_f32 v94, v80, v81
	v_cvt_pk_bf16_f32 v95, v82, v83
	v_cvt_pk_bf16_f32 v96, v84, v85
	v_cvt_pk_bf16_f32 v97, v86, v87
	v_cvt_pk_bf16_f32 v98, v88, v89
	v_cvt_pk_bf16_f32 v99, v90, v91
	global_store_dwordx2 v115, v[92:93], s[2:3] offset:0
	global_store_dwordx2 v115, v[94:95], s[2:3] offset:512
	global_store_dwordx2 v115, v[96:97], s[2:3] offset:1024
	global_store_dwordx2 v115, v[98:99], s[2:3] offset:1536
	s_add_u32 s2, s2, 0x800
	s_addc_u32 s3, s3, 0
	s_add_u32 s0, s0, 0x1000
	s_addc_u32 s1, s1, 0
	global_load_dwordx4 v[0:3], v114, s[0:1] offset:0
	global_load_dwordx4 v[4:7], v114, s[0:1] offset:1024
	global_load_dwordx4 v[8:11], v114, s[0:1] offset:2048
	global_load_dwordx4 v[12:15], v114, s[0:1] offset:3072
	s_waitcnt vmcnt(8)
; __device__ __forceinline__ void phase_ln(float* R, const float* __restrict__ g, const float* __restrict__ b, bf16_t* xbf, float samp_scale, const float* __restrict__ part, int nsplit, bool f32_all) {
;     ...
;     float s = 0.f;
; #pragma unroll
;     for (int i = 0; i < 4; ++i) s += v[i][0] + v[i][1] + v[i][2] + v[i][3];
; #pragma unroll
;     for (int o = 32; o >= 1; o >>= 1) s += __shfl_xor(s, o);
;     const float mean = s * (1.f / 1024.f);
;     float ss = 0.f;
; #pragma unroll
;     for (int i = 0; i < 4; ++i) { v[i] = v[i] - mean; ss += v[i][0] * v[i][0] + v[i][1] * v[i][1] + v[i][2] * v[i][2] + v[i][3] * v[i][3]; }
; #pragma unroll
;     for (int o = 32; o >= 1; o >>= 1) ss += __shfl_xor(ss, o);
;     const float rstd = rsqrtf(ss * (1.f / 1024.f) + LN_EPS);
; #pragma unroll
;     for (int i = 0; i < 4; ++i) {
;       const f32x4 y = v[i] * rstd * gv[i] + bv[i];
;       if (r >= MP) *(f32x4*)(row + i * 256 + lane * 4) = y * samp_scale;
;       else if (f32_all) *(f32x4*)(row + i * 256 + lane * 4) = y;
;       if (xbf) {
;         u32x2 wv;
;         wv[0] = cvt_pk_bf16(y[0], y[1]); wv[1] = cvt_pk_bf16(y[2], y[3]);
;         *(u32x2*)(xbf + (size_t)r * 1024 + i * 256 + lane * 4) = wv;
;       }
;     }
	v_pk_add_f32 v[66:67], v[18:19], v[20:21]
	v_pk_add_f32 v[68:69], v[22:23], v[24:25]
	v_pk_add_f32 v[70:71], v[26:27], v[28:29]
	v_pk_add_f32 v[72:73], v[30:31], v[32:33]
	v_pk_add_f32 v[66:67], v[66:67], v[68:69]
	v_pk_add_f32 v[70:71], v[70:71], v[72:73]
	v_pk_add_f32 v[66:67], v[66:67], v[70:71]
	v_add_f32_e32 v66, v66, v67
	s_nop 1
	v_add_f32_dpp v66, v66, v66 row_shr:1 row_mask:0xf bank_mask:0xf bound_ctrl:1
	s_nop 1
	v_add_f32_dpp v66, v66, v66 row_shr:2 row_mask:0xf bank_mask:0xf bound_ctrl:1
	s_nop 1
	v_add_f32_dpp v66, v66, v66 row_shr:4 row_mask:0xf bank_mask:0xf bound_ctrl:1
	s_nop 1
	v_add_f32_dpp v66, v66, v66 row_shr:8 row_mask:0xf bank_mask:0xf bound_ctrl:1
	s_nop 0
	v_readlane_b32 s9, v66, 15
	v_readlane_b32 s10, v66, 31
	v_readlane_b32 s11, v66, 47
	v_readlane_b32 vcc_lo, v66, 63
	s_nop 1
	v_mov_b32_e32 v66, s9
	v_add_f32_e32 v66, s10, v66
	v_add_f32_e32 v66, s11, v66
	v_add_f32_e32 v66, vcc_lo, v66
	v_mul_f32_e32 v116, 0x3a800000, v66
	v_mov_b32_e32 v117, v116
	v_pk_add_f32 v[18:19], v[18:19], v[116:117] neg_lo:[0,1] neg_hi:[0,1]
	v_pk_add_f32 v[20:21], v[20:21], v[116:117] neg_lo:[0,1] neg_hi:[0,1]
	v_pk_add_f32 v[22:23], v[22:23], v[116:117] neg_lo:[0,1] neg_hi:[0,1]
	v_pk_add_f32 v[24:25], v[24:25], v[116:117] neg_lo:[0,1] neg_hi:[0,1]
	v_pk_add_f32 v[26:27], v[26:27], v[116:117] neg_lo:[0,1] neg_hi:[0,1]
	v_pk_add_f32 v[28:29], v[28:29], v[116:117] neg_lo:[0,1] neg_hi:[0,1]
	v_pk_add_f32 v[30:31], v[30:31], v[116:117] neg_lo:[0,1] neg_hi:[0,1]
	v_pk_add_f32 v[32:33], v[32:33], v[116:117] neg_lo:[0,1] neg_hi:[0,1]
	v_pk_mul_f32 v[66:67], v[18:19], v[18:19]
	v_pk_mul_f32 v[68:69], v[20:21], v[20:21]
	v_pk_fma_f32 v[66:67], v[22:23], v[22:23], v[66:67]
	v_pk_fma_f32 v[68:69], v[24:25], v[24:25], v[68:69]
	v_pk_fma_f32 v[66:67], v[26:27], v[26:27], v[66:67]
	v_pk_fma_f32 v[68:69], v[28:29], v[28:29], v[68:69]
	v_pk_fma_f32 v[66:67], v[30:31], v[30:31], v[66:67]
	v_pk_fma_f32 v[68:69], v[32:33], v[32:33], v[68:69]
	v_pk_add_f32 v[66:67], v[66:67], v[68:69]
	v_add_f32_e32 v66, v66, v67
	s_nop 1
	v_add_f32_dpp v66, v66, v66 row_shr:1 row_mask:0xf bank_mask:0xf bound_ctrl:1
	s_nop 1
	v_add_f32_dpp v66, v66, v66 row_shr:2 row_mask:0xf bank_mask:0xf bound_ctrl:1
	s_nop 1
	v_add_f32_dpp v66, v66, v66 row_shr:4 row_mask:0xf bank_mask:0xf bound_ctrl:1
	s_nop 1
	v_add_f32_dpp v66, v66, v66 row_shr:8 row_mask:0xf bank_mask:0xf bound_ctrl:1
	s_nop 0
	v_readlane_b32 s9, v66, 15
	v_readlane_b32 s10, v66, 31
	v_readlane_b32 s11, v66, 47
	v_readlane_b32 vcc_lo, v66, 63
	s_nop 1
	v_mov_b32_e32 v66, s9
	v_add_f32_e32 v66, s10, v66
	v_add_f32_e32 v66, s11, v66
	v_add_f32_e32 v66, vcc_lo, v66
	v_mul_f32_e32 v66, 0x3a800000, v66
	v_add_f32_e32 v66, 0x3727c5ac, v66
	v_rsq_f32_e32 v118, v66
	s_nop 0
	v_mov_b32_e32 v119, v118
	v_pk_mul_f32 v[18:19], v[18:19], v[118:119]
	v_pk_mul_f32 v[20:21], v[20:21], v[118:119]
	v_pk_mul_f32 v[22:23], v[22:23], v[118:119]
	v_pk_mul_f32 v[24:25], v[24:25], v[118:119]
	v_pk_mul_f32 v[26:27], v[26:27], v[118:119]
	v_pk_mul_f32 v[28:29], v[28:29], v[118:119]
	v_pk_mul_f32 v[30:31], v[30:31], v[118:119]
	v_pk_mul_f32 v[32:33], v[32:33], v[118:119]
	v_pk_fma_f32 v[76:77], v[18:19], v[34:35], v[50:51]
	v_pk_fma_f32 v[78:79], v[20:21], v[36:37], v[52:53]
	v_pk_fma_f32 v[80:81], v[22:23], v[38:39], v[54:55]
	v_pk_fma_f32 v[82:83], v[24:25], v[40:41], v[56:57]
	v_pk_fma_f32 v[84:85], v[26:27], v[42:43], v[58:59]
	v_pk_fma_f32 v[86:87], v[28:29], v[44:45], v[60:61]
	v_pk_fma_f32 v[88:89], v[30:31], v[46:47], v[62:63]
	v_pk_fma_f32 v[90:91], v[32:33], v[48:49], v[64:65]
	v_cvt_pk_bf16_f32 v92, v76, v77
	v_cvt_pk_bf16_f32 v93, v78, v79
	v_cvt_pk_bf16_f32 v94, v80, v81
	v_cvt_pk_bf16_f32 v95, v82, v83
	v_cvt_pk_bf16_f32 v96, v84, v85
	v_cvt_pk_bf16_f32 v97, v86, v87
	v_cvt_pk_bf16_f32 v98, v88, v89
	v_cvt_pk_bf16_f32 v99, v90, v91
	global_store_dwordx2 v115, v[92:93], s[2:3] offset:0
	global_store_dwordx2 v115, v[94:95], s[2:3] offset:512
	global_store_dwordx2 v115, v[96:97], s[2:3] offset:1024
	global_store_dwordx2 v115, v[98:99], s[2:3] offset:1536
	s_add_u32 s2, s2, 0x800
	s_addc_u32 s3, s3, 0
	s_add_u32 s0, s0, 0x1000
	s_addc_u32 s1, s1, 0
	global_load_dwordx4 v[18:21], v114, s[0:1] offset:0
	global_load_dwordx4 v[22:25], v114, s[0:1] offset:1024
	global_load_dwordx4 v[26:29], v114, s[0:1] offset:2048
	global_load_dwordx4 v[30:33], v114, s[0:1] offset:3072
	s_waitcnt vmcnt(8)
; __device__ __forceinline__ void phase_ln(float* R, const float* __restrict__ g, const float* __restrict__ b, bf16_t* xbf, float samp_scale, const float* __restrict__ part, int nsplit, bool f32_all) {
;     ...
;     float s = 0.f;
; #pragma unroll
;     for (int i = 0; i < 4; ++i) s += v[i][0] + v[i][1] + v[i][2] + v[i][3];
; #pragma unroll
;     for (int o = 32; o >= 1; o >>= 1) s += __shfl_xor(s, o);
;     const float mean = s * (1.f / 1024.f);
;     float ss = 0.f;
; #pragma unroll
;     for (int i = 0; i < 4; ++i) { v[i] = v[i] - mean; ss += v[i][0] * v[i][0] + v[i][1] * v[i][1] + v[i][2] * v[i][2] + v[i][3] * v[i][3]; }
; #pragma unroll
;     for (int o = 32; o >= 1; o >>= 1) ss += __shfl_xor(ss, o);
;     const float rstd = rsqrtf(ss * (1.f / 1024.f) + LN_EPS);
; #pragma unroll
;     for (int i = 0; i < 4; ++i) {
;       const f32x4 y = v[i] * rstd * gv[i] + bv[i];
;       if (r >= MP) *(f32x4*)(row + i * 256 + lane * 4) = y * samp_scale;
;       else if (f32_all) *(f32x4*)(row + i * 256 + lane * 4) = y;
;       if (xbf) {
;         u32x2 wv;
;         wv[0] = cvt_pk_bf16(y[0], y[1]); wv[1] = cvt_pk_bf16(y[2], y[3]);
;         *(u32x2*)(xbf + (size_t)r * 1024 + i * 256 + lane * 4) = wv;
;       }
;     }
	v_pk_add_f32 v[66:67], v[0:1], v[2:3]
	v_pk_add_f32 v[68:69], v[4:5], v[6:7]
	v_pk_add_f32 v[70:71], v[8:9], v[10:11]
	v_pk_add_f32 v[72:73], v[12:13], v[14:15]
	v_pk_add_f32 v[66:67], v[66:67], v[68:69]
	v_pk_add_f32 v[70:71], v[70:71], v[72:73]
	v_pk_add_f32 v[66:67], v[66:67], v[70:71]
	v_add_f32_e32 v66, v66, v67
	s_nop 1
	v_add_f32_dpp v66, v66, v66 row_shr:1 row_mask:0xf bank_mask:0xf bound_ctrl:1
	s_nop 1
	v_add_f32_dpp v66, v66, v66 row_shr:2 row_mask:0xf bank_mask:0xf bound_ctrl:1
	s_nop 1
	v_add_f32_dpp v66, v66, v66 row_shr:4 row_mask:0xf bank_mask:0xf bound_ctrl:1
	s_nop 1
	v_add_f32_dpp v66, v66, v66 row_shr:8 row_mask:0xf bank_mask:0xf bound_ctrl:1
	s_nop 0
	v_readlane_b32 s9, v66, 15
	v_readlane_b32 s10, v66, 31
	v_readlane_b32 s11, v66, 47
	v_readlane_b32 vcc_lo, v66, 63
	s_nop 1
	v_mov_b32_e32 v66, s9
	v_add_f32_e32 v66, s10, v66
	v_add_f32_e32 v66, s11, v66
	v_add_f32_e32 v66, vcc_lo, v66
	v_mul_f32_e32 v116, 0x3a800000, v66
	v_mov_b32_e32 v117, v116
	v_pk_add_f32 v[0:1], v[0:1], v[116:117] neg_lo:[0,1] neg_hi:[0,1]
	v_pk_add_f32 v[2:3], v[2:3], v[116:117] neg_lo:[0,1] neg_hi:[0,1]
	v_pk_add_f32 v[4:5], v[4:5], v[116:117] neg_lo:[0,1] neg_hi:[0,1]
	v_pk_add_f32 v[6:7], v[6:7], v[116:117] neg_lo:[0,1] neg_hi:[0,1]
	v_pk_add_f32 v[8:9], v[8:9], v[116:117] neg_lo:[0,1] neg_hi:[0,1]
	v_pk_add_f32 v[10:11], v[10:11], v[116:117] neg_lo:[0,1] neg_hi:[0,1]
	v_pk_add_f32 v[12:13], v[12:13], v[116:117] neg_lo:[0,1] neg_hi:[0,1]
	v_pk_add_f32 v[14:15], v[14:15], v[116:117] neg_lo:[0,1] neg_hi:[0,1]
	v_pk_mul_f32 v[66:67], v[0:1], v[0:1]
	v_pk_mul_f32 v[68:69], v[2:3], v[2:3]
	v_pk_fma_f32 v[66:67], v[4:5], v[4:5], v[66:67]
	v_pk_fma_f32 v[68:69], v[6:7], v[6:7], v[68:69]
	v_pk_fma_f32 v[66:67], v[8:9], v[8:9], v[66:67]
	v_pk_fma_f32 v[68:69], v[10:11], v[10:11], v[68:69]
	v_pk_fma_f32 v[66:67], v[12:13], v[12:13], v[66:67]
	v_pk_fma_f32 v[68:69], v[14:15], v[14:15], v[68:69]
	v_pk_add_f32 v[66:67], v[66:67], v[68:69]
	v_add_f32_e32 v66, v66, v67
	s_nop 1
	v_add_f32_dpp v66, v66, v66 row_shr:1 row_mask:0xf bank_mask:0xf bound_ctrl:1
	s_nop 1
	v_add_f32_dpp v66, v66, v66 row_shr:2 row_mask:0xf bank_mask:0xf bound_ctrl:1
	s_nop 1
	v_add_f32_dpp v66, v66, v66 row_shr:4 row_mask:0xf bank_mask:0xf bound_ctrl:1
	s_nop 1
	v_add_f32_dpp v66, v66, v66 row_shr:8 row_mask:0xf bank_mask:0xf bound_ctrl:1
	s_nop 0
	v_readlane_b32 s9, v66, 15
	v_readlane_b32 s10, v66, 31
	v_readlane_b32 s11, v66, 47
	v_readlane_b32 vcc_lo, v66, 63
	s_nop 1
	v_mov_b32_e32 v66, s9
	v_add_f32_e32 v66, s10, v66
	v_add_f32_e32 v66, s11, v66
	v_add_f32_e32 v66, vcc_lo, v66
	v_mul_f32_e32 v66, 0x3a800000, v66
	v_add_f32_e32 v66, 0x3727c5ac, v66
	v_rsq_f32_e32 v118, v66
	s_nop 0
	v_mov_b32_e32 v119, v118
	v_pk_mul_f32 v[0:1], v[0:1], v[118:119]
	v_pk_mul_f32 v[2:3], v[2:3], v[118:119]
	v_pk_mul_f32 v[4:5], v[4:5], v[118:119]
	v_pk_mul_f32 v[6:7], v[6:7], v[118:119]
	v_pk_mul_f32 v[8:9], v[8:9], v[118:119]
	v_pk_mul_f32 v[10:11], v[10:11], v[118:119]
	v_pk_mul_f32 v[12:13], v[12:13], v[118:119]
	v_pk_mul_f32 v[14:15], v[14:15], v[118:119]
	v_pk_fma_f32 v[76:77], v[0:1], v[34:35], v[50:51]
	v_pk_fma_f32 v[78:79], v[2:3], v[36:37], v[52:53]
	v_pk_fma_f32 v[80:81], v[4:5], v[38:39], v[54:55]
	v_pk_fma_f32 v[82:83], v[6:7], v[40:41], v[56:57]
	v_pk_fma_f32 v[84:85], v[8:9], v[42:43], v[58:59]
	v_pk_fma_f32 v[86:87], v[10:11], v[44:45], v[60:61]
	v_pk_fma_f32 v[88:89], v[12:13], v[46:47], v[62:63]
	v_pk_fma_f32 v[90:91], v[14:15], v[48:49], v[64:65]
	v_cvt_pk_bf16_f32 v92, v76, v77
	v_cvt_pk_bf16_f32 v93, v78, v79
	v_cvt_pk_bf16_f32 v94, v80, v81
	v_cvt_pk_bf16_f32 v95, v82, v83
	v_cvt_pk_bf16_f32 v96, v84, v85
	v_cvt_pk_bf16_f32 v97, v86, v87
	v_cvt_pk_bf16_f32 v98, v88, v89
	v_cvt_pk_bf16_f32 v99, v90, v91
	global_store_dwordx2 v115, v[92:93], s[2:3] offset:0
	global_store_dwordx2 v115, v[94:95], s[2:3] offset:512
	global_store_dwordx2 v115, v[96:97], s[2:3] offset:1024
	global_store_dwordx2 v115, v[98:99], s[2:3] offset:1536
	s_add_u32 s2, s2, 0x800
	s_addc_u32 s3, s3, 0
	s_waitcnt vmcnt(4)
	v_pk_add_f32 v[66:67], v[18:19], v[20:21]
	v_pk_add_f32 v[68:69], v[22:23], v[24:25]
	v_pk_add_f32 v[70:71], v[26:27], v[28:29]
	v_pk_add_f32 v[72:73], v[30:31], v[32:33]
	v_pk_add_f32 v[66:67], v[66:67], v[68:69]
	v_pk_add_f32 v[70:71], v[70:71], v[72:73]
	v_pk_add_f32 v[66:67], v[66:67], v[70:71]
	v_add_f32_e32 v66, v66, v67
	s_nop 1
	v_add_f32_dpp v66, v66, v66 row_shr:1 row_mask:0xf bank_mask:0xf bound_ctrl:1
	s_nop 1
	v_add_f32_dpp v66, v66, v66 row_shr:2 row_mask:0xf bank_mask:0xf bound_ctrl:1
	s_nop 1
	v_add_f32_dpp v66, v66, v66 row_shr:4 row_mask:0xf bank_mask:0xf bound_ctrl:1
	s_nop 1
	v_add_f32_dpp v66, v66, v66 row_shr:8 row_mask:0xf bank_mask:0xf bound_ctrl:1
	s_nop 0
	v_readlane_b32 s9, v66, 15
	v_readlane_b32 s10, v66, 31
	v_readlane_b32 s11, v66, 47
	v_readlane_b32 vcc_lo, v66, 63
	s_nop 1
	v_mov_b32_e32 v66, s9
	v_add_f32_e32 v66, s10, v66
	v_add_f32_e32 v66, s11, v66
	v_add_f32_e32 v66, vcc_lo, v66
	v_mul_f32_e32 v116, 0x3a800000, v66
	v_mov_b32_e32 v117, v116
	v_pk_add_f32 v[18:19], v[18:19], v[116:117] neg_lo:[0,1] neg_hi:[0,1]
	v_pk_add_f32 v[20:21], v[20:21], v[116:117] neg_lo:[0,1] neg_hi:[0,1]
	v_pk_add_f32 v[22:23], v[22:23], v[116:117] neg_lo:[0,1] neg_hi:[0,1]
	v_pk_add_f32 v[24:25], v[24:25], v[116:117] neg_lo:[0,1] neg_hi:[0,1]
	v_pk_add_f32 v[26:27], v[26:27], v[116:117] neg_lo:[0,1] neg_hi:[0,1]
	v_pk_add_f32 v[28:29], v[28:29], v[116:117] neg_lo:[0,1] neg_hi:[0,1]
	v_pk_add_f32 v[30:31], v[30:31], v[116:117] neg_lo:[0,1] neg_hi:[0,1]
	v_pk_add_f32 v[32:33], v[32:33], v[116:117] neg_lo:[0,1] neg_hi:[0,1]
	v_pk_mul_f32 v[66:67], v[18:19], v[18:19]
; __device__ __forceinline__ void phase_ln(float* R, const float* __restrict__ g, const float* __restrict__ b, bf16_t* xbf, float samp_scale, const float* __restrict__ part, int nsplit, bool f32_all) {
;     ...
;   for (int r = gw; r < MT; r += nw) {
;     float* row = R + (size_t)r * 1024;
;     f32x4 v[4];
; #pragma unroll
;     for (int i = 0; i < 4; ++i) v[i] = *(const f32x4*)(row + i * 256 + lane * 4);
;     if (r >= MP) {
;       for (int sp = 0; sp < nsplit; ++sp) {
;         const float* prow = part + ((size_t)sp * MS + (r - MP)) * 1024;
; #pragma unroll
;         for (int i = 0; i < 4; ++i) v[i] = v[i] + *(const f32x4*)(prow + i * 256 + lane * 4);
;       }
;     }
;     float s = 0.f;
; #pragma unroll
;     for (int i = 0; i < 4; ++i) s += v[i][0] + v[i][1] + v[i][2] + v[i][3];
; #pragma unroll
;     for (int o = 32; o >= 1; o >>= 1) s += __shfl_xor(s, o);
;     const float mean = s * (1.f / 1024.f);
;     float ss = 0.f;
; #pragma unroll
;     for (int i = 0; i < 4; ++i) { v[i] = v[i] - mean; ss += v[i][0] * v[i][0] + v[i][1] * v[i][1] + v[i][2] * v[i][2] + v[i][3] * v[i][3]; }
; #pragma unroll
;     for (int o = 32; o >= 1; o >>= 1) ss += __shfl_xor(ss, o);
;     const float rstd = rsqrtf(ss * (1.f / 1024.f) + LN_EPS);
; #pragma unroll
;     for (int i = 0; i < 4; ++i) {
;       const f32x4 y = v[i] * rstd * gv[i] + bv[i];
;       if (r >= MP) *(f32x4*)(row + i * 256 + lane * 4) = y * samp_scale;
;       else if (f32_all) *(f32x4*)(row + i * 256 + lane * 4) = y;
;       if (xbf) {
;         u32x2 wv;
;         wv[0] = cvt_pk_bf16(y[0], y[1]); wv[1] = cvt_pk_bf16(y[2], y[3]);
;         *(u32x2*)(xbf + (size_t)r * 1024 + i * 256 + lane * 4) = wv;
;       }
;     }
	v_pk_mul_f32 v[68:69], v[20:21], v[20:21]
	v_pk_fma_f32 v[66:67], v[22:23], v[22:23], v[66:67]
	v_pk_fma_f32 v[68:69], v[24:25], v[24:25], v[68:69]
	v_pk_fma_f32 v[66:67], v[26:27], v[26:27], v[66:67]
	v_pk_fma_f32 v[68:69], v[28:29], v[28:29], v[68:69]
	v_pk_fma_f32 v[66:67], v[30:31], v[30:31], v[66:67]
	v_pk_fma_f32 v[68:69], v[32:33], v[32:33], v[68:69]
	v_pk_add_f32 v[66:67], v[66:67], v[68:69]
	v_add_f32_e32 v66, v66, v67
	s_nop 1
	v_add_f32_dpp v66, v66, v66 row_shr:1 row_mask:0xf bank_mask:0xf bound_ctrl:1
	s_nop 1
	v_add_f32_dpp v66, v66, v66 row_shr:2 row_mask:0xf bank_mask:0xf bound_ctrl:1
	s_nop 1
	v_add_f32_dpp v66, v66, v66 row_shr:4 row_mask:0xf bank_mask:0xf bound_ctrl:1
	s_nop 1
	v_add_f32_dpp v66, v66, v66 row_shr:8 row_mask:0xf bank_mask:0xf bound_ctrl:1
	s_nop 0
	v_readlane_b32 s9, v66, 15
	v_readlane_b32 s10, v66, 31
	v_readlane_b32 s11, v66, 47
	v_readlane_b32 vcc_lo, v66, 63
	s_nop 1
	v_mov_b32_e32 v66, s9
	v_add_f32_e32 v66, s10, v66
	v_add_f32_e32 v66, s11, v66
	v_add_f32_e32 v66, vcc_lo, v66
	v_mul_f32_e32 v66, 0x3a800000, v66
	v_add_f32_e32 v66, 0x3727c5ac, v66
	v_rsq_f32_e32 v118, v66
	s_nop 0
	v_mov_b32_e32 v119, v118
	v_pk_mul_f32 v[18:19], v[18:19], v[118:119]
	v_pk_mul_f32 v[20:21], v[20:21], v[118:119]
	v_pk_mul_f32 v[22:23], v[22:23], v[118:119]
	v_pk_mul_f32 v[24:25], v[24:25], v[118:119]
	v_pk_mul_f32 v[26:27], v[26:27], v[118:119]
	v_pk_mul_f32 v[28:29], v[28:29], v[118:119]
	v_pk_mul_f32 v[30:31], v[30:31], v[118:119]
	v_pk_mul_f32 v[32:33], v[32:33], v[118:119]
	v_pk_fma_f32 v[76:77], v[18:19], v[34:35], v[50:51]
	v_pk_fma_f32 v[78:79], v[20:21], v[36:37], v[52:53]
	v_pk_fma_f32 v[80:81], v[22:23], v[38:39], v[54:55]
	v_pk_fma_f32 v[82:83], v[24:25], v[40:41], v[56:57]
	v_pk_fma_f32 v[84:85], v[26:27], v[42:43], v[58:59]
	v_pk_fma_f32 v[86:87], v[28:29], v[44:45], v[60:61]
	v_pk_fma_f32 v[88:89], v[30:31], v[46:47], v[62:63]
	v_pk_fma_f32 v[90:91], v[32:33], v[48:49], v[64:65]
	v_cvt_pk_bf16_f32 v92, v76, v77
	v_cvt_pk_bf16_f32 v93, v78, v79
	v_cvt_pk_bf16_f32 v94, v80, v81
	v_cvt_pk_bf16_f32 v95, v82, v83
	v_cvt_pk_bf16_f32 v96, v84, v85
	v_cvt_pk_bf16_f32 v97, v86, v87
	v_cvt_pk_bf16_f32 v98, v88, v89
	v_cvt_pk_bf16_f32 v99, v90, v91
	global_store_dwordx2 v115, v[92:93], s[2:3] offset:0
	global_store_dwordx2 v115, v[94:95], s[2:3] offset:512
	global_store_dwordx2 v115, v[96:97], s[2:3] offset:1024
	global_store_dwordx2 v115, v[98:99], s[2:3] offset:1536
	s_add_u32 s2, s2, 0x800
	s_addc_u32 s3, s3, 0
	v_readfirstlane_b32 s10, v244
	v_readlane_b32 s9, v254, 6
	s_lshr_b32 s10, s10, 6
	s_cmp_ge_u32 s10, 2
	s_cbranch_scc1 .Lln1_done
	s_lshl_b32 s9, s9, 1
	s_add_i32 s9, s9, s10
	s_lshl_b32 s11, s9, 12
	s_add_u32 s11, s11, 0x8000000
	s_add_u32 s0, s4, s11
	s_addc_u32 s1, s5, 0
	s_lshl_b32 s11, s9, 11
	s_add_u32 s11, s11, 0x79c0000
	s_add_u32 s2, s6, s11
	s_addc_u32 s3, s7, 0
	s_lshl_b32 s11, s9, 12
	s_add_u32 s11, s11, 0x1e482000
	s_add_u32 s10, s6, s11
	s_addc_u32 s11, s7, 0
	global_load_dwordx4 v[0:3], v114, s[0:1] offset:0
	global_load_dwordx4 v[4:7], v114, s[0:1] offset:1024
	global_load_dwordx4 v[8:11], v114, s[0:1] offset:2048
	global_load_dwordx4 v[12:15], v114, s[0:1] offset:3072
	global_load_dwordx4 v[18:21], v114, s[10:11] offset:0
	global_load_dwordx4 v[22:25], v114, s[10:11] offset:1024
	global_load_dwordx4 v[26:29], v114, s[10:11] offset:2048
	global_load_dwordx4 v[30:33], v114, s[10:11] offset:3072
	s_add_u32 s10, s10, 0x200000
	s_addc_u32 s11, s11, 0
	global_load_dwordx4 v[66:69], v114, s[10:11] offset:0
	global_load_dwordx4 v[70:73], v114, s[10:11] offset:1024
	global_load_dwordx4 v[74:77], v114, s[10:11] offset:2048
	global_load_dwordx4 v[78:81], v114, s[10:11] offset:3072
	s_add_u32 s10, s10, 0x200000
	s_addc_u32 s11, s11, 0
	global_load_dwordx4 v[82:85], v114, s[10:11] offset:0
	global_load_dwordx4 v[86:89], v114, s[10:11] offset:1024
	global_load_dwordx4 v[90:93], v114, s[10:11] offset:2048
	global_load_dwordx4 v[94:97], v114, s[10:11] offset:3072
	s_add_u32 s10, s10, 0x200000
	s_addc_u32 s11, s11, 0
	global_load_dwordx4 v[98:101], v114, s[10:11] offset:0
	global_load_dwordx4 v[102:105], v114, s[10:11] offset:1024
	global_load_dwordx4 v[106:109], v114, s[10:11] offset:2048
	global_load_dwordx4 v[110:113], v114, s[10:11] offset:3072
	s_add_u32 s10, s10, 0x200000
	s_addc_u32 s11, s11, 0
	s_waitcnt vmcnt(0)
; __device__ __forceinline__ void phase_ln(float* R, const float* __restrict__ g, const float* __restrict__ b, bf16_t* xbf, float samp_scale, const float* __restrict__ part, int nsplit, bool f32_all) {
;     ...
;     if (r >= MP) {
;       for (int sp = 0; sp < nsplit; ++sp) {
;         const float* prow = part + ((size_t)sp * MS + (r - MP)) * 1024;
; #pragma unroll
;         for (int i = 0; i < 4; ++i) v[i] = v[i] + *(const f32x4*)(prow + i * 256 + lane * 4);
;       }
;     }
;     float s = 0.f;
; #pragma unroll
;     for (int i = 0; i < 4; ++i) s += v[i][0] + v[i][1] + v[i][2] + v[i][3];
; #pragma unroll
;     for (int o = 32; o >= 1; o >>= 1) s += __shfl_xor(s, o);
;     const float mean = s * (1.f / 1024.f);
;     float ss = 0.f;
; #pragma unroll
;     for (int i = 0; i < 4; ++i) { v[i] = v[i] - mean; ss += v[i][0] * v[i][0] + v[i][1] * v[i][1] + v[i][2] * v[i][2] + v[i][3] * v[i][3]; }
; #pragma unroll
;     for (int o = 32; o >= 1; o >>= 1) ss += __shfl_xor(ss, o);
;     const float rstd = rsqrtf(ss * (1.f / 1024.f) + LN_EPS);
; #pragma unroll
;     for (int i = 0; i < 4; ++i) {
;       const f32x4 y = v[i] * rstd * gv[i] + bv[i];
;       if (r >= MP) *(f32x4*)(row + i * 256 + lane * 4) = y * samp_scale;
;       else if (f32_all) *(f32x4*)(row + i * 256 + lane * 4) = y;
;       if (xbf) {
;         u32x2 wv;
;         wv[0] = cvt_pk_bf16(y[0], y[1]); wv[1] = cvt_pk_bf16(y[2], y[3]);
;         *(u32x2*)(xbf + (size_t)r * 1024 + i * 256 + lane * 4) = wv;
;       }
;     }
	v_pk_add_f32 v[0:1], v[0:1], v[18:19]
	v_pk_add_f32 v[2:3], v[2:3], v[20:21]
	v_pk_add_f32 v[4:5], v[4:5], v[22:23]
	v_pk_add_f32 v[6:7], v[6:7], v[24:25]
	v_pk_add_f32 v[8:9], v[8:9], v[26:27]
	v_pk_add_f32 v[10:11], v[10:11], v[28:29]
	v_pk_add_f32 v[12:13], v[12:13], v[30:31]
	v_pk_add_f32 v[14:15], v[14:15], v[32:33]
	v_pk_add_f32 v[0:1], v[0:1], v[66:67]
	v_pk_add_f32 v[2:3], v[2:3], v[68:69]
	v_pk_add_f32 v[4:5], v[4:5], v[70:71]
	v_pk_add_f32 v[6:7], v[6:7], v[72:73]
	v_pk_add_f32 v[8:9], v[8:9], v[74:75]
	v_pk_add_f32 v[10:11], v[10:11], v[76:77]
	v_pk_add_f32 v[12:13], v[12:13], v[78:79]
	v_pk_add_f32 v[14:15], v[14:15], v[80:81]
	v_pk_add_f32 v[0:1], v[0:1], v[82:83]
	v_pk_add_f32 v[2:3], v[2:3], v[84:85]
	v_pk_add_f32 v[4:5], v[4:5], v[86:87]
	v_pk_add_f32 v[6:7], v[6:7], v[88:89]
	v_pk_add_f32 v[8:9], v[8:9], v[90:91]
	v_pk_add_f32 v[10:11], v[10:11], v[92:93]
	v_pk_add_f32 v[12:13], v[12:13], v[94:95]
	v_pk_add_f32 v[14:15], v[14:15], v[96:97]
	v_pk_add_f32 v[0:1], v[0:1], v[98:99]
	v_pk_add_f32 v[2:3], v[2:3], v[100:101]
	v_pk_add_f32 v[4:5], v[4:5], v[102:103]
	v_pk_add_f32 v[6:7], v[6:7], v[104:105]
	v_pk_add_f32 v[8:9], v[8:9], v[106:107]
	v_pk_add_f32 v[10:11], v[10:11], v[108:109]
	v_pk_add_f32 v[12:13], v[12:13], v[110:111]
	v_pk_add_f32 v[14:15], v[14:15], v[112:113]
	v_pk_add_f32 v[66:67], v[0:1], v[2:3]
	v_pk_add_f32 v[68:69], v[4:5], v[6:7]
	v_pk_add_f32 v[70:71], v[8:9], v[10:11]
	v_pk_add_f32 v[72:73], v[12:13], v[14:15]
	v_pk_add_f32 v[66:67], v[66:67], v[68:69]
	v_pk_add_f32 v[70:71], v[70:71], v[72:73]
	v_pk_add_f32 v[66:67], v[66:67], v[70:71]
	v_add_f32_e32 v66, v66, v67
	s_nop 1
	v_add_f32_dpp v66, v66, v66 row_shr:1 row_mask:0xf bank_mask:0xf bound_ctrl:1
	s_nop 1
	v_add_f32_dpp v66, v66, v66 row_shr:2 row_mask:0xf bank_mask:0xf bound_ctrl:1
	s_nop 1
	v_add_f32_dpp v66, v66, v66 row_shr:4 row_mask:0xf bank_mask:0xf bound_ctrl:1
	s_nop 1
	v_add_f32_dpp v66, v66, v66 row_shr:8 row_mask:0xf bank_mask:0xf bound_ctrl:1
	s_nop 0
	v_readlane_b32 s9, v66, 15
	v_readlane_b32 s10, v66, 31
	v_readlane_b32 s11, v66, 47
	v_readlane_b32 vcc_lo, v66, 63
	s_nop 1
	v_mov_b32_e32 v66, s9
	v_add_f32_e32 v66, s10, v66
	v_add_f32_e32 v66, s11, v66
	v_add_f32_e32 v66, vcc_lo, v66
	v_mul_f32_e32 v116, 0x3a800000, v66
	v_mov_b32_e32 v117, v116
	v_pk_add_f32 v[0:1], v[0:1], v[116:117] neg_lo:[0,1] neg_hi:[0,1]
	v_pk_add_f32 v[2:3], v[2:3], v[116:117] neg_lo:[0,1] neg_hi:[0,1]
	v_pk_add_f32 v[4:5], v[4:5], v[116:117] neg_lo:[0,1] neg_hi:[0,1]
	v_pk_add_f32 v[6:7], v[6:7], v[116:117] neg_lo:[0,1] neg_hi:[0,1]
	v_pk_add_f32 v[8:9], v[8:9], v[116:117] neg_lo:[0,1] neg_hi:[0,1]
	v_pk_add_f32 v[10:11], v[10:11], v[116:117] neg_lo:[0,1] neg_hi:[0,1]
	v_pk_add_f32 v[12:13], v[12:13], v[116:117] neg_lo:[0,1] neg_hi:[0,1]
	v_pk_add_f32 v[14:15], v[14:15], v[116:117] neg_lo:[0,1] neg_hi:[0,1]
	v_pk_mul_f32 v[66:67], v[0:1], v[0:1]
	v_pk_mul_f32 v[68:69], v[2:3], v[2:3]
	v_pk_fma_f32 v[66:67], v[4:5], v[4:5], v[66:67]
	v_pk_fma_f32 v[68:69], v[6:7], v[6:7], v[68:69]
	v_pk_fma_f32 v[66:67], v[8:9], v[8:9], v[66:67]
	v_pk_fma_f32 v[68:69], v[10:11], v[10:11], v[68:69]
	v_pk_fma_f32 v[66:67], v[12:13], v[12:13], v[66:67]
	v_pk_fma_f32 v[68:69], v[14:15], v[14:15], v[68:69]
	v_pk_add_f32 v[66:67], v[66:67], v[68:69]
	v_add_f32_e32 v66, v66, v67
	s_nop 1
	v_add_f32_dpp v66, v66, v66 row_shr:1 row_mask:0xf bank_mask:0xf bound_ctrl:1
	s_nop 1
	v_add_f32_dpp v66, v66, v66 row_shr:2 row_mask:0xf bank_mask:0xf bound_ctrl:1
	s_nop 1
	v_add_f32_dpp v66, v66, v66 row_shr:4 row_mask:0xf bank_mask:0xf bound_ctrl:1
	s_nop 1
	v_add_f32_dpp v66, v66, v66 row_shr:8 row_mask:0xf bank_mask:0xf bound_ctrl:1
	s_nop 0
	v_readlane_b32 s9, v66, 15
	v_readlane_b32 s10, v66, 31
	v_readlane_b32 s11, v66, 47
	v_readlane_b32 vcc_lo, v66, 63
	s_nop 1
	v_mov_b32_e32 v66, s9
	v_add_f32_e32 v66, s10, v66
	v_add_f32_e32 v66, s11, v66
	v_add_f32_e32 v66, vcc_lo, v66
	v_mul_f32_e32 v66, 0x3a800000, v66
	v_add_f32_e32 v66, 0x3727c5ac, v66
	v_rsq_f32_e32 v118, v66
	s_nop 0
	v_mov_b32_e32 v119, v118
	v_pk_mul_f32 v[0:1], v[0:1], v[118:119]
	v_pk_mul_f32 v[2:3], v[2:3], v[118:119]
	v_pk_mul_f32 v[4:5], v[4:5], v[118:119]
	v_pk_mul_f32 v[6:7], v[6:7], v[118:119]
	v_pk_mul_f32 v[8:9], v[8:9], v[118:119]
	v_pk_mul_f32 v[10:11], v[10:11], v[118:119]
	v_pk_mul_f32 v[12:13], v[12:13], v[118:119]
	v_pk_mul_f32 v[14:15], v[14:15], v[118:119]
	v_pk_fma_f32 v[76:77], v[0:1], v[34:35], v[50:51]
	v_pk_fma_f32 v[78:79], v[2:3], v[36:37], v[52:53]
	v_pk_fma_f32 v[80:81], v[4:5], v[38:39], v[54:55]
	v_pk_fma_f32 v[82:83], v[6:7], v[40:41], v[56:57]
	v_pk_fma_f32 v[84:85], v[8:9], v[42:43], v[58:59]
	v_pk_fma_f32 v[86:87], v[10:11], v[44:45], v[60:61]
	v_pk_fma_f32 v[88:89], v[12:13], v[46:47], v[62:63]
	v_pk_fma_f32 v[90:91], v[14:15], v[48:49], v[64:65]
	s_mov_b32 s9, 0x3fb504f3
	v_mov_b32_e32 v120, s9
	v_mov_b32_e32 v121, s9
	v_pk_mul_f32 v[0:1], v[76:77], v[120:121]
	v_pk_mul_f32 v[2:3], v[78:79], v[120:121]
	v_pk_mul_f32 v[4:5], v[80:81], v[120:121]
	v_pk_mul_f32 v[6:7], v[82:83], v[120:121]
	v_pk_mul_f32 v[8:9], v[84:85], v[120:121]
	v_pk_mul_f32 v[10:11], v[86:87], v[120:121]
	v_pk_mul_f32 v[12:13], v[88:89], v[120:121]
	v_pk_mul_f32 v[14:15], v[90:91], v[120:121]
	global_store_dwordx4 v114, v[0:3], s[0:1] offset:0
	global_store_dwordx4 v114, v[4:7], s[0:1] offset:1024
	global_store_dwordx4 v114, v[8:11], s[0:1] offset:2048
	global_store_dwordx4 v114, v[12:15], s[0:1] offset:3072
	v_cvt_pk_bf16_f32 v92, v76, v77
	v_cvt_pk_bf16_f32 v93, v78, v79
	v_cvt_pk_bf16_f32 v94, v80, v81
	v_cvt_pk_bf16_f32 v95, v82, v83
	v_cvt_pk_bf16_f32 v96, v84, v85
	v_cvt_pk_bf16_f32 v97, v86, v87
	v_cvt_pk_bf16_f32 v98, v88, v89
	v_cvt_pk_bf16_f32 v99, v90, v91
	global_store_dwordx2 v115, v[92:93], s[2:3] offset:0
	global_store_dwordx2 v115, v[94:95], s[2:3] offset:512
	global_store_dwordx2 v115, v[96:97], s[2:3] offset:1024
	global_store_dwordx2 v115, v[98:99], s[2:3] offset:1536

; __device__ __forceinline__ int otid() { int t = threadIdx.x; asm volatile("" : "+v"(t)); return t; }
; __device__ __forceinline__ void phase_ln(float* R, const float* __restrict__ g, const float* __restrict__ b, bf16_t* xbf, float samp_scale, const float* __restrict__ part, int nsplit, bool f32_all) {
;   const int tid = otid(), lane = tid & 63, gw = blockIdx.x * 8 + (tid >> 6), nw = gridDim.x * 8;
;   f32x4 gv[4], bv[4];
; #pragma unroll
;   for (int i = 0; i < 4; ++i) { gv[i] = *(const f32x4*)(g + i * 256 + lane * 4); bv[i] = *(const f32x4*)(b + i * 256 + lane * 4); }
;   for (int r = gw; r < MT; r += nw) {
;     float* row = R + (size_t)r * 1024;
;     f32x4 v[4];
; #pragma unroll
;     for (int i = 0; i < 4; ++i) v[i] = *(const f32x4*)(row + i * 256 + lane * 4);
;     if (r >= MP) {
;       for (int sp = 0; sp < nsplit; ++sp) {
;         const float* prow = part + ((size_t)sp * MS + (r - MP)) * 1024;
; #pragma unroll
;         for (int i = 0; i < 4; ++i) v[i] = v[i] + *(const f32x4*)(prow + i * 256 + lane * 4);
;       }
;     }
;     float s = 0.f;
; #pragma unroll
;     for (int i = 0; i < 4; ++i) s += v[i][0] + v[i][1] + v[i][2] + v[i][3];
; #pragma unroll
;     for (int o = 32; o >= 1; o >>= 1) s += __shfl_xor(s, o);
;     const float mean = s * (1.f / 1024.f);
;     float ss = 0.f;
; #pragma unroll
;     for (int i = 0; i < 4; ++i) { v[i] = v[i] - mean; ss += v[i][0] * v[i][0] + v[i][1] * v[i][1] + v[i][2] * v[i][2] + v[i][3] * v[i][3]; }
; #pragma unroll
;     for (int o = 32; o >= 1; o >>= 1) ss += __shfl_xor(ss, o);
;     const float rstd = rsqrtf(ss * (1.f / 1024.f) + LN_EPS);
; #pragma unroll
;     for (int i = 0; i < 4; ++i) {
;       const f32x4 y = v[i] * rstd * gv[i] + bv[i];
;       if (r >= MP) *(f32x4*)(row + i * 256 + lane * 4) = y * samp_scale;
;       else if (f32_all) *(f32x4*)(row + i * 256 + lane * 4) = y;
;       if (xbf) {
;         u32x2 wv;
;         wv[0] = cvt_pk_bf16(y[0], y[1]); wv[1] = cvt_pk_bf16(y[2], y[3]);
;         *(u32x2*)(xbf + (size_t)r * 1024 + i * 256 + lane * 4) = wv;
;       }
;     }
.LBB0_3944:
	s_or_b64 exec, exec, s[0:1]
	v_readlane_b32 s0, v254, 51
	s_nop 0
	s_cmp_lg_u32 s0, 0
	s_cbranch_scc1 .Lln2_orig
	v_readlane_b32 s6, v254, 2
	v_readlane_b32 s7, v254, 3
	v_readlane_b32 s8, v255, 22
	s_waitcnt lgkmcnt(0)
	s_barrier
	s_load_dwordx4 s[0:3], s[6:7], 0x98
	s_load_dwordx4 s[4:7], s[6:7], 0xa8
	v_readlane_b32 s9, v254, 15
	v_readfirstlane_b32 s10, v244
	v_lshlrev_b32_e32 v114, 4, v252
	v_lshlrev_b32_e32 v115, 3, v252
	s_lshr_b32 s10, s10, 6
	s_add_i32 s9, s9, s10
	s_lshl_b32 s9, s9, 4
	s_lshl_b32 s11, s8, 12
	s_waitcnt lgkmcnt(0)
	s_add_u32 s0, s0, s11
	s_addc_u32 s1, s1, 0
	s_add_u32 s2, s2, s11
	s_addc_u32 s3, s3, 0
	global_load_dwordx4 v[34:37], v114, s[0:1] offset:0
	global_load_dwordx4 v[38:41], v114, s[0:1] offset:1024
	global_load_dwordx4 v[42:45], v114, s[0:1] offset:2048
	global_load_dwordx4 v[46:49], v114, s[0:1] offset:3072
	global_load_dwordx4 v[50:53], v114, s[2:3] offset:0
	global_load_dwordx4 v[54:57], v114, s[2:3] offset:1024
	global_load_dwordx4 v[58:61], v114, s[2:3] offset:2048
	global_load_dwordx4 v[62:65], v114, s[2:3] offset:3072
	s_lshl_b32 s11, s9, 12
	s_add_u32 s0, s4, s11
	s_addc_u32 s1, s5, 0
	s_lshl_b32 s11, s9, 11
	s_add_u32 s11, s11, 0x39c0000
	s_add_u32 s2, s6, s11
	s_addc_u32 s3, s7, 0
	global_load_dwordx4 v[0:3], v114, s[0:1] offset:0
	global_load_dwordx4 v[4:7], v114, s[0:1] offset:1024
	global_load_dwordx4 v[8:11], v114, s[0:1] offset:2048
	global_load_dwordx4 v[12:15], v114, s[0:1] offset:3072
	s_add_u32 s0, s0, 0x1000
	s_addc_u32 s1, s1, 0
	global_load_dwordx4 v[18:21], v114, s[0:1] offset:0
	global_load_dwordx4 v[22:25], v114, s[0:1] offset:1024
	global_load_dwordx4 v[26:29], v114, s[0:1] offset:2048
	global_load_dwordx4 v[30:33], v114, s[0:1] offset:3072
	s_waitcnt vmcnt(4)
	v_pk_add_f32 v[66:67], v[0:1], v[2:3]
	v_pk_add_f32 v[68:69], v[4:5], v[6:7]
	v_pk_add_f32 v[70:71], v[8:9], v[10:11]
	v_pk_add_f32 v[72:73], v[12:13], v[14:15]
	v_pk_add_f32 v[66:67], v[66:67], v[68:69]
	v_pk_add_f32 v[70:71], v[70:71], v[72:73]
	v_pk_add_f32 v[66:67], v[66:67], v[70:71]
	v_add_f32_e32 v66, v66, v67
	s_nop 1
	v_add_f32_dpp v66, v66, v66 row_shr:1 row_mask:0xf bank_mask:0xf bound_ctrl:1
	s_nop 1
	v_add_f32_dpp v66, v66, v66 row_shr:2 row_mask:0xf bank_mask:0xf bound_ctrl:1
	s_nop 1
	v_add_f32_dpp v66, v66, v66 row_shr:4 row_mask:0xf bank_mask:0xf bound_ctrl:1
	s_nop 1
	v_add_f32_dpp v66, v66, v66 row_shr:8 row_mask:0xf bank_mask:0xf bound_ctrl:1
	s_nop 0
	v_readlane_b32 s9, v66, 15
	v_readlane_b32 s10, v66, 31
	v_readlane_b32 s11, v66, 47
	v_readlane_b32 vcc_lo, v66, 63
	s_nop 1
	v_mov_b32_e32 v66, s9
	v_add_f32_e32 v66, s10, v66
	v_add_f32_e32 v66, s11, v66
	v_add_f32_e32 v66, vcc_lo, v66
	v_mul_f32_e32 v116, 0x3a800000, v66
	v_mov_b32_e32 v117, v116
	v_pk_add_f32 v[0:1], v[0:1], v[116:117] neg_lo:[0,1] neg_hi:[0,1]
	v_pk_add_f32 v[2:3], v[2:3], v[116:117] neg_lo:[0,1] neg_hi:[0,1]
	v_pk_add_f32 v[4:5], v[4:5], v[116:117] neg_lo:[0,1] neg_hi:[0,1]
	v_pk_add_f32 v[6:7], v[6:7], v[116:117] neg_lo:[0,1] neg_hi:[0,1]
	v_pk_add_f32 v[8:9], v[8:9], v[116:117] neg_lo:[0,1] neg_hi:[0,1]
	v_pk_add_f32 v[10:11], v[10:11], v[116:117] neg_lo:[0,1] neg_hi:[0,1]
	v_pk_add_f32 v[12:13], v[12:13], v[116:117] neg_lo:[0,1] neg_hi:[0,1]
	v_pk_add_f32 v[14:15], v[14:15], v[116:117] neg_lo:[0,1] neg_hi:[0,1]
	v_pk_mul_f32 v[66:67], v[0:1], v[0:1]
	v_pk_mul_f32 v[68:69], v[2:3], v[2:3]
	v_pk_fma_f32 v[66:67], v[4:5], v[4:5], v[66:67]
	v_pk_fma_f32 v[68:69], v[6:7], v[6:7], v[68:69]
	v_pk_fma_f32 v[66:67], v[8:9], v[8:9], v[66:67]
	v_pk_fma_f32 v[68:69], v[10:11], v[10:11], v[68:69]
	v_pk_fma_f32 v[66:67], v[12:13], v[12:13], v[66:67]
	v_pk_fma_f32 v[68:69], v[14:15], v[14:15], v[68:69]
	v_pk_add_f32 v[66:67], v[66:67], v[68:69]
	v_add_f32_e32 v66, v66, v67
	s_nop 1
	v_add_f32_dpp v66, v66, v66 row_shr:1 row_mask:0xf bank_mask:0xf bound_ctrl:1
	s_nop 1
	v_add_f32_dpp v66, v66, v66 row_shr:2 row_mask:0xf bank_mask:0xf bound_ctrl:1
	s_nop 1
	v_add_f32_dpp v66, v66, v66 row_shr:4 row_mask:0xf bank_mask:0xf bound_ctrl:1
	s_nop 1
	v_add_f32_dpp v66, v66, v66 row_shr:8 row_mask:0xf bank_mask:0xf bound_ctrl:1
	s_nop 0
	v_readlane_b32 s9, v66, 15
	v_readlane_b32 s10, v66, 31
	v_readlane_b32 s11, v66, 47
	v_readlane_b32 vcc_lo, v66, 63
	s_nop 1
	v_mov_b32_e32 v66, s9
	v_add_f32_e32 v66, s10, v66
	v_add_f32_e32 v66, s11, v66
	v_add_f32_e32 v66, vcc_lo, v66
	v_mul_f32_e32 v66, 0x3a800000, v66
	v_add_f32_e32 v66, 0x3727c5ac, v66
	v_rsq_f32_e32 v118, v66
	s_nop 0
	v_mov_b32_e32 v119, v118
	v_pk_mul_f32 v[0:1], v[0:1], v[118:119]
	v_pk_mul_f32 v[2:3], v[2:3], v[118:119]
	v_pk_mul_f32 v[4:5], v[4:5], v[118:119]
	v_pk_mul_f32 v[6:7], v[6:7], v[118:119]
	v_pk_mul_f32 v[8:9], v[8:9], v[118:119]
	v_pk_mul_f32 v[10:11], v[10:11], v[118:119]
	v_pk_mul_f32 v[12:13], v[12:13], v[118:119]
	v_pk_mul_f32 v[14:15], v[14:15], v[118:119]
	v_pk_fma_f32 v[76:77], v[0:1], v[34:35], v[50:51]
	v_pk_fma_f32 v[78:79], v[2:3], v[36:37], v[52:53]
	v_pk_fma_f32 v[80:81], v[4:5], v[38:39], v[54:55]
	v_pk_fma_f32 v[82:83], v[6:7], v[40:41], v[56:57]
	v_pk_fma_f32 v[84:85], v[8:9], v[42:43], v[58:59]
	v_pk_fma_f32 v[86:87], v[10:11], v[44:45], v[60:61]
	v_pk_fma_f32 v[88:89], v[12:13], v[46:47], v[62:63]
	v_pk_fma_f32 v[90:91], v[14:15], v[48:49], v[64:65]
	s_cmp_lg_u32 s8, 0
	s_cbranch_scc1 .Lln2_f32_0
	v_cvt_pk_bf16_f32 v92, v76, v77
	v_cvt_pk_bf16_f32 v93, v78, v79
	v_cvt_pk_bf16_f32 v94, v80, v81
	v_cvt_pk_bf16_f32 v95, v82, v83
	v_cvt_pk_bf16_f32 v96, v84, v85
	v_cvt_pk_bf16_f32 v97, v86, v87
	v_cvt_pk_bf16_f32 v98, v88, v89
	v_cvt_pk_bf16_f32 v99, v90, v91
	global_store_dwordx2 v115, v[92:93], s[2:3] offset:0
	global_store_dwordx2 v115, v[94:95], s[2:3] offset:512
	global_store_dwordx2 v115, v[96:97], s[2:3] offset:1024
	global_store_dwordx2 v115, v[98:99], s[2:3] offset:1536
	s_branch .Lln2_st_0
; __device__ __forceinline__ void phase_ln(float* R, const float* __restrict__ g, const float* __restrict__ b, bf16_t* xbf, float samp_scale, const float* __restrict__ part, int nsplit, bool f32_all) {
;     ...
;     float s = 0.f;
; #pragma unroll
;     for (int i = 0; i < 4; ++i) s += v[i][0] + v[i][1] + v[i][2] + v[i][3];
; #pragma unroll
;     for (int o = 32; o >= 1; o >>= 1) s += __shfl_xor(s, o);
;     const float mean = s * (1.f / 1024.f);
;     float ss = 0.f;
; #pragma unroll
;     for (int i = 0; i < 4; ++i) { v[i] = v[i] - mean; ss += v[i][0] * v[i][0] + v[i][1] * v[i][1] + v[i][2] * v[i][2] + v[i][3] * v[i][3]; }
; #pragma unroll
;     for (int o = 32; o >= 1; o >>= 1) ss += __shfl_xor(ss, o);
;     const float rstd = rsqrtf(ss * (1.f / 1024.f) + LN_EPS);
; #pragma unroll
;     for (int i = 0; i < 4; ++i) {
;       const f32x4 y = v[i] * rstd * gv[i] + bv[i];
;       if (r >= MP) *(f32x4*)(row + i * 256 + lane * 4) = y * samp_scale;
;       else if (f32_all) *(f32x4*)(row + i * 256 + lane * 4) = y;
;       if (xbf) {
;         u32x2 wv;
;         wv[0] = cvt_pk_bf16(y[0], y[1]); wv[1] = cvt_pk_bf16(y[2], y[3]);
;         *(u32x2*)(xbf + (size_t)r * 1024 + i * 256 + lane * 4) = wv;
;       }
;     }
.Lln2_f32_0:
	s_sub_u32 s10, s0, 0x1000
	s_subb_u32 s11, s1, 0
	global_store_dwordx4 v114, v[76:79], s[10:11] offset:0
	global_store_dwordx4 v114, v[80:83], s[10:11] offset:1024
	global_store_dwordx4 v114, v[84:87], s[10:11] offset:2048
	global_store_dwordx4 v114, v[88:91], s[10:11] offset:3072
.Lln2_st_0:
	s_add_u32 s2, s2, 0x800
	s_addc_u32 s3, s3, 0
	s_add_u32 s0, s0, 0x1000
	s_addc_u32 s1, s1, 0
	global_load_dwordx4 v[0:3], v114, s[0:1] offset:0
	global_load_dwordx4 v[4:7], v114, s[0:1] offset:1024
	global_load_dwordx4 v[8:11], v114, s[0:1] offset:2048
	global_load_dwordx4 v[12:15], v114, s[0:1] offset:3072
	s_waitcnt vmcnt(8)
	v_pk_add_f32 v[66:67], v[18:19], v[20:21]
	v_pk_add_f32 v[68:69], v[22:23], v[24:25]
	v_pk_add_f32 v[70:71], v[26:27], v[28:29]
	v_pk_add_f32 v[72:73], v[30:31], v[32:33]
	v_pk_add_f32 v[66:67], v[66:67], v[68:69]
	v_pk_add_f32 v[70:71], v[70:71], v[72:73]
	v_pk_add_f32 v[66:67], v[66:67], v[70:71]
	v_add_f32_e32 v66, v66, v67
	s_nop 1
	v_add_f32_dpp v66, v66, v66 row_shr:1 row_mask:0xf bank_mask:0xf bound_ctrl:1
	s_nop 1
	v_add_f32_dpp v66, v66, v66 row_shr:2 row_mask:0xf bank_mask:0xf bound_ctrl:1
	s_nop 1
	v_add_f32_dpp v66, v66, v66 row_shr:4 row_mask:0xf bank_mask:0xf bound_ctrl:1
	s_nop 1
	v_add_f32_dpp v66, v66, v66 row_shr:8 row_mask:0xf bank_mask:0xf bound_ctrl:1
	s_nop 0
	v_readlane_b32 s9, v66, 15
	v_readlane_b32 s10, v66, 31
	v_readlane_b32 s11, v66, 47
	v_readlane_b32 vcc_lo, v66, 63
	s_nop 1
	v_mov_b32_e32 v66, s9
	v_add_f32_e32 v66, s10, v66
	v_add_f32_e32 v66, s11, v66
	v_add_f32_e32 v66, vcc_lo, v66
	v_mul_f32_e32 v116, 0x3a800000, v66
	v_mov_b32_e32 v117, v116
	v_pk_add_f32 v[18:19], v[18:19], v[116:117] neg_lo:[0,1] neg_hi:[0,1]
	v_pk_add_f32 v[20:21], v[20:21], v[116:117] neg_lo:[0,1] neg_hi:[0,1]
	v_pk_add_f32 v[22:23], v[22:23], v[116:117] neg_lo:[0,1] neg_hi:[0,1]
	v_pk_add_f32 v[24:25], v[24:25], v[116:117] neg_lo:[0,1] neg_hi:[0,1]
	v_pk_add_f32 v[26:27], v[26:27], v[116:117] neg_lo:[0,1] neg_hi:[0,1]
	v_pk_add_f32 v[28:29], v[28:29], v[116:117] neg_lo:[0,1] neg_hi:[0,1]
	v_pk_add_f32 v[30:31], v[30:31], v[116:117] neg_lo:[0,1] neg_hi:[0,1]
	v_pk_add_f32 v[32:33], v[32:33], v[116:117] neg_lo:[0,1] neg_hi:[0,1]
	v_pk_mul_f32 v[66:67], v[18:19], v[18:19]
	v_pk_mul_f32 v[68:69], v[20:21], v[20:21]
	v_pk_fma_f32 v[66:67], v[22:23], v[22:23], v[66:67]
	v_pk_fma_f32 v[68:69], v[24:25], v[24:25], v[68:69]
	v_pk_fma_f32 v[66:67], v[26:27], v[26:27], v[66:67]
	v_pk_fma_f32 v[68:69], v[28:29], v[28:29], v[68:69]
	v_pk_fma_f32 v[66:67], v[30:31], v[30:31], v[66:67]
	v_pk_fma_f32 v[68:69], v[32:33], v[32:33], v[68:69]
	v_pk_add_f32 v[66:67], v[66:67], v[68:69]
	v_add_f32_e32 v66, v66, v67
	s_nop 1
	v_add_f32_dpp v66, v66, v66 row_shr:1 row_mask:0xf bank_mask:0xf bound_ctrl:1
	s_nop 1
	v_add_f32_dpp v66, v66, v66 row_shr:2 row_mask:0xf bank_mask:0xf bound_ctrl:1
	s_nop 1
	v_add_f32_dpp v66, v66, v66 row_shr:4 row_mask:0xf bank_mask:0xf bound_ctrl:1
	s_nop 1
	v_add_f32_dpp v66, v66, v66 row_shr:8 row_mask:0xf bank_mask:0xf bound_ctrl:1
	s_nop 0
	v_readlane_b32 s9, v66, 15
	v_readlane_b32 s10, v66, 31
	v_readlane_b32 s11, v66, 47
	v_readlane_b32 vcc_lo, v66, 63
	s_nop 1
	v_mov_b32_e32 v66, s9
	v_add_f32_e32 v66, s10, v66
	v_add_f32_e32 v66, s11, v66
	v_add_f32_e32 v66, vcc_lo, v66
	v_mul_f32_e32 v66, 0x3a800000, v66
	v_add_f32_e32 v66, 0x3727c5ac, v66
	v_rsq_f32_e32 v118, v66
	s_nop 0
	v_mov_b32_e32 v119, v118
	v_pk_mul_f32 v[18:19], v[18:19], v[118:119]
	v_pk_mul_f32 v[20:21], v[20:21], v[118:119]
	v_pk_mul_f32 v[22:23], v[22:23], v[118:119]
	v_pk_mul_f32 v[24:25], v[24:25], v[118:119]
	v_pk_mul_f32 v[26:27], v[26:27], v[118:119]
	v_pk_mul_f32 v[28:29], v[28:29], v[118:119]
	v_pk_mul_f32 v[30:31], v[30:31], v[118:119]
	v_pk_mul_f32 v[32:33], v[32:33], v[118:119]
	v_pk_fma_f32 v[76:77], v[18:19], v[34:35], v[50:51]
	v_pk_fma_f32 v[78:79], v[20:21], v[36:37], v[52:53]
	v_pk_fma_f32 v[80:81], v[22:23], v[38:39], v[54:55]
	v_pk_fma_f32 v[82:83], v[24:25], v[40:41], v[56:57]
	v_pk_fma_f32 v[84:85], v[26:27], v[42:43], v[58:59]
	v_pk_fma_f32 v[86:87], v[28:29], v[44:45], v[60:61]
	v_pk_fma_f32 v[88:89], v[30:31], v[46:47], v[62:63]
	v_pk_fma_f32 v[90:91], v[32:33], v[48:49], v[64:65]
	s_cmp_lg_u32 s8, 0
	s_cbranch_scc1 .Lln2_f32_1
	v_cvt_pk_bf16_f32 v92, v76, v77
	v_cvt_pk_bf16_f32 v93, v78, v79
	v_cvt_pk_bf16_f32 v94, v80, v81
	v_cvt_pk_bf16_f32 v95, v82, v83
	v_cvt_pk_bf16_f32 v96, v84, v85
	v_cvt_pk_bf16_f32 v97, v86, v87
	v_cvt_pk_bf16_f32 v98, v88, v89
	v_cvt_pk_bf16_f32 v99, v90, v91
	global_store_dwordx2 v115, v[92:93], s[2:3] offset:0
	global_store_dwordx2 v115, v[94:95], s[2:3] offset:512
	global_store_dwordx2 v115, v[96:97], s[2:3] offset:1024
	global_store_dwordx2 v115, v[98:99], s[2:3] offset:1536
	s_branch .Lln2_st_1

; __device__ __forceinline__ void phase_ln(float* R, const float* __restrict__ g, const float* __restrict__ b, bf16_t* xbf, float samp_scale, const float* __restrict__ part, int nsplit, bool f32_all) {
;     ...
;     float s = 0.f;
; #pragma unroll
;     for (int i = 0; i < 4; ++i) s += v[i][0] + v[i][1] + v[i][2] + v[i][3];
; #pragma unroll
;     for (int o = 32; o >= 1; o >>= 1) s += __shfl_xor(s, o);
;     const float mean = s * (1.f / 1024.f);
;     float ss = 0.f;
; #pragma unroll
;     for (int i = 0; i < 4; ++i) { v[i] = v[i] - mean; ss += v[i][0] * v[i][0] + v[i][1] * v[i][1] + v[i][2] * v[i][2] + v[i][3] * v[i][3]; }
; #pragma unroll
;     for (int o = 32; o >= 1; o >>= 1) ss += __shfl_xor(ss, o);
;     const float rstd = rsqrtf(ss * (1.f / 1024.f) + LN_EPS);
; #pragma unroll
;     for (int i = 0; i < 4; ++i) {
;       const f32x4 y = v[i] * rstd * gv[i] + bv[i];
;       if (r >= MP) *(f32x4*)(row + i * 256 + lane * 4) = y * samp_scale;
;       else if (f32_all) *(f32x4*)(row + i * 256 + lane * 4) = y;
;       if (xbf) {
;         u32x2 wv;
;         wv[0] = cvt_pk_bf16(y[0], y[1]); wv[1] = cvt_pk_bf16(y[2], y[3]);
;         *(u32x2*)(xbf + (size_t)r * 1024 + i * 256 + lane * 4) = wv;
;       }
;     }
.Lln2_st_1:
	s_add_u32 s2, s2, 0x800
	s_addc_u32 s3, s3, 0
	s_add_u32 s0, s0, 0x1000
	s_addc_u32 s1, s1, 0
	global_load_dwordx4 v[18:21], v114, s[0:1] offset:0
	global_load_dwordx4 v[22:25], v114, s[0:1] offset:1024
	global_load_dwordx4 v[26:29], v114, s[0:1] offset:2048
	global_load_dwordx4 v[30:33], v114, s[0:1] offset:3072
	s_waitcnt vmcnt(8)
	v_pk_add_f32 v[66:67], v[0:1], v[2:3]
	v_pk_add_f32 v[68:69], v[4:5], v[6:7]
	v_pk_add_f32 v[70:71], v[8:9], v[10:11]
	v_pk_add_f32 v[72:73], v[12:13], v[14:15]
	v_pk_add_f32 v[66:67], v[66:67], v[68:69]
	v_pk_add_f32 v[70:71], v[70:71], v[72:73]
	v_pk_add_f32 v[66:67], v[66:67], v[70:71]
	v_add_f32_e32 v66, v66, v67
	s_nop 1
	v_add_f32_dpp v66, v66, v66 row_shr:1 row_mask:0xf bank_mask:0xf bound_ctrl:1
	s_nop 1
	v_add_f32_dpp v66, v66, v66 row_shr:2 row_mask:0xf bank_mask:0xf bound_ctrl:1
	s_nop 1
	v_add_f32_dpp v66, v66, v66 row_shr:4 row_mask:0xf bank_mask:0xf bound_ctrl:1
	s_nop 1
	v_add_f32_dpp v66, v66, v66 row_shr:8 row_mask:0xf bank_mask:0xf bound_ctrl:1
	s_nop 0
	v_readlane_b32 s9, v66, 15
	v_readlane_b32 s10, v66, 31
	v_readlane_b32 s11, v66, 47
	v_readlane_b32 vcc_lo, v66, 63
	s_nop 1
	v_mov_b32_e32 v66, s9
	v_add_f32_e32 v66, s10, v66
	v_add_f32_e32 v66, s11, v66
	v_add_f32_e32 v66, vcc_lo, v66
	v_mul_f32_e32 v116, 0x3a800000, v66
	v_mov_b32_e32 v117, v116
	v_pk_add_f32 v[0:1], v[0:1], v[116:117] neg_lo:[0,1] neg_hi:[0,1]
	v_pk_add_f32 v[2:3], v[2:3], v[116:117] neg_lo:[0,1] neg_hi:[0,1]
	v_pk_add_f32 v[4:5], v[4:5], v[116:117] neg_lo:[0,1] neg_hi:[0,1]
	v_pk_add_f32 v[6:7], v[6:7], v[116:117] neg_lo:[0,1] neg_hi:[0,1]
	v_pk_add_f32 v[8:9], v[8:9], v[116:117] neg_lo:[0,1] neg_hi:[0,1]
	v_pk_add_f32 v[10:11], v[10:11], v[116:117] neg_lo:[0,1] neg_hi:[0,1]
	v_pk_add_f32 v[12:13], v[12:13], v[116:117] neg_lo:[0,1] neg_hi:[0,1]
	v_pk_add_f32 v[14:15], v[14:15], v[116:117] neg_lo:[0,1] neg_hi:[0,1]
	v_pk_mul_f32 v[66:67], v[0:1], v[0:1]
	v_pk_mul_f32 v[68:69], v[2:3], v[2:3]
	v_pk_fma_f32 v[66:67], v[4:5], v[4:5], v[66:67]
	v_pk_fma_f32 v[68:69], v[6:7], v[6:7], v[68:69]
	v_pk_fma_f32 v[66:67], v[8:9], v[8:9], v[66:67]
	v_pk_fma_f32 v[68:69], v[10:11], v[10:11], v[68:69]
	v_pk_fma_f32 v[66:67], v[12:13], v[12:13], v[66:67]
	v_pk_fma_f32 v[68:69], v[14:15], v[14:15], v[68:69]
	v_pk_add_f32 v[66:67], v[66:67], v[68:69]
	v_add_f32_e32 v66, v66, v67
	s_nop 1
	v_add_f32_dpp v66, v66, v66 row_shr:1 row_mask:0xf bank_mask:0xf bound_ctrl:1
	s_nop 1
	v_add_f32_dpp v66, v66, v66 row_shr:2 row_mask:0xf bank_mask:0xf bound_ctrl:1
	s_nop 1
	v_add_f32_dpp v66, v66, v66 row_shr:4 row_mask:0xf bank_mask:0xf bound_ctrl:1
	s_nop 1
	v_add_f32_dpp v66, v66, v66 row_shr:8 row_mask:0xf bank_mask:0xf bound_ctrl:1
	s_nop 0
	v_readlane_b32 s9, v66, 15
	v_readlane_b32 s10, v66, 31
	v_readlane_b32 s11, v66, 47
	v_readlane_b32 vcc_lo, v66, 63
	s_nop 1
	v_mov_b32_e32 v66, s9
	v_add_f32_e32 v66, s10, v66
	v_add_f32_e32 v66, s11, v66
	v_add_f32_e32 v66, vcc_lo, v66
	v_mul_f32_e32 v66, 0x3a800000, v66
	v_add_f32_e32 v66, 0x3727c5ac, v66
	v_rsq_f32_e32 v118, v66
	s_nop 0
	v_mov_b32_e32 v119, v118
	v_pk_mul_f32 v[0:1], v[0:1], v[118:119]
	v_pk_mul_f32 v[2:3], v[2:3], v[118:119]
	v_pk_mul_f32 v[4:5], v[4:5], v[118:119]
	v_pk_mul_f32 v[6:7], v[6:7], v[118:119]
	v_pk_mul_f32 v[8:9], v[8:9], v[118:119]
	v_pk_mul_f32 v[10:11], v[10:11], v[118:119]
	v_pk_mul_f32 v[12:13], v[12:13], v[118:119]
	v_pk_mul_f32 v[14:15], v[14:15], v[118:119]
	v_pk_fma_f32 v[76:77], v[0:1], v[34:35], v[50:51]
	v_pk_fma_f32 v[78:79], v[2:3], v[36:37], v[52:53]
	v_pk_fma_f32 v[80:81], v[4:5], v[38:39], v[54:55]
	v_pk_fma_f32 v[82:83], v[6:7], v[40:41], v[56:57]
	v_pk_fma_f32 v[84:85], v[8:9], v[42:43], v[58:59]
	v_pk_fma_f32 v[86:87], v[10:11], v[44:45], v[60:61]
	v_pk_fma_f32 v[88:89], v[12:13], v[46:47], v[62:63]
	v_pk_fma_f32 v[90:91], v[14:15], v[48:49], v[64:65]
	s_cmp_lg_u32 s8, 0
	s_cbranch_scc1 .Lln2_f32_2
	v_cvt_pk_bf16_f32 v92, v76, v77
	v_cvt_pk_bf16_f32 v93, v78, v79
	v_cvt_pk_bf16_f32 v94, v80, v81
	v_cvt_pk_bf16_f32 v95, v82, v83
	v_cvt_pk_bf16_f32 v96, v84, v85
	v_cvt_pk_bf16_f32 v97, v86, v87
	v_cvt_pk_bf16_f32 v98, v88, v89
	v_cvt_pk_bf16_f32 v99, v90, v91
	global_store_dwordx2 v115, v[92:93], s[2:3] offset:0
	global_store_dwordx2 v115, v[94:95], s[2:3] offset:512
	global_store_dwordx2 v115, v[96:97], s[2:3] offset:1024
	global_store_dwordx2 v115, v[98:99], s[2:3] offset:1536
	s_branch .Lln2_st_2

; __device__ __forceinline__ void phase_ln(float* R, const float* __restrict__ g, const float* __restrict__ b, bf16_t* xbf, float samp_scale, const float* __restrict__ part, int nsplit, bool f32_all) {
;     ...
;     float s = 0.f;
; #pragma unroll
;     for (int i = 0; i < 4; ++i) s += v[i][0] + v[i][1] + v[i][2] + v[i][3];
; #pragma unroll
;     for (int o = 32; o >= 1; o >>= 1) s += __shfl_xor(s, o);
;     const float mean = s * (1.f / 1024.f);
;     float ss = 0.f;
; #pragma unroll
;     for (int i = 0; i < 4; ++i) { v[i] = v[i] - mean; ss += v[i][0] * v[i][0] + v[i][1] * v[i][1] + v[i][2] * v[i][2] + v[i][3] * v[i][3]; }
; #pragma unroll
;     for (int o = 32; o >= 1; o >>= 1) ss += __shfl_xor(ss, o);
;     const float rstd = rsqrtf(ss * (1.f / 1024.f) + LN_EPS);
; #pragma unroll
;     for (int i = 0; i < 4; ++i) {
;       const f32x4 y = v[i] * rstd * gv[i] + bv[i];
;       if (r >= MP) *(f32x4*)(row + i * 256 + lane * 4) = y * samp_scale;
;       else if (f32_all) *(f32x4*)(row + i * 256 + lane * 4) = y;
;       if (xbf) {
;         u32x2 wv;
;         wv[0] = cvt_pk_bf16(y[0], y[1]); wv[1] = cvt_pk_bf16(y[2], y[3]);
;         *(u32x2*)(xbf + (size_t)r * 1024 + i * 256 + lane * 4) = wv;
;       }
;     }
.Lln2_st_14:
	s_add_u32 s2, s2, 0x800
	s_addc_u32 s3, s3, 0
	s_waitcnt vmcnt(4)
	v_pk_add_f32 v[66:67], v[18:19], v[20:21]
	v_pk_add_f32 v[68:69], v[22:23], v[24:25]
	v_pk_add_f32 v[70:71], v[26:27], v[28:29]
	v_pk_add_f32 v[72:73], v[30:31], v[32:33]
	v_pk_add_f32 v[66:67], v[66:67], v[68:69]
	v_pk_add_f32 v[70:71], v[70:71], v[72:73]
	v_pk_add_f32 v[66:67], v[66:67], v[70:71]
	v_add_f32_e32 v66, v66, v67
	s_nop 1
	v_add_f32_dpp v66, v66, v66 row_shr:1 row_mask:0xf bank_mask:0xf bound_ctrl:1
	s_nop 1
	v_add_f32_dpp v66, v66, v66 row_shr:2 row_mask:0xf bank_mask:0xf bound_ctrl:1
	s_nop 1
	v_add_f32_dpp v66, v66, v66 row_shr:4 row_mask:0xf bank_mask:0xf bound_ctrl:1
	s_nop 1
	v_add_f32_dpp v66, v66, v66 row_shr:8 row_mask:0xf bank_mask:0xf bound_ctrl:1
	s_nop 0
	v_readlane_b32 s9, v66, 15
	v_readlane_b32 s10, v66, 31
	v_readlane_b32 s11, v66, 47
	v_readlane_b32 vcc_lo, v66, 63
	s_nop 1
	v_mov_b32_e32 v66, s9
	v_add_f32_e32 v66, s10, v66
	v_add_f32_e32 v66, s11, v66
	v_add_f32_e32 v66, vcc_lo, v66
	v_mul_f32_e32 v116, 0x3a800000, v66
	v_mov_b32_e32 v117, v116
	v_pk_add_f32 v[18:19], v[18:19], v[116:117] neg_lo:[0,1] neg_hi:[0,1]
	v_pk_add_f32 v[20:21], v[20:21], v[116:117] neg_lo:[0,1] neg_hi:[0,1]
	v_pk_add_f32 v[22:23], v[22:23], v[116:117] neg_lo:[0,1] neg_hi:[0,1]
	v_pk_add_f32 v[24:25], v[24:25], v[116:117] neg_lo:[0,1] neg_hi:[0,1]
	v_pk_add_f32 v[26:27], v[26:27], v[116:117] neg_lo:[0,1] neg_hi:[0,1]
	v_pk_add_f32 v[28:29], v[28:29], v[116:117] neg_lo:[0,1] neg_hi:[0,1]
	v_pk_add_f32 v[30:31], v[30:31], v[116:117] neg_lo:[0,1] neg_hi:[0,1]
	v_pk_add_f32 v[32:33], v[32:33], v[116:117] neg_lo:[0,1] neg_hi:[0,1]
	v_pk_mul_f32 v[66:67], v[18:19], v[18:19]
	v_pk_mul_f32 v[68:69], v[20:21], v[20:21]
	v_pk_fma_f32 v[66:67], v[22:23], v[22:23], v[66:67]
	v_pk_fma_f32 v[68:69], v[24:25], v[24:25], v[68:69]
	v_pk_fma_f32 v[66:67], v[26:27], v[26:27], v[66:67]
	v_pk_fma_f32 v[68:69], v[28:29], v[28:29], v[68:69]
	v_pk_fma_f32 v[66:67], v[30:31], v[30:31], v[66:67]
	v_pk_fma_f32 v[68:69], v[32:33], v[32:33], v[68:69]
	v_pk_add_f32 v[66:67], v[66:67], v[68:69]
	v_add_f32_e32 v66, v66, v67
	s_nop 1
	v_add_f32_dpp v66, v66, v66 row_shr:1 row_mask:0xf bank_mask:0xf bound_ctrl:1
	s_nop 1
	v_add_f32_dpp v66, v66, v66 row_shr:2 row_mask:0xf bank_mask:0xf bound_ctrl:1
	s_nop 1
	v_add_f32_dpp v66, v66, v66 row_shr:4 row_mask:0xf bank_mask:0xf bound_ctrl:1
	s_nop 1
	v_add_f32_dpp v66, v66, v66 row_shr:8 row_mask:0xf bank_mask:0xf bound_ctrl:1
	s_nop 0
	v_readlane_b32 s9, v66, 15
	v_readlane_b32 s10, v66, 31
	v_readlane_b32 s11, v66, 47
	v_readlane_b32 vcc_lo, v66, 63
	s_nop 1
	v_mov_b32_e32 v66, s9
	v_add_f32_e32 v66, s10, v66
	v_add_f32_e32 v66, s11, v66
	v_add_f32_e32 v66, vcc_lo, v66
	v_mul_f32_e32 v66, 0x3a800000, v66
	v_add_f32_e32 v66, 0x3727c5ac, v66
	v_rsq_f32_e32 v118, v66
	s_nop 0
	v_mov_b32_e32 v119, v118
	v_pk_mul_f32 v[18:19], v[18:19], v[118:119]
	v_pk_mul_f32 v[20:21], v[20:21], v[118:119]
	v_pk_mul_f32 v[22:23], v[22:23], v[118:119]
	v_pk_mul_f32 v[24:25], v[24:25], v[118:119]
	v_pk_mul_f32 v[26:27], v[26:27], v[118:119]
	v_pk_mul_f32 v[28:29], v[28:29], v[118:119]
	v_pk_mul_f32 v[30:31], v[30:31], v[118:119]
	v_pk_mul_f32 v[32:33], v[32:33], v[118:119]
	v_pk_fma_f32 v[76:77], v[18:19], v[34:35], v[50:51]
	v_pk_fma_f32 v[78:79], v[20:21], v[36:37], v[52:53]
	v_pk_fma_f32 v[80:81], v[22:23], v[38:39], v[54:55]
	v_pk_fma_f32 v[82:83], v[24:25], v[40:41], v[56:57]
	v_pk_fma_f32 v[84:85], v[26:27], v[42:43], v[58:59]
	v_pk_fma_f32 v[86:87], v[28:29], v[44:45], v[60:61]
	v_pk_fma_f32 v[88:89], v[30:31], v[46:47], v[62:63]
	v_pk_fma_f32 v[90:91], v[32:33], v[48:49], v[64:65]
	s_cmp_lg_u32 s8, 0
	s_cbranch_scc1 .Lln2_f32_15
	v_cvt_pk_bf16_f32 v92, v76, v77
	v_cvt_pk_bf16_f32 v93, v78, v79
	v_cvt_pk_bf16_f32 v94, v80, v81
	v_cvt_pk_bf16_f32 v95, v82, v83
	v_cvt_pk_bf16_f32 v96, v84, v85
	v_cvt_pk_bf16_f32 v97, v86, v87
	v_cvt_pk_bf16_f32 v98, v88, v89
	v_cvt_pk_bf16_f32 v99, v90, v91
	global_store_dwordx2 v115, v[92:93], s[2:3] offset:0
	global_store_dwordx2 v115, v[94:95], s[2:3] offset:512
	global_store_dwordx2 v115, v[96:97], s[2:3] offset:1024
	global_store_dwordx2 v115, v[98:99], s[2:3] offset:1536
	s_branch .Lln2_st_15

; __device__ __forceinline__ void phase_ln(float* R, const float* __restrict__ g, const float* __restrict__ b, bf16_t* xbf, float samp_scale, const float* __restrict__ part, int nsplit, bool f32_all) {
;     ...
;   for (int r = gw; r < MT; r += nw) {
;     float* row = R + (size_t)r * 1024;
;     f32x4 v[4];
; #pragma unroll
;     for (int i = 0; i < 4; ++i) v[i] = *(const f32x4*)(row + i * 256 + lane * 4);
;     if (r >= MP) {
;       for (int sp = 0; sp < nsplit; ++sp) {
;         const float* prow = part + ((size_t)sp * MS + (r - MP)) * 1024;
; #pragma unroll
;         for (int i = 0; i < 4; ++i) v[i] = v[i] + *(const f32x4*)(prow + i * 256 + lane * 4);
;       }
;     }
.Lln2_st_15:
	s_add_u32 s2, s2, 0x800
	s_addc_u32 s3, s3, 0
	v_readfirstlane_b32 s10, v244
	v_readlane_b32 s9, v254, 6
	s_lshr_b32 s10, s10, 6
	s_cmp_ge_u32 s10, 2
	s_cbranch_scc1 .Lln2_done
	s_lshl_b32 s9, s9, 1
	s_add_i32 s9, s9, s10
	s_lshl_b32 s11, s9, 12
	s_add_u32 s11, s11, 0x8000000
	s_add_u32 s0, s4, s11
	s_addc_u32 s1, s5, 0
	s_lshl_b32 s11, s9, 11
	s_add_u32 s11, s11, 0x79c0000
	s_add_u32 s2, s6, s11
	s_addc_u32 s3, s7, 0
	s_lshl_b32 s11, s9, 12
	s_add_u32 s11, s11, 0x1e482000
	s_add_u32 s10, s6, s11
	s_addc_u32 s11, s7, 0
	global_load_dwordx4 v[0:3], v114, s[0:1] offset:0
	global_load_dwordx4 v[4:7], v114, s[0:1] offset:1024
	global_load_dwordx4 v[8:11], v114, s[0:1] offset:2048
	global_load_dwordx4 v[12:15], v114, s[0:1] offset:3072
	global_load_dwordx4 v[18:21], v114, s[10:11] offset:0
	global_load_dwordx4 v[22:25], v114, s[10:11] offset:1024
	global_load_dwordx4 v[26:29], v114, s[10:11] offset:2048
	global_load_dwordx4 v[30:33], v114, s[10:11] offset:3072
	s_add_u32 s10, s10, 0x200000
	s_addc_u32 s11, s11, 0
	global_load_dwordx4 v[66:69], v114, s[10:11] offset:0
	global_load_dwordx4 v[70:73], v114, s[10:11] offset:1024
	global_load_dwordx4 v[74:77], v114, s[10:11] offset:2048
	global_load_dwordx4 v[78:81], v114, s[10:11] offset:3072
	s_add_u32 s10, s10, 0x200000
	s_addc_u32 s11, s11, 0
	global_load_dwordx4 v[82:85], v114, s[10:11] offset:0
	global_load_dwordx4 v[86:89], v114, s[10:11] offset:1024
	global_load_dwordx4 v[90:93], v114, s[10:11] offset:2048
	global_load_dwordx4 v[94:97], v114, s[10:11] offset:3072
	s_add_u32 s10, s10, 0x200000
	s_addc_u32 s11, s11, 0
	global_load_dwordx4 v[98:101], v114, s[10:11] offset:0
	global_load_dwordx4 v[102:105], v114, s[10:11] offset:1024
	global_load_dwordx4 v[106:109], v114, s[10:11] offset:2048
	global_load_dwordx4 v[110:113], v114, s[10:11] offset:3072
	s_add_u32 s10, s10, 0x200000
	s_addc_u32 s11, s11, 0
	s_waitcnt vmcnt(0)
	v_pk_add_f32 v[0:1], v[0:1], v[18:19]
	v_pk_add_f32 v[2:3], v[2:3], v[20:21]
	v_pk_add_f32 v[4:5], v[4:5], v[22:23]
	v_pk_add_f32 v[6:7], v[6:7], v[24:25]
	v_pk_add_f32 v[8:9], v[8:9], v[26:27]
	v_pk_add_f32 v[10:11], v[10:11], v[28:29]
	v_pk_add_f32 v[12:13], v[12:13], v[30:31]
	v_pk_add_f32 v[14:15], v[14:15], v[32:33]
	v_pk_add_f32 v[0:1], v[0:1], v[66:67]
	v_pk_add_f32 v[2:3], v[2:3], v[68:69]
	v_pk_add_f32 v[4:5], v[4:5], v[70:71]
	v_pk_add_f32 v[6:7], v[6:7], v[72:73]
	v_pk_add_f32 v[8:9], v[8:9], v[74:75]
	v_pk_add_f32 v[10:11], v[10:11], v[76:77]
	v_pk_add_f32 v[12:13], v[12:13], v[78:79]
	v_pk_add_f32 v[14:15], v[14:15], v[80:81]
	v_pk_add_f32 v[0:1], v[0:1], v[82:83]
	v_pk_add_f32 v[2:3], v[2:3], v[84:85]
	v_pk_add_f32 v[4:5], v[4:5], v[86:87]
	v_pk_add_f32 v[6:7], v[6:7], v[88:89]
	v_pk_add_f32 v[8:9], v[8:9], v[90:91]
	v_pk_add_f32 v[10:11], v[10:11], v[92:93]
	v_pk_add_f32 v[12:13], v[12:13], v[94:95]
	v_pk_add_f32 v[14:15], v[14:15], v[96:97]
	v_pk_add_f32 v[0:1], v[0:1], v[98:99]
	v_pk_add_f32 v[2:3], v[2:3], v[100:101]
	v_pk_add_f32 v[4:5], v[4:5], v[102:103]
	v_pk_add_f32 v[6:7], v[6:7], v[104:105]
	v_pk_add_f32 v[8:9], v[8:9], v[106:107]
	v_pk_add_f32 v[10:11], v[10:11], v[108:109]
	v_pk_add_f32 v[12:13], v[12:13], v[110:111]
	v_pk_add_f32 v[14:15], v[14:15], v[112:113]
	global_load_dwordx4 v[18:21], v114, s[10:11] offset:0
	global_load_dwordx4 v[22:25], v114, s[10:11] offset:1024
	global_load_dwordx4 v[26:29], v114, s[10:11] offset:2048
	global_load_dwordx4 v[30:33], v114, s[10:11] offset:3072
	s_add_u32 s10, s10, 0x200000
	s_addc_u32 s11, s11, 0
	global_load_dwordx4 v[66:69], v114, s[10:11] offset:0
	global_load_dwordx4 v[70:73], v114, s[10:11] offset:1024
	global_load_dwordx4 v[74:77], v114, s[10:11] offset:2048
	global_load_dwordx4 v[78:81], v114, s[10:11] offset:3072
	s_add_u32 s10, s10, 0x200000
	s_addc_u32 s11, s11, 0
	global_load_dwordx4 v[82:85], v114, s[10:11] offset:0
	global_load_dwordx4 v[86:89], v114, s[10:11] offset:1024
	global_load_dwordx4 v[90:93], v114, s[10:11] offset:2048
	global_load_dwordx4 v[94:97], v114, s[10:11] offset:3072
	s_add_u32 s10, s10, 0x200000
	s_addc_u32 s11, s11, 0
	global_load_dwordx4 v[98:101], v114, s[10:11] offset:0
	global_load_dwordx4 v[102:105], v114, s[10:11] offset:1024
	global_load_dwordx4 v[106:109], v114, s[10:11] offset:2048
	global_load_dwordx4 v[110:113], v114, s[10:11] offset:3072
	s_add_u32 s10, s10, 0x200000
	s_addc_u32 s11, s11, 0
	s_waitcnt vmcnt(0)
; __device__ __forceinline__ void phase_ln(float* R, const float* __restrict__ g, const float* __restrict__ b, bf16_t* xbf, float samp_scale, const float* __restrict__ part, int nsplit, bool f32_all) {
;     ...
;     if (r >= MP) {
;       for (int sp = 0; sp < nsplit; ++sp) {
;         const float* prow = part + ((size_t)sp * MS + (r - MP)) * 1024;
; #pragma unroll
;         for (int i = 0; i < 4; ++i) v[i] = v[i] + *(const f32x4*)(prow + i * 256 + lane * 4);
;       }
;     }
;     float s = 0.f;
; #pragma unroll
;     for (int i = 0; i < 4; ++i) s += v[i][0] + v[i][1] + v[i][2] + v[i][3];
; #pragma unroll
;     for (int o = 32; o >= 1; o >>= 1) s += __shfl_xor(s, o);
;     const float mean = s * (1.f / 1024.f);
;     float ss = 0.f;
; #pragma unroll
;     for (int i = 0; i < 4; ++i) { v[i] = v[i] - mean; ss += v[i][0] * v[i][0] + v[i][1] * v[i][1] + v[i][2] * v[i][2] + v[i][3] * v[i][3]; }
; #pragma unroll
;     for (int o = 32; o >= 1; o >>= 1) ss += __shfl_xor(ss, o);
;     const float rstd = rsqrtf(ss * (1.f / 1024.f) + LN_EPS);
; #pragma unroll
;     for (int i = 0; i < 4; ++i) {
;       const f32x4 y = v[i] * rstd * gv[i] + bv[i];
;       if (r >= MP) *(f32x4*)(row + i * 256 + lane * 4) = y * samp_scale;
;       else if (f32_all) *(f32x4*)(row + i * 256 + lane * 4) = y;
;       if (xbf) {
;         u32x2 wv;
;         wv[0] = cvt_pk_bf16(y[0], y[1]); wv[1] = cvt_pk_bf16(y[2], y[3]);
;         *(u32x2*)(xbf + (size_t)r * 1024 + i * 256 + lane * 4) = wv;
;       }
;     }
	v_pk_add_f32 v[0:1], v[0:1], v[18:19]
	v_pk_add_f32 v[2:3], v[2:3], v[20:21]
	v_pk_add_f32 v[4:5], v[4:5], v[22:23]
	v_pk_add_f32 v[6:7], v[6:7], v[24:25]
	v_pk_add_f32 v[8:9], v[8:9], v[26:27]
	v_pk_add_f32 v[10:11], v[10:11], v[28:29]
	v_pk_add_f32 v[12:13], v[12:13], v[30:31]
	v_pk_add_f32 v[14:15], v[14:15], v[32:33]
	v_pk_add_f32 v[0:1], v[0:1], v[66:67]
	v_pk_add_f32 v[2:3], v[2:3], v[68:69]
	v_pk_add_f32 v[4:5], v[4:5], v[70:71]
	v_pk_add_f32 v[6:7], v[6:7], v[72:73]
	v_pk_add_f32 v[8:9], v[8:9], v[74:75]
	v_pk_add_f32 v[10:11], v[10:11], v[76:77]
	v_pk_add_f32 v[12:13], v[12:13], v[78:79]
	v_pk_add_f32 v[14:15], v[14:15], v[80:81]
	v_pk_add_f32 v[0:1], v[0:1], v[82:83]
	v_pk_add_f32 v[2:3], v[2:3], v[84:85]
	v_pk_add_f32 v[4:5], v[4:5], v[86:87]
	v_pk_add_f32 v[6:7], v[6:7], v[88:89]
	v_pk_add_f32 v[8:9], v[8:9], v[90:91]
	v_pk_add_f32 v[10:11], v[10:11], v[92:93]
	v_pk_add_f32 v[12:13], v[12:13], v[94:95]
	v_pk_add_f32 v[14:15], v[14:15], v[96:97]
	v_pk_add_f32 v[0:1], v[0:1], v[98:99]
	v_pk_add_f32 v[2:3], v[2:3], v[100:101]
	v_pk_add_f32 v[4:5], v[4:5], v[102:103]
	v_pk_add_f32 v[6:7], v[6:7], v[104:105]
	v_pk_add_f32 v[8:9], v[8:9], v[106:107]
	v_pk_add_f32 v[10:11], v[10:11], v[108:109]
	v_pk_add_f32 v[12:13], v[12:13], v[110:111]
	v_pk_add_f32 v[14:15], v[14:15], v[112:113]
	v_pk_add_f32 v[66:67], v[0:1], v[2:3]
	v_pk_add_f32 v[68:69], v[4:5], v[6:7]
	v_pk_add_f32 v[70:71], v[8:9], v[10:11]
	v_pk_add_f32 v[72:73], v[12:13], v[14:15]
	v_pk_add_f32 v[66:67], v[66:67], v[68:69]
	v_pk_add_f32 v[70:71], v[70:71], v[72:73]
	v_pk_add_f32 v[66:67], v[66:67], v[70:71]
	v_add_f32_e32 v66, v66, v67
	s_nop 1
	v_add_f32_dpp v66, v66, v66 row_shr:1 row_mask:0xf bank_mask:0xf bound_ctrl:1
	s_nop 1
	v_add_f32_dpp v66, v66, v66 row_shr:2 row_mask:0xf bank_mask:0xf bound_ctrl:1
	s_nop 1
	v_add_f32_dpp v66, v66, v66 row_shr:4 row_mask:0xf bank_mask:0xf bound_ctrl:1
	s_nop 1
	v_add_f32_dpp v66, v66, v66 row_shr:8 row_mask:0xf bank_mask:0xf bound_ctrl:1
	s_nop 0
	v_readlane_b32 s9, v66, 15
	v_readlane_b32 s10, v66, 31
	v_readlane_b32 s11, v66, 47
	v_readlane_b32 vcc_lo, v66, 63
	s_nop 1
	v_mov_b32_e32 v66, s9
	v_add_f32_e32 v66, s10, v66
	v_add_f32_e32 v66, s11, v66
	v_add_f32_e32 v66, vcc_lo, v66
	v_mul_f32_e32 v116, 0x3a800000, v66
	v_mov_b32_e32 v117, v116
	v_pk_add_f32 v[0:1], v[0:1], v[116:117] neg_lo:[0,1] neg_hi:[0,1]
	v_pk_add_f32 v[2:3], v[2:3], v[116:117] neg_lo:[0,1] neg_hi:[0,1]
	v_pk_add_f32 v[4:5], v[4:5], v[116:117] neg_lo:[0,1] neg_hi:[0,1]
	v_pk_add_f32 v[6:7], v[6:7], v[116:117] neg_lo:[0,1] neg_hi:[0,1]
	v_pk_add_f32 v[8:9], v[8:9], v[116:117] neg_lo:[0,1] neg_hi:[0,1]
	v_pk_add_f32 v[10:11], v[10:11], v[116:117] neg_lo:[0,1] neg_hi:[0,1]
	v_pk_add_f32 v[12:13], v[12:13], v[116:117] neg_lo:[0,1] neg_hi:[0,1]
	v_pk_add_f32 v[14:15], v[14:15], v[116:117] neg_lo:[0,1] neg_hi:[0,1]
	v_pk_mul_f32 v[66:67], v[0:1], v[0:1]
	v_pk_mul_f32 v[68:69], v[2:3], v[2:3]
	v_pk_fma_f32 v[66:67], v[4:5], v[4:5], v[66:67]
	v_pk_fma_f32 v[68:69], v[6:7], v[6:7], v[68:69]
	v_pk_fma_f32 v[66:67], v[8:9], v[8:9], v[66:67]
	v_pk_fma_f32 v[68:69], v[10:11], v[10:11], v[68:69]
	v_pk_fma_f32 v[66:67], v[12:13], v[12:13], v[66:67]
	v_pk_fma_f32 v[68:69], v[14:15], v[14:15], v[68:69]
	v_pk_add_f32 v[66:67], v[66:67], v[68:69]
	v_add_f32_e32 v66, v66, v67
	s_nop 1
	v_add_f32_dpp v66, v66, v66 row_shr:1 row_mask:0xf bank_mask:0xf bound_ctrl:1
	s_nop 1
	v_add_f32_dpp v66, v66, v66 row_shr:2 row_mask:0xf bank_mask:0xf bound_ctrl:1
	s_nop 1
	v_add_f32_dpp v66, v66, v66 row_shr:4 row_mask:0xf bank_mask:0xf bound_ctrl:1
	s_nop 1
	v_add_f32_dpp v66, v66, v66 row_shr:8 row_mask:0xf bank_mask:0xf bound_ctrl:1
	s_nop 0
	v_readlane_b32 s9, v66, 15
	v_readlane_b32 s10, v66, 31
	v_readlane_b32 s11, v66, 47
	v_readlane_b32 vcc_lo, v66, 63
	s_nop 1
	v_mov_b32_e32 v66, s9
	v_add_f32_e32 v66, s10, v66
	v_add_f32_e32 v66, s11, v66
	v_add_f32_e32 v66, vcc_lo, v66
	v_mul_f32_e32 v66, 0x3a800000, v66
	v_add_f32_e32 v66, 0x3727c5ac, v66
	v_rsq_f32_e32 v118, v66
	s_nop 0
	v_mov_b32_e32 v119, v118
	v_pk_mul_f32 v[0:1], v[0:1], v[118:119]
	v_pk_mul_f32 v[2:3], v[2:3], v[118:119]
	v_pk_mul_f32 v[4:5], v[4:5], v[118:119]
	v_pk_mul_f32 v[6:7], v[6:7], v[118:119]
	v_pk_mul_f32 v[8:9], v[8:9], v[118:119]
	v_pk_mul_f32 v[10:11], v[10:11], v[118:119]
	v_pk_mul_f32 v[12:13], v[12:13], v[118:119]
	v_pk_mul_f32 v[14:15], v[14:15], v[118:119]
	v_pk_fma_f32 v[76:77], v[0:1], v[34:35], v[50:51]
	v_pk_fma_f32 v[78:79], v[2:3], v[36:37], v[52:53]
	v_pk_fma_f32 v[80:81], v[4:5], v[38:39], v[54:55]
	v_pk_fma_f32 v[82:83], v[6:7], v[40:41], v[56:57]
	v_pk_fma_f32 v[84:85], v[8:9], v[42:43], v[58:59]
	v_pk_fma_f32 v[86:87], v[10:11], v[44:45], v[60:61]
	v_pk_fma_f32 v[88:89], v[12:13], v[46:47], v[62:63]
	v_pk_fma_f32 v[90:91], v[14:15], v[48:49], v[64:65]
	s_cmp_lg_u32 s8, 0
	s_cselect_b32 s9, 1.0, 0x3fb504f3
	v_mov_b32_e32 v120, s9
	v_mov_b32_e32 v121, s9
	v_pk_mul_f32 v[0:1], v[76:77], v[120:121]
	v_pk_mul_f32 v[2:3], v[78:79], v[120:121]
	v_pk_mul_f32 v[4:5], v[80:81], v[120:121]
	v_pk_mul_f32 v[6:7], v[82:83], v[120:121]
	v_pk_mul_f32 v[8:9], v[84:85], v[120:121]
	v_pk_mul_f32 v[10:11], v[86:87], v[120:121]
	v_pk_mul_f32 v[12:13], v[88:89], v[120:121]
	v_pk_mul_f32 v[14:15], v[90:91], v[120:121]
	global_store_dwordx4 v114, v[0:3], s[0:1] offset:0
	global_store_dwordx4 v114, v[4:7], s[0:1] offset:1024
	global_store_dwordx4 v114, v[8:11], s[0:1] offset:2048
	global_store_dwordx4 v114, v[12:15], s[0:1] offset:3072
	s_cmp_lg_u32 s8, 0
	s_cbranch_scc1 .Lln2_done
	v_cvt_pk_bf16_f32 v92, v76, v77
	v_cvt_pk_bf16_f32 v93, v78, v79
	v_cvt_pk_bf16_f32 v94, v80, v81
	v_cvt_pk_bf16_f32 v95, v82, v83
	v_cvt_pk_bf16_f32 v96, v84, v85
	v_cvt_pk_bf16_f32 v97, v86, v87
	v_cvt_pk_bf16_f32 v98, v88, v89
	v_cvt_pk_bf16_f32 v99, v90, v91
	global_store_dwordx2 v115, v[92:93], s[2:3] offset:0
	global_store_dwordx2 v115, v[94:95], s[2:3] offset:512
	global_store_dwordx2 v115, v[96:97], s[2:3] offset:1024
	global_store_dwordx2 v115, v[98:99], s[2:3] offset:1536
